# LDS pointer-table reads: flat_load -> ds_read_b32 (same LDS words)
# speedup vs baseline: 1.0487x; 1.0010x over previous
.LBB0_7:
	s_or_b64 exec, exec, s[0:1]
	s_add_i32 s57, 0, 0x23fd0
	s_mov_b64 s[6:7], src_shared_base
	s_cmp_lg_u32 s57, -1
	s_cselect_b32 s0, s57, 0
	s_cselect_b32 s1, s7, 0
	s_add_i32 s58, 0, 0x23fd4
	s_cmp_lg_u32 s58, -1
	v_mov_b32_e32 v10, v224
	v_mov_b32_e32 v2, s0
	v_mov_b32_e32 v3, s1
	s_cselect_b32 s0, s58, 0
	ds_read_b32 v22, v2
	s_waitcnt vmcnt(0) lgkmcnt(0)
	s_cselect_b32 s1, s7, 0
	v_mov_b32_e32 v2, s0
	s_add_i32 s0, 0, 0x23f08
	s_cmp_lg_u32 s0, -1
	v_mov_b32_e32 v3, s1
	s_cselect_b32 s0, s0, 0
	ds_read_b32 v23, v2
	s_waitcnt vmcnt(0) lgkmcnt(0)
	s_cselect_b32 s1, s7, 0
	v_mov_b32_e32 v2, s0
	s_add_i32 s0, 0, 0x23f0c
	s_cmp_lg_u32 s0, -1
	v_mov_b32_e32 v3, s1
	s_cselect_b32 s0, s0, 0
	ds_read_b32 v1, v2
	s_waitcnt vmcnt(0) lgkmcnt(0)
	s_cselect_b32 s1, s7, 0
	v_mov_b32_e32 v2, s0
	s_add_i32 s0, 0, 0x23f18
	s_cmp_lg_u32 s0, -1
	v_mov_b32_e32 v3, s1
	s_cselect_b32 s0, s0, 0
	ds_read_b32 v4, v2
	s_waitcnt vmcnt(0) lgkmcnt(0)
	s_cselect_b32 s1, s7, 0
	v_mov_b32_e32 v2, s0
	s_add_i32 s0, 0, 0x23f1c
	s_cmp_lg_u32 s0, -1
	v_mov_b32_e32 v3, s1
	s_cselect_b32 s0, s0, 0
	s_cselect_b32 s1, s7, 0
	ds_read_b32 v5, v2
	s_waitcnt vmcnt(0) lgkmcnt(0)
	v_mov_b32_e32 v2, s0
	v_mov_b32_e32 v3, s1
	ds_read_b32 v16, v2
	s_waitcnt vmcnt(0) lgkmcnt(0)
	v_and_b32_e32 v2, 0x3ff, v10
	v_add_u32_e32 v3, 0x200, v10
	v_lshlrev_b32_e32 v12, 2, v2
	s_movk_i32 s6, 0x1000
	v_mov_b32_e32 v13, 0
	v_ashrrev_i32_e32 v11, 31, v10
	v_and_b32_e32 v18, 0x3ff, v3
	s_movk_i32 s18, 0xc00
	s_mov_b64 s[10:11], 0x1000
	v_add_u32_e32 v6, 0x600, v10
	v_cmp_gt_i32_e32 vcc, s6, v10
	s_movk_i32 s17, 0xe00
	s_mov_b64 s[0:1], 0x800
	v_and_b32_e32 v24, 0x3ff, v6
	s_movk_i32 s20, 0xa00
	s_mov_b64 s[12:13], 0x1800
	s_movk_i32 s21, 0x800
	s_mov_b64 s[14:15], 0x2000
	s_movk_i32 s19, 0x600
	s_movk_i32 s6, 0x400
	s_movk_i32 s16, 0x200
	s_lshl_b32 s60, s76, 3
	s_waitcnt lgkmcnt(0)
	v_readfirstlane_b32 s8, v1
	s_nop 1
	v_mov_b32_e32 v2, s8
	v_readfirstlane_b32 s8, v4
	s_nop 1
	v_mov_b32_e32 v3, s8
	v_lshl_add_u64 v[2:3], v[10:11], 2, v[2:3]
	v_lshl_add_u64 v[6:7], v[2:3], 0, s[10:11]
	v_lshl_add_u64 v[8:9], v[2:3], 0, s[12:13]
	v_lshl_add_u64 v[14:15], v[2:3], 0, s[14:15]
	v_readfirstlane_b32 s8, v5
	v_lshl_add_u64 v[4:5], v[2:3], 0, s[0:1]
	s_mov_b64 s[0:1], 0x2800
	v_readfirstlane_b32 s9, v16
	s_nop 1
	v_lshl_add_u64 v[16:17], s[8:9], 0, v[12:13]
	v_lshlrev_b32_e32 v12, 2, v18
	v_cndmask_b32_e32 v19, v17, v3, vcc
	v_cndmask_b32_e32 v18, v16, v2, vcc
	v_cmp_gt_i32_e32 vcc, s18, v10
	v_lshl_add_u64 v[20:21], s[8:9], 0, v[12:13]
	v_lshlrev_b32_e32 v12, 2, v24
	v_cndmask_b32_e32 v7, v17, v7, vcc
	v_cndmask_b32_e32 v6, v16, v6, vcc
	v_cmp_gt_i32_e32 vcc, s17, v10
	global_load_dword v1, v[18:19], off
	s_nop 0
	v_cndmask_b32_e32 v5, v21, v5, vcc
	v_cndmask_b32_e32 v4, v20, v4, vcc
	global_load_dword v18, v[6:7], off
	v_lshl_add_u64 v[6:7], s[8:9], 0, v[12:13]
	v_cmp_gt_i32_e32 vcc, s20, v10
	global_load_dword v19, v[4:5], off
	s_nop 0
	v_cndmask_b32_e32 v4, v6, v8, vcc
	v_add_u32_e32 v6, 0xa00, v10
	v_cndmask_b32_e32 v5, v7, v9, vcc
	v_cmp_gt_i32_e32 vcc, s21, v10
	v_and_b32_e32 v6, 0x3ff, v6
	global_load_dword v8, v[4:5], off
	v_cndmask_b32_e32 v5, v17, v15, vcc
	v_cndmask_b32_e32 v4, v16, v14, vcc
	v_lshlrev_b32_e32 v12, 2, v6
	global_load_dword v9, v[4:5], off
	v_lshl_add_u64 v[4:5], v[2:3], 0, s[0:1]
	v_lshl_add_u64 v[6:7], s[8:9], 0, v[12:13]
	v_cmp_gt_i32_e32 vcc, s19, v10
	s_mov_b64 s[0:1], 0x3000
	s_waitcnt vmcnt(1)
	v_mul_f32_e32 v20, 0xbfb8aa3b, v8
	v_cndmask_b32_e32 v5, v7, v5, vcc
	v_cndmask_b32_e32 v4, v6, v4, vcc
	v_add_u32_e32 v6, 0xe00, v10
	global_load_dword v14, v[4:5], off
	v_lshl_add_u64 v[4:5], v[2:3], 0, s[0:1]
	v_cmp_gt_i32_e32 vcc, s6, v10
	v_and_b32_e32 v6, 0x3ff, v6
	s_mov_b64 s[0:1], 0x3800
	v_cndmask_b32_e32 v5, v17, v5, vcc
	v_cndmask_b32_e32 v4, v16, v4, vcc
	v_lshlrev_b32_e32 v12, 2, v6
	global_load_dword v15, v[4:5], off
	v_lshl_add_u64 v[4:5], v[2:3], 0, s[0:1]
	v_lshl_add_u64 v[6:7], s[8:9], 0, v[12:13]
	v_cmp_gt_i32_e64 s[0:1], s16, v10
	s_movk_i32 s6, 0xfe00
	v_exp_f32_e32 v20, v20
	v_cndmask_b32_e64 v5, v7, v5, s[0:1]
	v_cndmask_b32_e64 v4, v6, v4, s[0:1]
	s_mov_b64 s[0:1], 0x4000
	global_load_dword v6, v[4:5], off
	v_lshl_add_u64 v[4:5], v[2:3], 0, s[0:1]
	v_cmp_gt_i32_e64 s[0:1], 0, v10
	v_add_f32_e32 v20, 1.0, v20
	v_rcp_f32_e32 v20, v20
	v_cndmask_b32_e64 v5, v17, v5, s[0:1]
	v_cndmask_b32_e64 v4, v16, v4, s[0:1]
	global_load_dword v7, v[4:5], off
	v_add_u32_e32 v4, 0x1200, v10
	v_and_b32_e32 v4, 0x3ff, v4
	s_mov_b64 s[0:1], 0x4800
	v_lshlrev_b32_e32 v12, 2, v4
	v_lshl_add_u64 v[2:3], v[2:3], 0, s[0:1]
	v_lshl_add_u64 v[4:5], s[8:9], 0, v[12:13]
	v_cmp_gt_i32_e64 s[0:1], s6, v10
	s_waitcnt vmcnt(4)
	v_mul_f32_e32 v12, 0xbfb8aa3b, v9
	v_mul_f32_e32 v17, 0xbfb8aa3b, v19
	v_cndmask_b32_e64 v3, v5, v3, s[0:1]
	v_cndmask_b32_e64 v2, v4, v2, s[0:1]
	global_load_dword v2, v[2:3], off
	v_mul_f32_e32 v4, 0xbfb8aa3b, v1
	v_mul_f32_e32 v5, 0xbfb8aa3b, v18
	v_exp_f32_e32 v4, v4
	v_exp_f32_e32 v5, v5
	v_exp_f32_e32 v12, v12
	v_exp_f32_e32 v17, v17
	v_add_f32_e32 v4, 1.0, v4
	v_add_f32_e32 v5, 1.0, v5
	v_add_f32_e32 v12, 1.0, v12
	v_add_f32_e32 v17, 1.0, v17
	v_rcp_f32_e32 v4, v4
	v_rcp_f32_e32 v5, v5
	v_rcp_f32_e32 v12, v12
	v_rcp_f32_e32 v17, v17
	v_lshl_add_u32 v3, v10, 2, 0
	v_add_u32_e32 v3, 0x14000, v3
	v_mul_f32_e32 v1, v1, v4
	v_mul_f32_e32 v4, v18, v5
	v_mul_f32_e32 v5, v9, v12
	v_mul_f32_e32 v9, v19, v17
	ds_write2st64_b32 v3, v1, v9 offset1:8
	v_mul_f32_e32 v1, v8, v20
	ds_write2st64_b32 v3, v4, v1 offset0:16 offset1:24
	s_add_i32 s0, 0, 0x23f20
	s_cmp_lg_u32 s0, -1
	s_cselect_b32 s0, s0, 0
	s_cselect_b32 s1, s7, 0
	v_readfirstlane_b32 s6, v22
	s_waitcnt vmcnt(4)
	v_mul_f32_e32 v21, 0xbfb8aa3b, v14
	v_exp_f32_e32 v21, v21
	s_waitcnt vmcnt(3)
	v_mul_f32_e32 v16, 0xbfb8aa3b, v15
	v_add_f32_e32 v21, 1.0, v21
	v_rcp_f32_e32 v21, v21
	v_exp_f32_e32 v16, v16
	v_mul_f32_e32 v4, v14, v21
	ds_write2st64_b32 v3, v5, v4 offset0:32 offset1:40
	v_add_f32_e32 v16, 1.0, v16
	s_waitcnt vmcnt(2)
	v_mul_f32_e32 v24, 0xbfb8aa3b, v6
	v_exp_f32_e32 v1, v24
	v_rcp_f32_e32 v16, v16
	v_add_f32_e32 v1, 1.0, v1
	v_rcp_f32_e32 v1, v1
	s_waitcnt vmcnt(1)
	v_mul_f32_e32 v5, 0xbfb8aa3b, v7
	v_exp_f32_e32 v5, v5
	v_mul_f32_e32 v4, v15, v16
	v_mul_f32_e32 v1, v6, v1
	ds_write2st64_b32 v3, v4, v1 offset0:48 offset1:56
	v_add_f32_e32 v5, 1.0, v5
	v_rcp_f32_e32 v5, v5
	s_waitcnt vmcnt(0)
	v_mul_f32_e32 v8, 0xbfb8aa3b, v2
	v_exp_f32_e32 v8, v8
	v_mul_f32_e32 v1, v7, v5
	v_add_f32_e32 v8, 1.0, v8
	v_rcp_f32_e32 v8, v8
	s_nop 0
	v_mul_f32_e32 v2, v2, v8
	ds_write2st64_b32 v3, v1, v2 offset0:64 offset1:72
	v_mov_b32_e32 v2, s0
	s_add_i32 s0, 0, 0x23f24
	s_cmp_lg_u32 s0, -1
	v_mov_b32_e32 v3, s1
	s_cselect_b32 s0, s0, 0
	s_waitcnt lgkmcnt(0)
	s_barrier
	ds_read_b32 v4, v2
	s_waitcnt vmcnt(0) lgkmcnt(0)
	s_cselect_b32 s1, s7, 0
	v_mov_b32_e32 v2, s0
	s_add_i32 s0, 0, 0x23f28
	s_cmp_lg_u32 s0, -1
	v_mov_b32_e32 v3, s1
	s_cselect_b32 s0, s0, 0
	ds_read_b32 v5, v2
	s_waitcnt vmcnt(0) lgkmcnt(0)
	s_cselect_b32 s1, s7, 0
	v_mov_b32_e32 v2, s0
	s_add_i32 s0, 0, 0x23f2c
	s_cmp_lg_u32 s0, -1
	v_mov_b32_e32 v3, s1
	s_cselect_b32 s0, s0, 0
	s_cselect_b32 s1, s7, 0
	ds_read_b32 v6, v2
	s_waitcnt vmcnt(0) lgkmcnt(0)
	v_mov_b32_e32 v2, s0
	v_mov_b32_e32 v3, s1
	ds_read_b32 v2, v2
	s_waitcnt vmcnt(0) lgkmcnt(0)
	v_ashrrev_i32_e32 v1, 6, v10
	v_mul_lo_u32 v1, v1, s76
	s_movk_i32 s0, 0x480
	v_add_u32_e32 v1, s75, v1
	v_readfirstlane_b32 s7, v23
	v_cmp_gt_i32_e64 s[0:1], s0, v1
	s_waitcnt lgkmcnt(0)
	v_readfirstlane_b32 s12, v4
	v_readfirstlane_b32 s13, v5
	v_readfirstlane_b32 s8, v6
	v_readfirstlane_b32 s9, v2
	s_and_saveexec_b64 s[10:11], s[0:1]
	s_cbranch_execz .LBB0_14
	v_lshlrev_b32_e32 v2, 2, v10
	s_add_u32 s12, s12, 0x48000
	v_and_b32_e32 v56, 0xfc, v2
	s_addc_u32 s13, s13, 0
	s_mov_b64 s[14:15], 0
	s_mov_b32 s20, 0x38e38e39
	s_movk_i32 s21, 0xff00
	s_mov_b32 s22, 0x2400000
	s_mov_b32 s23, 0xfffb8000
	s_mov_b32 s24, 0xfffc1000
	s_mov_b32 s25, 0xfffca000
	s_mov_b32 s26, 0xfffd3000
	s_mov_b32 s27, 0xfffdc000
	s_mov_b32 s28, 0xfffe5000
	s_mov_b32 s29, 0xfffee000
	s_mov_b32 s30, 0xffff7000
	s_mov_b32 s31, 0x9000
	s_mov_b32 s34, 0x12000
	s_mov_b32 s35, 0x1b000
	s_mov_b32 s36, 0x24000
	s_mov_b32 s37, 0x2d000
	s_mov_b32 s38, 0x36000
	s_mov_b32 s39, 0x3f000
	s_mov_b64 s[16:17], 0x90000
	s_movk_i32 s40, 0x47f
	s_branch .LBB0_10

.LBB0_21:
	s_cmpk_gt_i32 s26, 0x15f
	s_mov_b64 s[10:11], -1
	s_cbranch_scc0 .LBB0_23
	s_mov_b64 s[10:11], src_shared_base
	s_cmp_lg_u32 s19, -1
	s_cselect_b32 s8, s19, 0
	s_cselect_b32 s10, s11, 0
	s_cmp_lg_u32 s20, -1
	v_mov_b32_e32 v6, s8
	v_mov_b32_e32 v7, s10
	s_cselect_b32 s8, s20, 0
	s_cselect_b32 s10, s11, 0
	ds_read_b32 v15, v6
	s_waitcnt vmcnt(0) lgkmcnt(0)
	v_mov_b32_e32 v6, s8
	v_mov_b32_e32 v7, s10
	ds_read_b32 v30, v6
	s_waitcnt vmcnt(0) lgkmcnt(0)
	s_and_b32 s12, s15, 0x300
	s_and_b32 s8, s17, 0xfc0
	s_lshl_b32 s10, s12, 2
	v_add_u32_e32 v6, s8, v1
	v_ashrrev_i32_e32 v7, 31, v6
	v_or_b32_e32 v16, 1, v6
	v_or_b32_e32 v18, 2, v6
	v_or_b32_e32 v20, 3, v6
	v_or_b32_e32 v22, 4, v6
	v_or_b32_e32 v24, 5, v6
	v_or_b32_e32 v26, 6, v6
	v_or_b32_e32 v28, 7, v6
	v_lshlrev_b64 v[6:7], 12, v[6:7]
	v_ashrrev_i32_e32 v17, 31, v16
	v_ashrrev_i32_e32 v19, 31, v18
	v_ashrrev_i32_e32 v21, 31, v20
	v_ashrrev_i32_e32 v23, 31, v22
	v_ashrrev_i32_e32 v25, 31, v24
	v_ashrrev_i32_e32 v27, 31, v26
	v_ashrrev_i32_e32 v29, 31, v28
	v_lshlrev_b64 v[16:17], 12, v[16:17]
	v_lshlrev_b64 v[18:19], 12, v[18:19]
	v_lshlrev_b64 v[20:21], 12, v[20:21]
	v_lshlrev_b64 v[22:23], 12, v[22:23]
	v_lshlrev_b64 v[24:25], 12, v[24:25]
	v_lshlrev_b64 v[26:27], 12, v[26:27]
	v_lshlrev_b64 v[28:29], 12, v[28:29]
	s_waitcnt lgkmcnt(0)
	v_readfirstlane_b32 s11, v15
	s_add_u32 s10, s11, s10
	v_readfirstlane_b32 s13, v30
	s_addc_u32 s11, s13, 0
	v_lshl_add_u64 v[30:31], s[10:11], 0, v[2:3]
	v_lshl_add_u64 v[6:7], v[30:31], 0, v[6:7]
	v_lshl_add_u64 v[48:49], v[30:31], 0, v[16:17]
	v_lshl_add_u64 v[50:51], v[30:31], 0, v[18:19]
	v_lshl_add_u64 v[52:53], v[30:31], 0, v[20:21]
	v_lshl_add_u64 v[54:55], v[30:31], 0, v[22:23]
	v_lshl_add_u64 v[56:57], v[30:31], 0, v[24:25]
	v_lshl_add_u64 v[58:59], v[30:31], 0, v[26:27]
	v_lshl_add_u64 v[60:61], v[30:31], 0, v[28:29]
	global_load_dwordx4 v[16:19], v[6:7], off
	global_load_dwordx4 v[20:23], v[48:49], off
	global_load_dwordx4 v[24:27], v[50:51], off
	global_load_dwordx4 v[28:31], v[52:53], off
	global_load_dwordx4 v[32:35], v[54:55], off
	global_load_dwordx4 v[36:39], v[56:57], off
	global_load_dwordx4 v[40:43], v[58:59], off
	global_load_dwordx4 v[44:47], v[60:61], off
	v_or_b32_sdwa v6, s12, v10 dst_sel:DWORD dst_unused:UNUSED_PAD src0_sel:DWORD src1_sel:BYTE_0
	v_mul_u32_u24_e32 v6, 0xb00, v6
	v_mov_b32_e32 v7, v3
	v_lshlrev_b32_e32 v6, 1, v6
	v_lshl_add_u64 v[6:7], s[0:1], 0, v[6:7]
	s_lshl_b32 s8, s8, 1
	v_lshl_add_u64 v[6:7], v[6:7], 0, s[8:9]
	s_barrier
	s_mov_b64 s[10:11], 0
	s_waitcnt vmcnt(7)
	ds_write_b128 v13, v[16:19]
	s_waitcnt vmcnt(6)
	ds_write_b128 v13, v[20:23] offset:1040
	s_waitcnt vmcnt(5)
	ds_write_b128 v13, v[24:27] offset:2080
	s_waitcnt vmcnt(4)
	ds_write_b128 v13, v[28:31] offset:3120
	s_waitcnt vmcnt(3)
	ds_write_b128 v13, v[32:35] offset:4160
	s_waitcnt vmcnt(2)
	ds_write_b128 v13, v[36:39] offset:5200
	s_waitcnt vmcnt(1)
	ds_write_b128 v13, v[40:43] offset:6240
	s_waitcnt vmcnt(0)
	ds_write_b128 v14, v[44:47]
	s_waitcnt lgkmcnt(0)
	s_barrier
.LBB0_23:
	s_andn2_b64 vcc, exec, s[10:11]
	s_cbranch_vccnz .LBB0_20
	s_mov_b64 s[10:11], src_shared_base
	s_mul_hi_i32 s8, s26, 0x2e8ba2e9
	s_lshr_b32 s10, s8, 31
	s_ashr_i32 s8, s8, 2
	s_add_i32 s8, s8, s10
	s_cmp_lg_u32 s21, -1
	s_cselect_b32 s10, s21, 0
	s_cselect_b32 s12, s11, 0
	s_cmp_lg_u32 s22, -1
	v_mov_b32_e32 v6, s10
	v_mov_b32_e32 v7, s12
	s_cselect_b32 s10, s22, 0
	s_cselect_b32 s11, s11, 0
	ds_read_b32 v15, v6
	s_waitcnt vmcnt(0) lgkmcnt(0)
	v_mov_b32_e32 v6, s10
	v_mov_b32_e32 v7, s11
	ds_read_b32 v6, v6
	s_waitcnt vmcnt(0) lgkmcnt(0)
	s_mul_i32 s11, s8, 0xffffea00
	s_add_i32 s12, s15, s11
	s_ashr_i32 s13, s12, 31
	s_lshl_b32 s10, s8, 6
	s_lshl_b64 s[28:29], s[12:13], 2
	v_add_u32_e32 v16, s10, v1
	v_or_b32_e32 v17, 1, v16
	v_or_b32_e32 v18, 2, v16
	v_or_b32_e32 v19, 3, v16
	v_or_b32_e32 v20, 4, v16
	v_or_b32_e32 v21, 5, v16
	v_or_b32_e32 v22, 6, v16
	v_or_b32_e32 v23, 7, v16
	s_waitcnt lgkmcnt(0)
	v_readfirstlane_b32 s11, v15
	s_add_u32 s28, s11, s28
	v_readfirstlane_b32 s13, v6
	s_addc_u32 s29, s13, s29
	v_lshl_add_u64 v[6:7], s[28:29], 0, v[2:3]
	v_mad_i64_i32 v[48:49], s[28:29], v16, s23, v[6:7]
	v_mad_i64_i32 v[50:51], s[28:29], v17, s23, v[6:7]
	v_mad_i64_i32 v[52:53], s[28:29], v18, s23, v[6:7]
	v_mad_i64_i32 v[54:55], s[28:29], v19, s23, v[6:7]
	v_mad_i64_i32 v[56:57], s[28:29], v20, s23, v[6:7]
	v_mad_i64_i32 v[58:59], s[28:29], v21, s23, v[6:7]
	v_mad_i64_i32 v[60:61], s[28:29], v22, s23, v[6:7]
	v_mad_i64_i32 v[6:7], s[28:29], v23, s23, v[6:7]
	global_load_dwordx4 v[16:19], v[48:49], off
	global_load_dwordx4 v[20:23], v[50:51], off
	global_load_dwordx4 v[24:27], v[52:53], off
	global_load_dwordx4 v[28:31], v[54:55], off
	global_load_dwordx4 v[32:35], v[56:57], off
	global_load_dwordx4 v[36:39], v[58:59], off
	global_load_dwordx4 v[40:43], v[60:61], off
	global_load_dwordx4 v[44:47], v[6:7], off
	v_add_u32_sdwa v6, s12, v10 dst_sel:DWORD dst_unused:UNUSED_PAD src0_sel:DWORD src1_sel:BYTE_0
	v_and_b32_e32 v6, 0xffffffe0, v6
	v_cmp_lt_i32_e32 vcc, s24, v6
	s_barrier
	s_waitcnt vmcnt(7)
	ds_write_b128 v13, v[16:19]
	s_waitcnt vmcnt(6)
	ds_write_b128 v13, v[20:23] offset:1040
	s_waitcnt vmcnt(5)
	ds_write_b128 v13, v[24:27] offset:2080
	s_waitcnt vmcnt(4)
	ds_write_b128 v13, v[28:31] offset:3120
	s_waitcnt vmcnt(3)
	ds_write_b128 v13, v[32:35] offset:4160
	s_waitcnt vmcnt(2)
	ds_write_b128 v13, v[36:39] offset:5200
	s_waitcnt vmcnt(1)
	ds_write_b128 v13, v[40:43] offset:6240
	s_waitcnt vmcnt(0)
	ds_write_b128 v14, v[44:47]
	s_waitcnt lgkmcnt(0)
	s_barrier
	s_and_saveexec_b64 s[12:13], vcc
	s_xor_b64 s[12:13], exec, s[12:13]
	s_mulk_i32 s8, 0xd400
	v_add_u32_e32 v6, s8, v12
	v_and_or_b32 v7, v6, s25, v11
	s_andn2_saveexec_b64 s[12:13], s[12:13]
	s_cbranch_execz .LBB0_19
	v_ashrrev_i32_e32 v7, 31, v6
	v_lshrrev_b32_e32 v7, 25, v7
	v_add_u32_e32 v7, v6, v7
	v_and_b32_e32 v7, 0xffffff80, v7
	v_add_u32_e32 v7, v7, v6
	s_branch .LBB0_19

.LBB0_40:
	s_mov_b64 s[0:1], src_shared_base
	s_cmp_lg_u32 s57, -1
	s_cselect_b32 s0, s57, 0
	s_cselect_b32 s2, s1, 0
	s_cmp_lg_u32 s58, -1
	v_mov_b32_e32 v0, s0
	v_mov_b32_e32 v1, s2
	s_cselect_b32 s0, s58, 0
	s_cselect_b32 s1, s1, 0
	ds_read_b32 v2, v0
	s_waitcnt vmcnt(0) lgkmcnt(0)
	v_mov_b32_e32 v0, s0
	v_mov_b32_e32 v1, s1
	ds_read_b32 v0, v0
	s_waitcnt vmcnt(0) lgkmcnt(0)
	s_getreg_b32 s4, hwreg(HW_REG_XCC_ID, 0, 4)
	s_waitcnt vmcnt(0)
	s_waitcnt lgkmcnt(0)
	s_barrier
	v_readfirstlane_b32 s2, v2
	v_readfirstlane_b32 s3, v0
	s_and_saveexec_b64 s[0:1], s[78:79]
	s_cbranch_execz .LBB0_92
	s_add_i32 s5, 0, 0x23e00
	v_mov_b32_e32 v0, s5
	s_waitcnt vmcnt(0) expcnt(0) lgkmcnt(0)
	ds_read_b32 v2, v0
	s_add_i32 s5, 0, 0x23e04
	v_mov_b32_e32 v0, s5
	ds_read_b32 v0, v0
	s_and_b32 s46, s4, 15
	s_waitcnt lgkmcnt(1)
	v_cmp_ne_u32_e32 vcc, 0, v2
	s_cbranch_vccnz .LBB0_56
	s_add_u32 s4, s2, 0x3c0200
	s_addc_u32 s5, s3, 0
	s_add_u32 s6, s2, 0x3c0400
	s_addc_u32 s7, s3, 0
	s_add_u32 s8, s2, 0x3c0500
	s_addc_u32 s9, s3, 0
	s_add_u32 s10, s2, 0x3c0600
	s_addc_u32 s11, s3, 0
	s_add_u32 s12, s2, 0x3c0700
	s_addc_u32 s13, s3, 0
	s_add_u32 s14, s2, 0x3c0800
	s_addc_u32 s15, s3, 0
	s_add_u32 s16, s2, 0x3c0900
	s_addc_u32 s17, s3, 0
	s_add_u32 s18, s2, 0x3c0a00
	s_addc_u32 s19, s3, 0
	s_add_u32 s20, s2, 0x3c0b00
	s_addc_u32 s21, s3, 0
	s_add_u32 s22, s2, 0x3c0c00
	s_addc_u32 s23, s3, 0
	s_add_u32 s24, s2, 0x3c0d00
	s_addc_u32 s25, s3, 0
	s_add_u32 s26, s2, 0x3c0e00
	s_addc_u32 s27, s3, 0
	s_add_u32 s28, s2, 0x3c0f00
	s_addc_u32 s29, s3, 0
	s_add_u32 s30, s2, 0x3c1000
	s_addc_u32 s31, s3, 0
	s_add_u32 s34, s2, 0x3c1100
	s_addc_u32 s35, s3, 0
	s_add_u32 s36, s2, 0x3c1200
	s_addc_u32 s37, s3, 0
	s_mul_i32 s47, s77, s33
	s_add_u32 s38, s2, 0x3c1300
	s_mul_i32 s47, s47, s76
	s_addc_u32 s39, s3, 0
	s_mov_b32 s48, 1
	v_mov_b32_e32 v16, 0
	s_branch .LBB0_44

.LBB0_92:
	s_or_b64 exec, exec, s[0:1]
	s_mov_b64 s[0:1], src_shared_base
	s_cmp_lg_u32 s57, -1
	s_cselect_b32 s0, s57, 0
	s_cselect_b32 s2, s1, 0
	s_cmp_lg_u32 s58, -1
	v_mov_b32_e32 v32, v224
	s_waitcnt lgkmcnt(0)
	v_mov_b32_e32 v0, s0
	v_mov_b32_e32 v1, s2
	s_cselect_b32 s0, s58, 0
	s_cselect_b32 s1, s1, 0
	s_barrier
	ds_read_b32 v40, v0
	s_waitcnt vmcnt(0) lgkmcnt(0)
	v_mov_b32_e32 v0, s0
	v_mov_b32_e32 v1, s1
	ds_read_b32 v41, v0
	s_waitcnt vmcnt(0) lgkmcnt(0)
	v_add_u32_e32 v0, 0x400, v32
	v_add_u32_e32 v2, 0x800, v32
	v_add_u32_e32 v4, 0xc00, v32
	v_add_u32_e32 v6, 0x1000, v32
	v_add_u32_e32 v8, 0x1400, v32
	v_add_u32_e32 v10, 0x1800, v32
	v_add_u32_e32 v12, 0x1c00, v32
	v_add_u32_e32 v14, 0x2000, v32
	v_add_u32_e32 v16, 0x2400, v32
	v_add_u32_e32 v18, 0x2800, v32
	v_add_u32_e32 v20, 0x2c00, v32
	v_add_u32_e32 v22, 0x3000, v32
	v_add_u32_e32 v24, 0x3400, v32
	v_add_u32_e32 v26, 0x3800, v32
	v_add_u32_e32 v28, 0x3c00, v32
	v_add_u32_e32 v30, 0x4000, v32
	v_add_u32_e32 v34, 0x4400, v32
	v_add_u32_e32 v36, 0x4800, v32
	v_add_u32_e32 v38, 0x4c00, v32
	s_mov_b32 s4, 0
	s_movk_i32 s5, 0xc00
	s_mov_b32 s7, 1
	s_mov_b32 s11, 40
	s_mov_b32 s6, 0x66666667
	s_mov_b32 s8, 0x88888889
	s_mov_b32 s9, 0x55555556
	s_mov_b32 s10, 0x9000
	v_mov_b32_e32 v1, v32
	v_mov_b32_e32 v3, v0
	v_mov_b32_e32 v5, v2
	v_mov_b32_e32 v7, v4
	v_mov_b32_e32 v9, v6
	v_mov_b32_e32 v11, v8
	v_mov_b32_e32 v13, v10
	v_mov_b32_e32 v15, v12
	v_mov_b32_e32 v17, v14
	v_mov_b32_e32 v19, v16
	v_mov_b32_e32 v21, v18
	v_mov_b32_e32 v23, v20
	v_mov_b32_e32 v25, v22
	v_mov_b32_e32 v27, v24
	v_mov_b32_e32 v29, v26
	v_mov_b32_e32 v31, v28
	v_mov_b32_e32 v33, v30
	v_mov_b32_e32 v35, v34
	v_mov_b32_e32 v37, v36
	v_mov_b32_e32 v39, v38
	s_waitcnt lgkmcnt(0)
	v_readfirstlane_b32 s2, v40
	v_readfirstlane_b32 s3, v41
	v_mov_b32_e32 v41, 0
	s_branch .LBB0_94

.LBB0_96:
	s_mov_b64 s[0:1], src_shared_base
	s_lshl_b32 s5, s75, 3
	s_add_i32 s0, 0, 0x23f00
	s_cmp_lg_u32 s0, -1
	s_cselect_b32 s4, s1, 0
	v_writelane_b32 v253, s0, 0
	s_cselect_b32 s0, s0, 0
	v_mov_b32_e32 v0, s0
	s_add_i32 s0, 0, 0x23f04
	s_cmp_lg_u32 s0, -1
	v_mov_b32_e32 v1, s4
	v_writelane_b32 v253, s0, 1
	s_cselect_b32 s0, s0, 0
	ds_read_b32 v2, v0
	s_waitcnt vmcnt(0) lgkmcnt(0)
	s_cselect_b32 s4, s1, 0
	v_mov_b32_e32 v0, s0
	s_add_i32 s0, 0, 0x23f10
	s_cmp_lg_u32 s0, -1
	v_mov_b32_e32 v1, s4
	v_writelane_b32 v253, s0, 2
	s_cselect_b32 s0, s0, 0
	ds_read_b32 v3, v0
	s_waitcnt vmcnt(0) lgkmcnt(0)
	s_cselect_b32 s4, s1, 0
	v_mov_b32_e32 v0, s0
	s_add_i32 s0, 0, 0x23f14
	s_cmp_lg_u32 s0, -1
	v_mov_b32_e32 v1, s4
	v_writelane_b32 v253, s0, 3
	s_cselect_b32 s0, s0, 0
	ds_read_b32 v4, v0
	s_waitcnt vmcnt(0) lgkmcnt(0)
	s_cselect_b32 s4, s1, 0
	v_mov_b32_e32 v0, s0
	s_add_i32 s0, 0, 0x23f30
	s_cmp_lg_u32 s0, -1
	v_mov_b32_e32 v1, s4
	v_writelane_b32 v253, s0, 4
	s_cselect_b32 s0, s0, 0
	ds_read_b32 v5, v0
	s_waitcnt vmcnt(0) lgkmcnt(0)
	s_cselect_b32 s4, s1, 0
	v_mov_b32_e32 v0, s0
	s_add_i32 s0, 0, 0x23f34
	s_cmp_lg_u32 s0, -1
	v_mov_b32_e32 v1, s4
	v_writelane_b32 v253, s0, 5
	s_cselect_b32 s0, s0, 0
	s_cselect_b32 s1, s1, 0
	ds_read_b32 v6, v0
	s_waitcnt vmcnt(0) lgkmcnt(0)
	v_mov_b32_e32 v0, s0
	v_mov_b32_e32 v1, s1
	ds_read_b32 v0, v0
	s_waitcnt vmcnt(0) lgkmcnt(0)
	v_ashrrev_i32_e32 v33, 6, v32
	s_movk_i32 s0, 0x2200
	v_add_u32_e32 v60, s5, v33
	v_and_b32_e32 v59, 63, v32
	v_writelane_b32 v253, s5, 6
	v_cmp_gt_i32_e32 vcc, s0, v60
	v_mbcnt_lo_u32_b32 v58, -1, 0
	s_waitcnt lgkmcnt(0)
	v_readfirstlane_b32 s14, v2
	v_readfirstlane_b32 s16, v3
	v_readfirstlane_b32 s15, v4
	v_readfirstlane_b32 s17, v5
	v_readfirstlane_b32 s8, v6
	v_readfirstlane_b32 s9, v0
	s_and_saveexec_b64 s[4:5], vcc
	s_cbranch_execz .LBB0_103
	v_mbcnt_hi_u32_b32 v1, -1, v58
	v_and_b32_e32 v2, 64, v1
	v_add_u32_e32 v2, 64, v2
	v_xor_b32_e32 v3, 1, v1
	v_cmp_lt_i32_e32 vcc, v3, v2
	v_lshlrev_b32_e32 v34, 1, v60
	v_lshlrev_b32_e32 v0, 2, v59
	v_cndmask_b32_e32 v3, v1, v3, vcc
	v_lshlrev_b32_e32 v61, 2, v3
	v_xor_b32_e32 v3, 2, v1
	v_cmp_lt_i32_e32 vcc, v3, v2
	s_lshl_b32 s6, s76, 4
	v_ashrrev_i32_e32 v35, 31, v34
	v_cndmask_b32_e32 v3, v1, v3, vcc
	v_lshlrev_b32_e32 v62, 2, v3
	v_xor_b32_e32 v3, 4, v1
	v_cmp_lt_i32_e32 vcc, v3, v2
	v_mov_b32_e32 v37, 0
	v_lshlrev_b32_e32 v36, 4, v59
	v_cndmask_b32_e32 v3, v1, v3, vcc
	v_lshlrev_b32_e32 v63, 2, v3
	v_xor_b32_e32 v3, 8, v1
	v_cmp_lt_i32_e32 vcc, v3, v2
	v_or_b32_e32 v4, 0x200, v0
	v_or_b32_e32 v6, 0x300, v0
	v_cndmask_b32_e32 v3, v1, v3, vcc
	v_lshlrev_b32_e32 v64, 2, v3
	v_xor_b32_e32 v3, 16, v1
	v_cmp_lt_i32_e32 vcc, v3, v2
	s_ashr_i32 s7, s6, 31
	v_lshlrev_b64 v[40:41], 11, v[34:35]
	v_cndmask_b32_e32 v3, v1, v3, vcc
	v_lshlrev_b32_e32 v65, 2, v3
	v_xor_b32_e32 v3, 32, v1
	v_cmp_lt_i32_e32 vcc, v3, v2
	v_or_b32_e32 v2, 0x100, v0
	v_cmp_eq_u32_e64 s[0:1], 0, v59
	v_cndmask_b32_e32 v1, v1, v3, vcc
	v_lshlrev_b32_e32 v66, 2, v1
	v_lshl_add_u64 v[38:39], s[8:9], 0, v[36:37]
	v_lshl_or_b32 v40, v59, 3, v40
	s_lshl_b64 s[8:9], s[6:7], 11
	v_lshlrev_b64 v[42:43], 2, v[34:35]
	s_lshl_b64 s[10:11], s[6:7], 2
	s_mov_b64 s[12:13], 0
	s_movk_i32 s18, 0x4000
	v_mov_b32_e32 v67, s17
	v_mov_b32_e32 v68, s16
	v_mov_b32_e32 v69, s15
	v_mov_b32_e32 v70, s14
	v_lshlrev_b32_e32 v36, 2, v0
	s_mov_b64 s[14:15], 0x1000
	s_mov_b32 s19, 0x5a00000
	v_lshlrev_b32_e32 v44, 2, v2
	v_lshlrev_b32_e32 v46, 2, v4
	v_lshlrev_b32_e32 v48, 2, v6
	s_movk_i32 s20, 0x43ff
	s_branch .LBB0_99

.LBB0_107:
	v_ashrrev_i32_e32 v4, 4, v60
	v_cmp_lt_i32_e32 vcc, s15, v4
	s_and_saveexec_b64 s[0:1], vcc
	s_xor_b64 s[10:11], exec, s[0:1]
	s_cbranch_execz .LBB0_113
	v_cmp_lt_u32_e64 s[0:1], s16, v4
	s_and_saveexec_b64 s[8:9], s[0:1]
	s_xor_b64 s[0:1], exec, s[8:9]
	s_cbranch_execz .LBB0_110
	s_mov_b64 s[8:9], src_shared_base
	s_cmp_lg_u32 s17, -1
	s_cselect_b32 s8, s17, 0
	s_cselect_b32 s12, s9, 0
	s_cmp_lg_u32 s18, -1
	v_mov_b32_e32 v0, s8
	v_mov_b32_e32 v1, s12
	s_cselect_b32 s8, s18, 0
	s_cselect_b32 s9, s9, 0
	ds_read_b32 v2, v0
	s_waitcnt vmcnt(0) lgkmcnt(0)
	v_mov_b32_e32 v0, s8
	v_mov_b32_e32 v1, s9
	ds_read_b32 v0, v0
	s_waitcnt vmcnt(0) lgkmcnt(0)
	v_add_u32_e32 v43, 0xfffffe84, v4
	s_waitcnt lgkmcnt(0)
	v_readfirstlane_b32 s12, v2
	v_readfirstlane_b32 s13, v0
.LBB0_110:
	s_or_saveexec_b64 s[0:1], s[0:1]
	v_mov_b32_e32 v42, 20
	v_mov_b64_e32 v[0:1], 0x1010
	s_mov_b64 s[8:9], 0
	v_mov_b64_e32 v[2:3], s[12:13]
	s_xor_b64 exec, exec, s[0:1]
	s_cbranch_execz .LBB0_112
	s_mov_b64 s[12:13], src_shared_base
	s_cmp_lg_u32 s19, -1
	s_cselect_b32 s12, s19, 0
	s_cselect_b32 s30, s13, 0
	s_cmp_lg_u32 s20, -1
	v_mov_b32_e32 v0, s12
	v_mov_b32_e32 v1, s30
	s_cselect_b32 s12, s20, 0
	s_cselect_b32 s13, s13, 0
	ds_read_b32 v2, v0
	s_waitcnt vmcnt(0) lgkmcnt(0)
	v_mov_b32_e32 v0, s12
	v_mov_b32_e32 v1, s13
	ds_read_b32 v0, v0
	s_waitcnt vmcnt(0) lgkmcnt(0)
	s_mov_b64 s[8:9], exec
	v_add_u32_e32 v43, 0xfffffea0, v4
	v_mov_b32_e32 v42, 5
	s_waitcnt lgkmcnt(0)
	v_readfirstlane_b32 s12, v2
	v_readfirstlane_b32 s13, v0
	v_mov_b64_e32 v[0:1], 0x700
	s_nop 0
	v_mov_b64_e32 v[2:3], s[12:13]

.LBB0_113:
	s_andn2_saveexec_b64 s[10:11], s[10:11]
	s_cbranch_execz .LBB0_115
	v_mul_hi_i32 v0, v4, s21
	v_lshrrev_b32_e32 v1, 31, v0
	v_ashrrev_i32_e32 v0, 4, v0
	v_add_u32_e32 v2, v0, v1
	v_and_b32_e32 v3, 1, v2
	v_cmp_eq_u32_e64 s[0:1], 0, v3
	s_mov_b64 s[12:13], src_shared_base
	v_mov_b32_e32 v1, s13
	v_cndmask_b32_e64 v0, v39, 56, s[0:1]
	v_readlane_b32 s0, v253, 0
	v_mad_i32_i24 v43, v2, s22, v4
	v_ashrrev_i32_e32 v4, 1, v2
	v_add_u32_e32 v0, s0, v0
	ds_read_b32 v5, v0
	s_waitcnt vmcnt(0) lgkmcnt(0)
	v_add_u32_e32 v0, 4, v0
	ds_read_b32 v6, v0
	s_waitcnt vmcnt(0) lgkmcnt(0)
	v_mul_u32_u24_e32 v2, 10, v3
	v_mad_i32_i24 v42, v4, 15, v2
	v_mov_b64_e32 v[0:1], 0x1600
	s_andn2_b64 s[8:9], s[8:9], exec
	s_waitcnt lgkmcnt(0)
	v_readfirstlane_b32 s0, v5
	s_nop 1
	v_mov_b32_e32 v2, s0
	v_readfirstlane_b32 s1, v6
	s_nop 1
	v_mov_b32_e32 v3, s1
	v_mad_i64_i32 v[2:3], s[0:1], v4, s23, v[2:3]

.LBB0_130:
	s_or_b64 exec, exec, s[4:5]
	s_mov_b64 s[0:1], src_shared_base
	s_cmp_lg_u32 s57, -1
	s_cselect_b32 s0, s57, 0
	s_cselect_b32 s2, s1, 0
	s_cmp_lg_u32 s58, -1
	v_mov_b32_e32 v0, v224
	v_mov_b32_e32 v2, s0
	v_mov_b32_e32 v3, s2
	s_cselect_b32 s0, s58, 0
	s_cselect_b32 s1, s1, 0
	s_barrier
	ds_read_b32 v1, v2
	s_waitcnt vmcnt(0) lgkmcnt(0)
	v_mov_b32_e32 v2, s0
	v_mov_b32_e32 v3, s1
	ds_read_b32 v2, v2
	s_waitcnt vmcnt(0) lgkmcnt(0)
	s_mov_b32 s1, 0
	s_cmpk_gt_i32 s75, 0x81f
	s_waitcnt lgkmcnt(0)
	v_readfirstlane_b32 s0, v1
	v_readfirstlane_b32 s10, v2
	s_cbranch_scc1 .LBB0_161
	v_and_b32_e32 v2, 63, v0
	v_ashrrev_i32_e32 v3, 3, v0
	s_add_u32 s2, s0, 0x5780000
	v_lshlrev_b32_e32 v4, 2, v2
	v_lshl_add_u32 v5, v2, 4, 0
	s_movk_i32 s4, 0x410
	v_or_b32_e32 v2, 7, v3
	s_addc_u32 s3, s10, 0
	v_and_b32_e32 v6, -8, v3
	v_mul_lo_u32 v12, v2, s4
	v_and_b32_e32 v2, 0xffffffe0, v3
	v_mul_lo_u32 v11, v6, s4
	v_mul_lo_u32 v3, v2, s4
	s_add_u32 s4, s0, 0x4f80000
	s_addc_u32 s5, s10, 0
	s_add_u32 s6, s0, 0x4d80000
	s_addc_u32 s7, s10, 0
	s_add_u32 s8, s0, 0x4a00000
	s_addc_u32 s9, s10, 0
	s_add_u32 s16, s0, 0x3400000
	v_and_b32_e32 v7, 0xff, v0
	s_addc_u32 s17, s10, 0
	v_lshlrev_b32_e32 v8, 2, v7
	v_and_b32_e32 v9, 31, v0
	v_and_b32_e32 v0, 0x60, v0
	s_add_u32 s18, s0, 0x800000
	v_mov_b32_e32 v1, 0
	v_add3_u32 v8, 0, v3, v8
	v_ashrrev_i32_e32 v3, 31, v2
	s_addc_u32 s19, s10, 0
	v_or_b32_e32 v10, 0x80, v0
	s_lshl_b32 s20, s75, 4
	s_lshl_b32 s21, s76, 4
	s_lshl_b32 s22, s75, 2
	s_lshl_b32 s23, s76, 2
	s_lshl_b32 s24, s75, 8
	s_lshl_b32 s25, s76, 8
	s_add_i32 s26, s75, 0xfbe0
	s_add_i32 s27, 0, 0x23fb8
	s_add_i32 s28, 0, 0x23fbc
	v_add_u32_e32 v11, v5, v11
	v_add_u32_e32 v12, v5, v12
	s_movk_i32 s29, 0x3e0
	s_movk_i32 s30, 0x4040
	s_movk_i32 s31, 0xfe0
	s_movk_i32 s34, 0x1c00
	s_mov_b32 s35, 0x7fffff00
	s_movk_i32 s36, 0x5800
	s_movk_i32 s37, 0xaff
	v_lshlrev_b32_e32 v0, 2, v4
	s_add_i32 s38, 0, 0x23fa0
	s_add_i32 s39, 0, 0x23fa4
	v_mov_b32_e32 v13, 0x7e0
	v_mov_b32_e32 v14, 0x7ffffc00
	v_not_b32_e32 v15, 31
	v_mov_b32_e32 v16, 0x7fffea00
	s_mov_b32 s40, s75
	s_branch .LBB0_134

.LBB0_134:
	s_cmpk_gt_i32 s40, 0x41f
	s_mov_b64 s[10:11], -1
	s_cbranch_scc0 .LBB0_156
	s_cmpk_gt_u32 s40, 0x62f
	s_cbranch_scc0 .LBB0_153
	s_cmpk_gt_u32 s40, 0x69f
	s_cbranch_scc0 .LBB0_146
	s_cmpk_gt_u32 s40, 0x6df
	s_cbranch_scc0 .LBB0_143
	s_cmpk_gt_u32 s40, 0x7df
	s_cbranch_scc0 .LBB0_140
	s_mov_b64 s[10:11], src_shared_base
	s_cmp_lg_u32 s27, -1
	s_cselect_b32 s0, s27, 0
	s_cselect_b32 s10, s11, 0
	s_cmp_lg_u32 s28, -1
	v_mov_b32_e32 v4, s0
	v_mov_b32_e32 v5, s10
	s_cselect_b32 s0, s28, 0
	s_cselect_b32 s10, s11, 0
	ds_read_b32 v17, v4
	s_waitcnt vmcnt(0) lgkmcnt(0)
	v_mov_b32_e32 v4, s0
	v_mov_b32_e32 v5, s10
	ds_read_b32 v32, v4
	s_waitcnt vmcnt(0) lgkmcnt(0)
	s_and_b32 s0, s20, 0x7fffffc0
	s_and_b32 s10, s24, 0x300
	s_addk_i32 s0, 0x8200
	s_lshl_b32 s10, s10, 2
	v_add_u32_e32 v4, s0, v6
	v_ashrrev_i32_e32 v5, 31, v4
	v_or_b32_e32 v18, 1, v4
	v_or_b32_e32 v20, 2, v4
	v_or_b32_e32 v22, 3, v4
	v_or_b32_e32 v24, 4, v4
	v_or_b32_e32 v26, 5, v4
	v_or_b32_e32 v28, 6, v4
	v_or_b32_e32 v30, 7, v4
	v_lshlrev_b64 v[4:5], 12, v[4:5]
	v_ashrrev_i32_e32 v19, 31, v18
	v_ashrrev_i32_e32 v21, 31, v20
	v_ashrrev_i32_e32 v23, 31, v22
	v_ashrrev_i32_e32 v25, 31, v24
	v_ashrrev_i32_e32 v27, 31, v26
	v_ashrrev_i32_e32 v29, 31, v28
	v_ashrrev_i32_e32 v31, 31, v30
	v_lshlrev_b64 v[18:19], 12, v[18:19]
	v_lshlrev_b64 v[20:21], 12, v[20:21]
	v_lshlrev_b64 v[22:23], 12, v[22:23]
	v_lshlrev_b64 v[24:25], 12, v[24:25]
	v_lshlrev_b64 v[26:27], 12, v[26:27]
	v_lshlrev_b64 v[28:29], 12, v[28:29]
	v_lshlrev_b64 v[30:31], 12, v[30:31]
	s_waitcnt lgkmcnt(0)
	v_readfirstlane_b32 s11, v17
	s_add_u32 s10, s11, s10
	v_readfirstlane_b32 s12, v32
	s_addc_u32 s11, s12, 0
	v_lshl_add_u64 v[32:33], s[10:11], 0, v[0:1]
	v_lshl_add_u64 v[4:5], v[32:33], 0, v[4:5]
	v_lshl_add_u64 v[50:51], v[32:33], 0, v[18:19]
	v_lshl_add_u64 v[52:53], v[32:33], 0, v[20:21]
	v_lshl_add_u64 v[54:55], v[32:33], 0, v[22:23]
	v_lshl_add_u64 v[56:57], v[32:33], 0, v[24:25]
	v_lshl_add_u64 v[60:61], v[32:33], 0, v[26:27]
	v_lshl_add_u64 v[62:63], v[32:33], 0, v[28:29]
	v_lshl_add_u64 v[64:65], v[32:33], 0, v[30:31]
	global_load_dwordx4 v[18:21], v[4:5], off
	global_load_dwordx4 v[22:25], v[50:51], off
	global_load_dwordx4 v[26:29], v[52:53], off
	global_load_dwordx4 v[30:33], v[54:55], off
	global_load_dwordx4 v[34:37], v[56:57], off
	global_load_dwordx4 v[38:41], v[60:61], off
	global_load_dwordx4 v[42:45], v[62:63], off
	global_load_dwordx4 v[46:49], v[64:65], off
	v_add_u32_e32 v4, s24, v7
	v_and_or_b32 v4, v4, s29, v9
	v_mov_b32_e32 v5, v1
	v_lshlrev_b32_e32 v4, 11, v4
	v_lshl_add_u64 v[4:5], s[2:3], 0, v[4:5]
	v_lshl_add_u64 v[4:5], s[0:1], 1, v[4:5]
	s_barrier
	s_mov_b64 s[10:11], 0
	s_waitcnt vmcnt(7)
	ds_write_b128 v11, v[18:21]
	s_waitcnt vmcnt(6)
	ds_write_b128 v11, v[22:25] offset:1040
	s_waitcnt vmcnt(5)
	ds_write_b128 v11, v[26:29] offset:2080
	s_waitcnt vmcnt(4)
	ds_write_b128 v11, v[30:33] offset:3120
	s_waitcnt vmcnt(3)
	ds_write_b128 v11, v[34:37] offset:4160
	s_waitcnt vmcnt(2)
	ds_write_b128 v11, v[38:41] offset:5200
	s_waitcnt vmcnt(1)
	ds_write_b128 v11, v[42:45] offset:6240
	s_waitcnt vmcnt(0)
	ds_write_b128 v12, v[46:49]
	s_waitcnt lgkmcnt(0)
	s_barrier
.LBB0_140:
	s_andn2_b64 vcc, exec, s[10:11]
	s_cbranch_vccnz .LBB0_142
	s_mov_b64 s[10:11], src_shared_base
	s_cmp_lg_u32 s38, -1
	s_cselect_b32 s0, s38, 0
	s_cselect_b32 s10, s11, 0
	s_cmp_lg_u32 s39, -1
	v_mov_b32_e32 v4, s0
	v_mov_b32_e32 v5, s10
	s_cselect_b32 s0, s39, 0
	s_cselect_b32 s10, s11, 0
	ds_read_b32 v17, v4
	s_waitcnt vmcnt(0) lgkmcnt(0)
	v_mov_b32_e32 v4, s0
	v_mov_b32_e32 v5, s10
	ds_read_b32 v4, v4
	s_waitcnt vmcnt(0) lgkmcnt(0)
	s_and_b32 s0, s22, 0x1fc0
	s_and_b32 s10, s24, 0xf00
	s_addk_i32 s0, 0xe480
	s_lshl_b32 s10, s10, 2
	v_add_u32_e32 v18, s0, v6
	v_or_b32_e32 v20, 1, v18
	v_or_b32_e32 v21, 2, v18
	v_or_b32_e32 v22, 3, v18
	v_or_b32_e32 v23, 4, v18
	v_or_b32_e32 v24, 5, v18
	v_or_b32_e32 v25, 6, v18
	v_or_b32_e32 v26, 7, v18
	s_waitcnt lgkmcnt(0)
	v_readfirstlane_b32 s11, v17
	s_add_u32 s10, s11, s10
	v_readfirstlane_b32 s12, v4
	s_addc_u32 s11, s12, 0
	v_lshl_add_u64 v[4:5], s[10:11], 0, v[0:1]
	v_mad_i64_i32 v[18:19], s[10:11], v18, s30, v[4:5]
	v_mad_i64_i32 v[50:51], s[10:11], v20, s30, v[4:5]
	v_mad_i64_i32 v[52:53], s[10:11], v21, s30, v[4:5]
	v_mad_i64_i32 v[54:55], s[10:11], v22, s30, v[4:5]
	v_mad_i64_i32 v[56:57], s[10:11], v23, s30, v[4:5]
	v_mad_i64_i32 v[60:61], s[10:11], v24, s30, v[4:5]
	v_mad_i64_i32 v[62:63], s[10:11], v25, s30, v[4:5]
	v_mad_i64_i32 v[4:5], s[10:11], v26, s30, v[4:5]
	global_load_dwordx4 v[18:21], v[18:19], off
	s_nop 0
	global_load_dwordx4 v[22:25], v[50:51], off
	global_load_dwordx4 v[26:29], v[52:53], off
	global_load_dwordx4 v[30:33], v[54:55], off
	global_load_dwordx4 v[34:37], v[56:57], off
	global_load_dwordx4 v[38:41], v[60:61], off
	global_load_dwordx4 v[42:45], v[62:63], off
	global_load_dwordx4 v[46:49], v[4:5], off
	v_add_u32_e32 v4, s24, v7
	v_and_or_b32 v4, v4, s31, v9
	v_mov_b32_e32 v5, v1
	v_lshlrev_b32_e32 v4, 11, v4
	v_lshl_add_u64 v[4:5], s[4:5], 0, v[4:5]
	v_lshl_add_u64 v[4:5], s[0:1], 1, v[4:5]
	s_barrier
	s_waitcnt vmcnt(7)
	ds_write_b128 v11, v[18:21]
	s_waitcnt vmcnt(6)
	ds_write_b128 v11, v[22:25] offset:1040
	s_waitcnt vmcnt(5)
	ds_write_b128 v11, v[26:29] offset:2080
	s_waitcnt vmcnt(4)
	ds_write_b128 v11, v[30:33] offset:3120
	s_waitcnt vmcnt(3)
	ds_write_b128 v11, v[34:37] offset:4160
	s_waitcnt vmcnt(2)
	ds_write_b128 v11, v[38:41] offset:5200
	s_waitcnt vmcnt(1)
	ds_write_b128 v11, v[42:45] offset:6240
	s_waitcnt vmcnt(0)
	ds_write_b128 v12, v[46:49]
	s_waitcnt lgkmcnt(0)
	s_barrier

.LBB0_143:
	s_andn2_b64 vcc, exec, s[10:11]
	s_cbranch_vccnz .LBB0_145
	s_add_i32 s0, 0, 0x23f98
	s_cmp_lg_u32 s0, -1
	s_mov_b64 s[10:11], src_shared_base
	s_cselect_b32 s0, s0, 0
	s_cselect_b32 s10, s11, 0
	v_mov_b32_e32 v4, s0
	s_add_i32 s0, 0, 0x23f9c
	s_cmp_lg_u32 s0, -1
	v_mov_b32_e32 v5, s10
	s_cselect_b32 s0, s0, 0
	s_cselect_b32 s10, s11, 0
	ds_read_b32 v17, v4
	s_waitcnt vmcnt(0) lgkmcnt(0)
	v_mov_b32_e32 v4, s0
	v_mov_b32_e32 v5, s10
	ds_read_b32 v32, v4
	s_waitcnt vmcnt(0) lgkmcnt(0)
	s_and_b32 s0, s20, 0x7fc0
	s_and_b32 s10, s24, 0x300
	s_addk_i32 s0, 0x9600
	s_lshl_b32 s10, s10, 2
	v_add_u32_e32 v4, s0, v6
	v_ashrrev_i32_e32 v5, 31, v4
	v_or_b32_e32 v18, 1, v4
	v_or_b32_e32 v20, 2, v4
	v_or_b32_e32 v22, 3, v4
	v_or_b32_e32 v24, 4, v4
	v_or_b32_e32 v26, 5, v4
	v_or_b32_e32 v28, 6, v4
	v_or_b32_e32 v30, 7, v4
	v_lshlrev_b64 v[4:5], 12, v[4:5]
	v_ashrrev_i32_e32 v19, 31, v18
	v_ashrrev_i32_e32 v21, 31, v20
	v_ashrrev_i32_e32 v23, 31, v22
	v_ashrrev_i32_e32 v25, 31, v24
	v_ashrrev_i32_e32 v27, 31, v26
	v_ashrrev_i32_e32 v29, 31, v28
	v_ashrrev_i32_e32 v31, 31, v30
	v_lshlrev_b64 v[18:19], 12, v[18:19]
	v_lshlrev_b64 v[20:21], 12, v[20:21]
	v_lshlrev_b64 v[22:23], 12, v[22:23]
	v_lshlrev_b64 v[24:25], 12, v[24:25]
	v_lshlrev_b64 v[26:27], 12, v[26:27]
	v_lshlrev_b64 v[28:29], 12, v[28:29]
	v_lshlrev_b64 v[30:31], 12, v[30:31]
	s_waitcnt lgkmcnt(0)
	v_readfirstlane_b32 s11, v17
	s_add_u32 s10, s11, s10
	v_readfirstlane_b32 s11, v32
	s_addc_u32 s11, s11, 0
	s_nop 0
	v_lshl_add_u64 v[32:33], s[10:11], 0, v[0:1]
	v_lshl_add_u64 v[4:5], v[32:33], 0, v[4:5]
	v_lshl_add_u64 v[50:51], v[32:33], 0, v[18:19]
	v_lshl_add_u64 v[52:53], v[32:33], 0, v[20:21]
	v_lshl_add_u64 v[54:55], v[32:33], 0, v[22:23]
	v_lshl_add_u64 v[56:57], v[32:33], 0, v[24:25]
	v_lshl_add_u64 v[60:61], v[32:33], 0, v[26:27]
	v_lshl_add_u64 v[62:63], v[32:33], 0, v[28:29]
	v_lshl_add_u64 v[64:65], v[32:33], 0, v[30:31]
	global_load_dwordx4 v[18:21], v[4:5], off
	global_load_dwordx4 v[22:25], v[50:51], off
	global_load_dwordx4 v[26:29], v[52:53], off
	global_load_dwordx4 v[30:33], v[54:55], off
	global_load_dwordx4 v[34:37], v[56:57], off
	global_load_dwordx4 v[38:41], v[60:61], off
	global_load_dwordx4 v[42:45], v[62:63], off
	global_load_dwordx4 v[46:49], v[64:65], off
	v_add_u32_e32 v4, s24, v7
	v_and_or_b32 v4, v4, s29, v9
	v_mov_b32_e32 v5, v1
	v_lshlrev_b32_e32 v4, 11, v4
	v_lshl_add_u64 v[4:5], s[6:7], 0, v[4:5]
	v_lshl_add_u64 v[4:5], s[0:1], 1, v[4:5]
	s_barrier
	s_waitcnt vmcnt(7)
	ds_write_b128 v11, v[18:21]
	s_waitcnt vmcnt(6)
	ds_write_b128 v11, v[22:25] offset:1040
	s_waitcnt vmcnt(5)
	ds_write_b128 v11, v[26:29] offset:2080
	s_waitcnt vmcnt(4)
	ds_write_b128 v11, v[30:33] offset:3120
	s_waitcnt vmcnt(3)
	ds_write_b128 v11, v[34:37] offset:4160
	s_waitcnt vmcnt(2)
	ds_write_b128 v11, v[38:41] offset:5200
	s_waitcnt vmcnt(1)
	ds_write_b128 v11, v[42:45] offset:6240
	s_waitcnt vmcnt(0)
	ds_write_b128 v12, v[46:49]
	s_waitcnt lgkmcnt(0)
	s_barrier

.LBB0_146:
	s_andn2_b64 vcc, exec, s[10:11]
	s_cbranch_vccnz .LBB0_152
	s_mov_b64 s[10:11], src_shared_base
	s_add_i32 s0, s40, 0xffd0
	s_and_b32 s10, s0, 0xff
	s_mul_i32 s10, s10, 37
	s_lshr_b32 s12, s10, 8
	s_sub_i32 s12, s0, s12
	s_bfe_u32 s12, s12, 0x70001
	s_bfe_u32 s10, s10, 0x80008
	s_add_i32 s12, s12, s10
	s_bfe_u32 s10, s12, 0x60002
	s_mul_i32 s12, s10, 7
	s_sub_i32 s0, s0, s12
	s_and_b32 s12, s0, 0xff
	s_add_i32 s0, 0, 0x23f68
	s_cmp_lg_u32 s0, -1
	s_cselect_b32 s0, s0, 0
	s_cselect_b32 s13, s11, 0
	v_mov_b32_e32 v4, s0
	s_add_i32 s0, 0, 0x23f6c
	s_cmp_lg_u32 s0, -1
	v_mov_b32_e32 v5, s13
	s_cselect_b32 s0, s0, 0
	s_cselect_b32 s11, s11, 0
	ds_read_b32 v17, v4
	s_waitcnt vmcnt(0) lgkmcnt(0)
	v_mov_b32_e32 v4, s0
	v_mov_b32_e32 v5, s11
	ds_read_b32 v4, v4
	s_waitcnt vmcnt(0) lgkmcnt(0)
	s_lshl_b32 s0, s10, 6
	s_lshl_b32 s13, s12, 8
	s_lshl_b32 s10, s12, 10
	v_add_u32_e32 v18, s0, v6
	v_or_b32_e32 v20, 1, v18
	v_or_b32_e32 v21, 2, v18
	v_or_b32_e32 v24, 3, v18
	v_or_b32_e32 v25, 4, v18
	v_or_b32_e32 v28, 5, v18
	v_or_b32_e32 v29, 6, v18
	v_or_b32_e32 v32, 7, v18
	s_waitcnt lgkmcnt(0)
	v_readfirstlane_b32 s11, v17
	s_add_u32 s10, s11, s10
	v_readfirstlane_b32 s11, v4
	s_addc_u32 s11, s11, 0
	s_nop 0
	v_lshl_add_u64 v[4:5], s[10:11], 0, v[0:1]
	v_mad_i64_i32 v[18:19], s[10:11], v18, s34, v[4:5]
	v_mad_i64_i32 v[22:23], s[10:11], v20, s34, v[4:5]
	v_mad_i64_i32 v[26:27], s[10:11], v21, s34, v[4:5]
	v_mad_i64_i32 v[30:31], s[10:11], v24, s34, v[4:5]
	v_mad_i64_i32 v[34:35], s[10:11], v25, s34, v[4:5]
	v_mad_i64_i32 v[38:39], s[10:11], v28, s34, v[4:5]
	v_mad_i64_i32 v[42:43], s[10:11], v29, s34, v[4:5]
	v_mad_i64_i32 v[4:5], s[10:11], v32, s34, v[4:5]
	global_load_dwordx4 v[18:21], v[18:19], off
	s_nop 0
	global_load_dwordx4 v[22:25], v[22:23], off
	s_nop 0
	global_load_dwordx4 v[26:29], v[26:27], off
	s_nop 0
	global_load_dwordx4 v[30:33], v[30:31], off
	s_nop 0
	global_load_dwordx4 v[34:37], v[34:35], off
	s_nop 0
	global_load_dwordx4 v[38:41], v[38:39], off
	s_nop 0
	global_load_dwordx4 v[42:45], v[42:43], off
	s_nop 0
	global_load_dwordx4 v[46:49], v[4:5], off
	v_or_b32_e32 v4, s13, v7
	v_bitop3_b32 v5, s13, v13, v7 bitop3:0xc8
	s_cmp_gt_u32 s12, 1
	s_mov_b64 s[10:11], -1
	s_barrier
	s_waitcnt vmcnt(7)
	ds_write_b128 v11, v[18:21]
	s_waitcnt vmcnt(6)
	ds_write_b128 v11, v[22:25] offset:1040
	s_waitcnt vmcnt(5)
	ds_write_b128 v11, v[26:29] offset:2080
	s_waitcnt vmcnt(4)
	ds_write_b128 v11, v[30:33] offset:3120
	s_waitcnt vmcnt(3)
	ds_write_b128 v11, v[34:37] offset:4160
	s_waitcnt vmcnt(2)
	ds_write_b128 v11, v[38:41] offset:5200
	s_waitcnt vmcnt(1)
	ds_write_b128 v11, v[42:45] offset:6240
	s_waitcnt vmcnt(0)
	ds_write_b128 v12, v[46:49]
	s_waitcnt lgkmcnt(0)
	s_barrier
	s_cbranch_scc0 .LBB0_149
	s_cmp_lt_u32 s12, 4
	v_lshl_add_u32 v17, v4, 1, v14
	v_and_or_b32 v17, v17, s35, v10
	s_cselect_b64 vcc, -1, 0
	v_cndmask_b32_e32 v17, v5, v17, vcc
	s_mov_b64 s[10:11], 0

.LBB0_153:
	s_andn2_b64 vcc, exec, s[10:11]
	s_cbranch_vccnz .LBB0_155
	s_mov_b64 s[10:11], src_shared_base
	s_and_b32 s0, 0xffff, s26
	s_mul_hi_u32 s0, s0, 0x1745d18
	s_mul_i32 s10, s40, 0xba2f
	s_mul_i32 s0, s0, 0xff50
	s_add_i32 s10, s10, 0xfcfffe20
	s_lshr_b32 s10, s10, 23
	s_add_i32 s0, s40, s0
	s_add_i32 s10, s10, 1
	s_add_i32 s0, s0, 0xfbe0
	s_lshr_b32 s12, s10, 1
	s_and_b32 s13, s10, 1
	s_sext_i32_i16 s10, s0
	s_bfe_u32 s10, s10, 0x2001d
	s_add_i32 s10, s0, s10
	s_and_b32 s14, s10, 0xfffc
	s_sub_i32 s14, s0, s14
	s_cmp_eq_u32 s13, 0
	s_cselect_b32 s0, 64, 0x60
	s_add_i32 s0, s0, 0
	s_add_i32 s15, s0, 0x23f00
	v_mov_b32_e32 v4, s15
	v_mov_b32_e32 v5, s11
	s_add_i32 s0, s0, 0x23f04
	ds_read_b32 v17, v4
	s_waitcnt vmcnt(0) lgkmcnt(0)
	v_mov_b32_e32 v4, s0
	ds_read_b32 v4, v4
	s_waitcnt vmcnt(0) lgkmcnt(0)
	s_mul_i32 s0, s12, 0x2c0000
	s_sext_i32_i16 s15, s10
	s_lshl_b64 s[10:11], s[0:1], 2
	s_sext_i32_i16 s14, s14
	s_waitcnt lgkmcnt(0)
	v_readfirstlane_b32 s0, v17
	s_add_u32 s44, s0, s10
	v_readfirstlane_b32 s41, v4
	s_addc_u32 s41, s41, s11
	s_lshl_b32 s0, s12, 11
	s_lshl_b32 s10, s13, 10
	s_or_b32 s0, s10, s0
	s_mulk_i32 s0, 0xb00
	s_lshl_b64 s[10:11], s[0:1], 1
	s_add_u32 s12, s16, s10
	s_addc_u32 s13, s17, s11
	s_lshl_b32 s0, s15, 4
	s_lshl_b32 s14, s14, 8
	s_and_b32 s10, s0, 0xffffffc0
	s_ashr_i32 s15, s14, 31
	v_add_u32_e32 v4, s10, v6
	s_lshl_b64 s[42:43], s[14:15], 2
	s_add_u32 s42, s44, s42
	v_or_b32_e32 v18, 1, v4
	v_or_b32_e32 v20, 2, v4
	v_or_b32_e32 v22, 3, v4
	v_or_b32_e32 v24, 4, v4
	v_or_b32_e32 v26, 5, v4
	v_or_b32_e32 v28, 6, v4
	v_or_b32_e32 v30, 7, v4
	v_ashrrev_i32_e32 v5, 31, v4
	s_addc_u32 s43, s41, s43
	v_ashrrev_i32_e32 v19, 31, v18
	v_ashrrev_i32_e32 v21, 31, v20
	v_ashrrev_i32_e32 v23, 31, v22
	v_ashrrev_i32_e32 v25, 31, v24
	v_ashrrev_i32_e32 v27, 31, v26
	v_ashrrev_i32_e32 v29, 31, v28
	v_ashrrev_i32_e32 v31, 31, v30
	v_lshlrev_b64 v[4:5], 12, v[4:5]
	v_lshl_add_u64 v[32:33], s[42:43], 0, v[0:1]
	v_lshlrev_b64 v[18:19], 12, v[18:19]
	v_lshlrev_b64 v[20:21], 12, v[20:21]
	v_lshlrev_b64 v[22:23], 12, v[22:23]
	v_lshlrev_b64 v[24:25], 12, v[24:25]
	v_lshlrev_b64 v[26:27], 12, v[26:27]
	v_lshlrev_b64 v[28:29], 12, v[28:29]
	v_lshlrev_b64 v[30:31], 12, v[30:31]
	v_lshl_add_u64 v[4:5], v[32:33], 0, v[4:5]
	v_lshl_add_u64 v[34:35], v[32:33], 0, v[18:19]
	v_lshl_add_u64 v[36:37], v[32:33], 0, v[20:21]
	v_lshl_add_u64 v[38:39], v[32:33], 0, v[22:23]
	v_lshl_add_u64 v[40:41], v[32:33], 0, v[24:25]
	v_lshl_add_u64 v[42:43], v[32:33], 0, v[26:27]
	v_lshl_add_u64 v[44:45], v[32:33], 0, v[28:29]
	v_lshl_add_u64 v[46:47], v[32:33], 0, v[30:31]
	global_load_dwordx4 v[18:21], v[4:5], off
	global_load_dwordx4 v[22:25], v[34:35], off
	global_load_dwordx4 v[26:29], v[36:37], off
	global_load_dwordx4 v[30:33], v[38:39], off
	s_nop 0
	global_load_dwordx4 v[34:37], v[40:41], off
	s_nop 0
	global_load_dwordx4 v[38:41], v[42:43], off
	s_nop 0
	global_load_dwordx4 v[42:45], v[44:45], off
	s_nop 0
	global_load_dwordx4 v[46:49], v[46:47], off
	v_or_b32_e32 v4, s14, v7
	v_mul_i32_i24_e32 v4, 0xb00, v4
	v_ashrrev_i32_e32 v5, 31, v4
	v_lshl_add_u64 v[4:5], v[4:5], 1, s[12:13]
	s_ashr_i32 s11, s10, 31
	v_lshl_add_u64 v[4:5], s[10:11], 1, v[4:5]
	s_barrier
	s_waitcnt vmcnt(7)
	ds_write_b128 v11, v[18:21]
	s_waitcnt vmcnt(6)
	ds_write_b128 v11, v[22:25] offset:1040
	s_waitcnt vmcnt(5)
	ds_write_b128 v11, v[26:29] offset:2080
	s_waitcnt vmcnt(4)
	ds_write_b128 v11, v[30:33] offset:3120
	s_waitcnt vmcnt(3)
	ds_write_b128 v11, v[34:37] offset:4160
	s_waitcnt vmcnt(2)
	ds_write_b128 v11, v[38:41] offset:5200
	s_waitcnt vmcnt(1)
	ds_write_b128 v11, v[42:45] offset:6240
	s_waitcnt vmcnt(0)
	ds_write_b128 v12, v[46:49]
	s_waitcnt lgkmcnt(0)
	s_barrier

.LBB0_156:
	s_andn2_b64 vcc, exec, s[10:11]
	s_cbranch_vccnz .LBB0_133
	s_mov_b64 s[10:11], src_shared_base
	s_mul_hi_i32 s0, s40, 0x2e8ba2e9
	s_lshr_b32 s10, s0, 31
	s_ashr_i32 s0, s0, 6
	s_add_i32 s10, s0, s10
	s_mul_i32 s13, s10, 0xfffffea0
	s_add_i32 s13, s40, s13
	s_mul_hi_i32 s14, s13, 0x2e8ba2e9
	s_lshr_b32 s15, s14, 31
	s_ashr_i32 s14, s14, 2
	s_add_i32 s14, s14, s15
	s_add_i32 s0, s10, 1
	s_mul_i32 s15, s14, 22
	s_ashr_i32 s12, s0, 1
	s_sub_i32 s13, s13, s15
	s_bitcmp0_b32 s10, 0
	s_cselect_b32 s10, 0x58, 56
	s_add_i32 s10, s10, 0
	s_add_i32 s15, s10, 0x23f00
	v_mov_b32_e32 v4, s15
	v_mov_b32_e32 v5, s11
	s_add_i32 s10, s10, 0x23f04
	ds_read_b32 v17, v4
	s_waitcnt vmcnt(0) lgkmcnt(0)
	v_mov_b32_e32 v4, s10
	ds_read_b32 v4, v4
	s_waitcnt vmcnt(0) lgkmcnt(0)
	s_mul_hi_i32 s10, s12, 0x1600000
	s_mul_i32 s12, s12, 0x1600000
	s_waitcnt lgkmcnt(0)
	v_readfirstlane_b32 s11, v17
	s_add_u32 s11, s11, s12
	v_readfirstlane_b32 s15, v4
	s_addc_u32 s41, s15, s10
	s_lshl_b32 s12, s13, 8
	s_ashr_i32 s13, s12, 31
	s_lshl_b32 s10, s14, 6
	s_lshl_b64 s[14:15], s[12:13], 2
	s_add_u32 s14, s11, s14
	v_add_u32_e32 v17, s10, v6
	s_addc_u32 s15, s41, s15
	v_or_b32_e32 v20, 1, v17
	v_or_b32_e32 v21, 2, v17
	v_or_b32_e32 v24, 3, v17
	v_or_b32_e32 v25, 4, v17
	v_or_b32_e32 v28, 5, v17
	v_or_b32_e32 v29, 6, v17
	v_lshl_add_u64 v[4:5], s[14:15], 0, v[0:1]
	v_or_b32_e32 v32, 7, v17
	v_mad_i64_i32 v[18:19], s[14:15], v17, s36, v[4:5]
	v_mad_i64_i32 v[22:23], s[14:15], v20, s36, v[4:5]
	v_mad_i64_i32 v[26:27], s[14:15], v21, s36, v[4:5]
	v_mad_i64_i32 v[30:31], s[14:15], v24, s36, v[4:5]
	v_mad_i64_i32 v[34:35], s[14:15], v25, s36, v[4:5]
	v_mad_i64_i32 v[38:39], s[14:15], v28, s36, v[4:5]
	v_mad_i64_i32 v[42:43], s[14:15], v29, s36, v[4:5]
	v_mad_i64_i32 v[4:5], s[14:15], v32, s36, v[4:5]
	global_load_dwordx4 v[18:21], v[18:19], off
	s_nop 0
	global_load_dwordx4 v[22:25], v[22:23], off
	s_nop 0
	global_load_dwordx4 v[26:29], v[26:27], off
	s_nop 0
	global_load_dwordx4 v[30:33], v[30:31], off
	s_nop 0
	global_load_dwordx4 v[34:37], v[34:35], off
	s_nop 0
	global_load_dwordx4 v[38:41], v[38:39], off
	s_nop 0
	global_load_dwordx4 v[42:45], v[42:43], off
	s_nop 0
	global_load_dwordx4 v[46:49], v[4:5], off
	v_bitop3_b32 v4, s12, v15, v7 bitop3:0xc8
	v_cmp_lt_i32_e32 vcc, s37, v4
	s_barrier
	s_waitcnt vmcnt(7)
	ds_write_b128 v11, v[18:21]
	s_waitcnt vmcnt(6)
	ds_write_b128 v11, v[22:25] offset:1040
	s_waitcnt vmcnt(5)
	ds_write_b128 v11, v[26:29] offset:2080
	s_waitcnt vmcnt(4)
	ds_write_b128 v11, v[30:33] offset:3120
	s_waitcnt vmcnt(3)
	ds_write_b128 v11, v[34:37] offset:4160
	s_waitcnt vmcnt(2)
	ds_write_b128 v11, v[38:41] offset:5200
	s_waitcnt vmcnt(1)
	ds_write_b128 v11, v[42:45] offset:6240
	s_waitcnt vmcnt(0)
	ds_write_b128 v12, v[46:49]
	s_waitcnt lgkmcnt(0)
	s_barrier
	s_and_saveexec_b64 s[14:15], vcc
	s_xor_b64 s[14:15], exec, s[14:15]
	v_or_b32_e32 v4, s12, v7
	v_lshl_add_u32 v4, v4, 1, v16
	v_and_or_b32 v5, v4, s35, v10
	s_andn2_saveexec_b64 s[12:13], s[14:15]
	s_cbranch_execz .LBB0_132
	v_ashrrev_i32_e32 v5, 31, v4
	v_lshrrev_b32_e32 v5, 25, v5
	v_add_u32_e32 v5, v4, v5
	v_and_b32_e32 v5, 0xffffff80, v5
	v_add_u32_e32 v5, v5, v4
	s_branch .LBB0_132
.LBB0_161:
	s_mov_b64 s[0:1], src_shared_base
	s_cmp_lg_u32 s57, -1
	s_cselect_b32 s0, s57, 0
	s_cselect_b32 s2, s1, 0
	s_cmp_lg_u32 s58, -1
	v_mov_b32_e32 v0, s0
	v_mov_b32_e32 v1, s2
	s_cselect_b32 s0, s58, 0
	s_cselect_b32 s1, s1, 0
	s_barrier
	ds_read_b32 v2, v0
	s_waitcnt vmcnt(0) lgkmcnt(0)
	v_mov_b32_e32 v0, s0
	v_mov_b32_e32 v1, s1
	ds_read_b32 v0, v0
	s_waitcnt vmcnt(0) lgkmcnt(0)
	s_getreg_b32 s4, hwreg(HW_REG_XCC_ID, 0, 4)
	s_waitcnt vmcnt(0)
	s_waitcnt lgkmcnt(0)
	s_barrier
	v_readfirstlane_b32 s2, v2
	v_readfirstlane_b32 s3, v0
	s_and_saveexec_b64 s[0:1], s[78:79]
	s_cbranch_execz .LBB0_213
	s_add_i32 s5, 0, 0x23e00
	v_mov_b32_e32 v0, s5
	s_waitcnt vmcnt(0) expcnt(0) lgkmcnt(0)
	ds_read_b32 v2, v0
	s_add_i32 s5, 0, 0x23e04
	v_mov_b32_e32 v0, s5
	ds_read_b32 v0, v0
	s_and_b32 s46, s4, 15
	s_waitcnt lgkmcnt(1)
	v_cmp_ne_u32_e32 vcc, 0, v2
	s_cbranch_vccnz .LBB0_177
	s_add_u32 s4, s2, 0x3c0200
	s_addc_u32 s5, s3, 0
	s_add_u32 s6, s2, 0x3c0400
	s_addc_u32 s7, s3, 0
	s_add_u32 s8, s2, 0x3c0500
	s_addc_u32 s9, s3, 0
	s_add_u32 s10, s2, 0x3c0600
	s_addc_u32 s11, s3, 0
	s_add_u32 s12, s2, 0x3c0700
	s_addc_u32 s13, s3, 0
	s_add_u32 s14, s2, 0x3c0800
	s_addc_u32 s15, s3, 0
	s_add_u32 s16, s2, 0x3c0900
	s_addc_u32 s17, s3, 0
	s_add_u32 s18, s2, 0x3c0a00
	s_addc_u32 s19, s3, 0
	s_add_u32 s20, s2, 0x3c0b00
	s_addc_u32 s21, s3, 0
	s_add_u32 s22, s2, 0x3c0c00
	s_addc_u32 s23, s3, 0
	s_add_u32 s24, s2, 0x3c0d00
	s_addc_u32 s25, s3, 0
	s_add_u32 s26, s2, 0x3c0e00
	s_addc_u32 s27, s3, 0
	s_add_u32 s28, s2, 0x3c0f00
	s_addc_u32 s29, s3, 0
	s_add_u32 s30, s2, 0x3c1000
	s_addc_u32 s31, s3, 0
	s_add_u32 s34, s2, 0x3c1100
	s_addc_u32 s35, s3, 0
	s_add_u32 s36, s2, 0x3c1200
	s_addc_u32 s37, s3, 0
	s_mul_i32 s47, s77, s33
	s_add_u32 s38, s2, 0x3c1300
	s_mul_i32 s47, s47, s76
	s_addc_u32 s39, s3, 0
	s_mov_b32 s48, 1
	v_mov_b32_e32 v16, 0
	s_branch .LBB0_165

.LBB0_217:
	s_cmp_lg_u32 s57, -1
	s_cselect_b32 s0, s57, 0
	s_cselect_b32 s1, s55, 0
	s_cmp_lg_u32 s58, -1
	v_mov_b32_e32 v2, s0
	v_mov_b32_e32 v3, s1
	s_cselect_b32 s0, s58, 0
	s_cselect_b32 s1, s55, 0
	ds_read_b32 v1, v2
	s_waitcnt vmcnt(0) lgkmcnt(0)
	v_mov_b32_e32 v2, s0
	v_mov_b32_e32 v3, s1
	ds_read_b32 v2, v2
	s_waitcnt vmcnt(0) lgkmcnt(0)
	s_mul_i32 s0, s49, 0x33000
	v_writelane_b32 v254, s0, 26
	s_lshl_b32 s0, s49, 1
	v_writelane_b32 v254, s0, 27
	v_readlane_b32 s0, v253, 7
	v_mov_b32_e32 v10, v224
	v_readlane_b32 s1, v253, 8
	s_andn2_b64 vcc, exec, s[0:1]
	v_writelane_b32 v254, s49, 28
	v_readfirstlane_b32 s0, v10
	s_waitcnt lgkmcnt(0)
	v_readfirstlane_b32 s8, v1
	v_readfirstlane_b32 s9, v2
	s_cbranch_vccnz .LBB0_233
	v_lshlrev_b32_e32 v1, 4, v10
	v_add_u32_e32 v2, 0x2000, v1
	v_ashrrev_i32_e32 v3, 31, v2
	v_lshrrev_b32_e32 v3, 22, v3
	v_add_u32_e32 v3, v2, v3
	v_ashrrev_i32_e32 v11, 10, v3
	v_mul_i32_i24_e32 v3, 0x400, v11
	v_sub_u32_e32 v2, v2, v3
	v_lshrrev_b32_e32 v3, 4, v2
	v_bitop3_b32 v2, v3, v2, 32 bitop3:0x6c
	s_add_u32 s26, s8, 0x5a00000
	v_readlane_b32 s1, v254, 27
	v_ashrrev_i32_e32 v3, 31, v2
	s_addc_u32 s27, s9, 0
	s_mul_i32 s1, s1, 0xb00000
	v_lshrrev_b32_e32 v3, 26, v3
	s_add_u32 s1, s8, s1
	v_add_u32_e32 v3, v2, v3
	v_lshlrev_b32_e32 v4, 3, v11
	s_addc_u32 s4, s9, 0
	v_ashrrev_i32_e32 v12, 6, v3
	v_and_b32_e32 v4, -16, v4
	s_add_u32 s28, s1, 0x800000
	v_add_u32_e32 v4, v12, v4
	s_addc_u32 s29, s4, 0
	v_and_b32_e32 v5, 3, v12
	s_mov_b32 s4, 0x1fffe0
	v_lshrrev_b32_e32 v6, 2, v4
	v_lshlrev_b32_e32 v7, 1, v4
	v_and_or_b32 v5, v4, s4, v5
	v_and_b32_e32 v6, 4, v6
	v_and_b32_e32 v7, 24, v7
	v_and_b32_e32 v3, 0xc0, v3
	v_or3_b32 v5, v5, v6, v7
	v_sub_u32_e32 v2, v2, v3
	v_mov_b32_e32 v7, 1
	v_lshlrev_b32_e32 v6, 5, v11
	v_ashrrev_i16_sdwa v2, v7, sext(v2) dst_sel:DWORD dst_unused:UNUSED_PAD src0_sel:DWORD src1_sel:BYTE_0
	v_and_b32_e32 v6, 32, v6
	v_bfe_i32 v13, v2, 0, 16
	v_add_lshl_u32 v2, v6, v13, 1
	v_lshl_add_u32 v148, v5, 11, v2
	v_lshl_add_u32 v150, v4, 11, v2
	v_bfe_i32 v2, v10, 27, 1
	v_lshrrev_b32_e32 v2, 22, v2
	v_add_u32_e32 v2, v1, v2
	v_and_b32_e32 v2, 0xfffffc00, v2
	v_sub_u32_e32 v1, v1, v2
	v_lshrrev_b32_e32 v2, 4, v1
	v_bitop3_b32 v2, v2, v1, 32 bitop3:0x6c
	v_ashrrev_i32_e32 v1, 31, v1
	v_lshrrev_b32_e32 v1, 26, v1
	v_add_u32_e32 v1, v2, v1
	v_ashrrev_i32_e32 v14, 6, v1
	v_ashrrev_i32_e32 v1, 31, v10
	v_lshrrev_b32_e32 v1, 26, v1
	v_add_u32_e32 v1, v10, v1
	v_ashrrev_i32_e32 v15, 6, v1
	v_lshlrev_b32_e32 v1, 3, v15
	v_and_b32_e32 v1, -16, v1
	v_add_u32_e32 v1, v14, v1
	v_and_b32_e32 v3, 3, v14
	v_lshrrev_b32_e32 v4, 2, v1
	v_lshlrev_b32_e32 v5, 1, v1
	s_ashr_i32 s10, s0, 6
	v_and_or_b32 v3, v1, s4, v3
	v_and_b32_e32 v4, 4, v4
	v_and_b32_e32 v5, 24, v5
	s_ashr_i32 s1, s0, 8
	s_lshl_b32 s30, s10, 10
	v_or3_b32 v3, v3, v4, v5
	v_mul_i32_i24_e32 v5, 64, v14
	v_readlane_b32 s4, v253, 52
	v_sub_u32_e32 v2, v2, v5
	v_readlane_b32 s5, v253, 53
	s_add_u32 s20, s26, s4
	v_lshlrev_b32_e32 v4, 5, v15
	v_ashrrev_i16_sdwa v2, v7, sext(v2) dst_sel:DWORD dst_unused:UNUSED_PAD src0_sel:DWORD src1_sel:BYTE_0
	s_addc_u32 s21, s27, s5
	v_readlane_b32 s4, v253, 54
	v_and_b32_e32 v4, 32, v4
	v_bfe_i32 v16, v2, 0, 16
	v_readlane_b32 s5, v253, 55
	s_add_u32 s22, s28, s4
	v_add_lshl_u32 v2, v4, v16, 1
	s_addc_u32 s23, s29, s5
	s_add_i32 s31, s30, 0
	v_lshl_add_u32 v152, v3, 11, v2
	s_add_i32 m0, s31, 0x10000
	v_lshl_add_u32 v154, v1, 11, v2
	global_load_lds_dwordx4 v152, s[22:23]
	s_add_i32 m0, s31, 0x12000
	s_add_u32 s4, s22, 0x40000
	global_load_lds_dwordx4 v148, s[22:23]
	s_addc_u32 s5, s23, 0
	s_add_i32 m0, s31, 0x14000
	s_add_i32 s34, s31, 0x2000
	global_load_lds_dwordx4 v152, s[4:5]
	s_add_i32 m0, s31, 0x16000
	v_mov_b32_e32 v153, v0
	global_load_lds_dwordx4 v148, s[4:5]
	s_mov_b32 m0, s31
	s_add_u32 s4, s20, 0x40000
	global_load_lds_dwordx4 v154, s[20:21]
	s_mov_b32 m0, s34
	s_addc_u32 s5, s21, 0
	s_add_i32 s35, s31, 0x4000
	global_load_lds_dwordx4 v150, s[20:21]
	s_mov_b32 m0, s35
	s_add_i32 s36, s31, 0x6000
	global_load_lds_dwordx4 v154, s[4:5]
	s_mov_b32 m0, s36
	v_mov_b32_e32 v149, v0
	global_load_lds_dwordx4 v150, s[4:5]
	v_mov_b32_e32 v155, v0
	v_mov_b32_e32 v151, v0
	s_cmp_eq_u32 s1, 1
	v_lshl_add_u64 v[8:9], s[22:23], 0, v[152:153]
	v_lshl_add_u64 v[6:7], s[22:23], 0, v[148:149]
	v_lshl_add_u64 v[2:3], s[20:21], 0, v[154:155]
	s_cselect_b64 s[4:5], -1, 0
	s_cmp_lg_u32 s1, 1
	v_lshl_add_u64 v[4:5], s[20:21], 0, v[150:151]
	s_cbranch_scc1 .LBB0_220
	s_barrier

.LBB0_233:
	s_cmp_lg_u32 s57, -1
	s_cselect_b32 s0, s57, 0
	s_cselect_b32 s1, s55, 0
	s_cmp_lg_u32 s58, -1
	v_mov_b32_e32 v2, s0
	v_mov_b32_e32 v3, s1
	s_cselect_b32 s0, s58, 0
	s_cselect_b32 s1, s55, 0
	ds_read_b32 v1, v2
	s_waitcnt vmcnt(0) lgkmcnt(0)
	v_mov_b32_e32 v2, s0
	v_mov_b32_e32 v3, s1
	ds_read_b32 v2, v2
	s_waitcnt vmcnt(0) lgkmcnt(0)
	s_getreg_b32 s6, hwreg(HW_REG_XCC_ID, 0, 4)
	s_waitcnt vmcnt(0)
	s_waitcnt lgkmcnt(0)
	s_barrier
	v_readfirstlane_b32 s4, v1
	v_readfirstlane_b32 s5, v2
	s_and_saveexec_b64 s[0:1], s[78:79]
	s_cbranch_execz .LBB0_285
	v_readlane_b32 s7, v253, 59
	s_waitcnt vmcnt(0) expcnt(0) lgkmcnt(0)
	s_and_b32 s33, s6, 15
	v_mov_b32_e32 v1, s7
	ds_read_b32 v3, v1
	v_readlane_b32 s7, v253, 60
	s_waitcnt lgkmcnt(0)
	v_cmp_ne_u32_e32 vcc, 0, v3
	v_mov_b32_e32 v1, s7
	ds_read_b32 v2, v1
	s_cbranch_vccnz .LBB0_249
	s_add_u32 s6, s4, 0x3c0200
	s_addc_u32 s7, s5, 0
	s_add_u32 s8, s4, 0x3c0400
	s_addc_u32 s9, s5, 0
	s_add_u32 s10, s4, 0x3c0500
	s_addc_u32 s11, s5, 0
	s_add_u32 s12, s4, 0x3c0600
	s_addc_u32 s13, s5, 0
	s_add_u32 s14, s4, 0x3c0700
	s_addc_u32 s15, s5, 0
	s_add_u32 s16, s4, 0x3c0800
	s_addc_u32 s17, s5, 0
	s_add_u32 s18, s4, 0x3c0900
	s_addc_u32 s19, s5, 0
	s_add_u32 s20, s4, 0x3c0a00
	s_addc_u32 s21, s5, 0
	s_add_u32 s22, s4, 0x3c0b00
	s_addc_u32 s23, s5, 0
	s_add_u32 s24, s4, 0x3c0c00
	s_addc_u32 s25, s5, 0
	s_add_u32 s26, s4, 0x3c0d00
	s_addc_u32 s27, s5, 0
	s_add_u32 s28, s4, 0x3c0e00
	s_addc_u32 s29, s5, 0
	s_add_u32 s30, s4, 0x3c0f00
	s_addc_u32 s31, s5, 0
	s_add_u32 s34, s4, 0x3c1000
	s_addc_u32 s35, s5, 0
	s_add_u32 s36, s4, 0x3c1100
	s_addc_u32 s37, s5, 0
	s_add_u32 s38, s4, 0x3c1200
	s_addc_u32 s39, s5, 0
	s_add_u32 s40, s4, 0x3c1300
	s_addc_u32 s41, s5, 0
	s_mov_b32 s48, 1
	s_branch .LBB0_237

.LBB0_285:
	s_or_b64 exec, exec, s[0:1]
	s_xor_b64 s[10:11], s[62:63], -1
	s_mul_i32 s0, s49, 0x2d000
	s_cmp_lg_u32 s57, -1
	v_writelane_b32 v254, s0, 29
	s_cselect_b32 s0, s57, 0
	s_cselect_b32 s1, s55, 0
	s_cmp_lg_u32 s58, -1
	s_waitcnt lgkmcnt(0)
	v_mov_b32_e32 v2, s0
	v_mov_b32_e32 v3, s1
	s_cselect_b32 s0, s58, 0
	s_cselect_b32 s1, s55, 0
	s_barrier
	ds_read_b32 v1, v2
	s_waitcnt vmcnt(0) lgkmcnt(0)
	v_mov_b32_e32 v2, s0
	v_mov_b32_e32 v3, s1
	ds_read_b32 v2, v2
	s_waitcnt vmcnt(0) lgkmcnt(0)
	s_add_i32 s0, 0, 0x23fc8
	s_cmp_lg_u32 s0, -1
	v_writelane_b32 v254, s0, 24
	s_cselect_b32 s0, s0, 0
	s_cselect_b32 s1, s55, 0
	v_mov_b32_e32 v3, s1
	s_waitcnt lgkmcnt(0)
	v_readfirstlane_b32 s8, v1
	v_readfirstlane_b32 s9, v2
	v_mov_b32_e32 v2, s0
	s_add_i32 s0, 0, 0x23fcc
	s_cmp_lg_u32 s0, -1
	ds_read_b32 v1, v2
	s_waitcnt vmcnt(0) lgkmcnt(0)
	v_writelane_b32 v254, s0, 25
	s_cselect_b32 s0, s0, 0
	s_cselect_b32 s1, s55, 0
	v_mov_b32_e32 v2, s0
	v_mov_b32_e32 v3, s1
	ds_read_b32 v2, v2
	s_waitcnt vmcnt(0) lgkmcnt(0)
	s_andn2_b64 vcc, exec, s[62:63]
	s_waitcnt lgkmcnt(0)
	v_readfirstlane_b32 s12, v1
	v_cndmask_b32_e64 v1, 0, 1, s[62:63]
	v_cmp_ne_u32_e64 s[0:1], 1, v1
	v_readfirstlane_b32 s13, v2
	s_nop 0
	v_writelane_b32 v254, s0, 30
	s_mov_b64 s[14:15], s[12:13]
	s_nop 0
	v_writelane_b32 v254, s1, 31
	s_cbranch_vccnz .LBB0_287
	v_readlane_b32 s0, v253, 0
	s_cmp_lg_u32 s0, -1
	s_cselect_b32 s0, s0, 0
	v_mov_b32_e32 v2, s0
	v_readlane_b32 s0, v253, 1
	s_cselect_b32 s1, s55, 0
	s_cmp_lg_u32 s0, -1
	v_mov_b32_e32 v3, s1
	s_cselect_b32 s0, s0, 0
	s_cselect_b32 s1, s55, 0
	ds_read_b32 v1, v2
	s_waitcnt vmcnt(0) lgkmcnt(0)
	v_mov_b32_e32 v2, s0
	v_mov_b32_e32 v3, s1
	ds_read_b32 v2, v2
	s_waitcnt vmcnt(0) lgkmcnt(0)
	v_readfirstlane_b32 s14, v1
	v_readfirstlane_b32 s15, v2
.LBB0_287:
	v_writelane_b32 v254, s62, 32
	s_nop 1
	v_writelane_b32 v254, s63, 33
	s_nop 0
	v_readlane_b32 s0, v254, 30
	v_readlane_b32 s1, v254, 31
	s_and_b64 vcc, exec, s[0:1]
	s_cbranch_vccnz .LBB0_289
	v_readlane_b32 s0, v253, 2
	s_cmp_lg_u32 s0, -1
	s_cselect_b32 s0, s0, 0
	v_mov_b32_e32 v2, s0
	v_readlane_b32 s0, v253, 3
	s_cselect_b32 s1, s55, 0
	s_cmp_lg_u32 s0, -1
	v_mov_b32_e32 v3, s1
	s_cselect_b32 s0, s0, 0
	s_cselect_b32 s1, s55, 0
	ds_read_b32 v1, v2
	s_waitcnt vmcnt(0) lgkmcnt(0)
	v_mov_b32_e32 v2, s0
	v_mov_b32_e32 v3, s1
	s_waitcnt lgkmcnt(0)
	ds_read_b32 v1, v2
	s_waitcnt vmcnt(0) lgkmcnt(0)
.LBB0_289:
	s_add_i32 s50, 0, 0x23f48
	s_cmp_lg_u32 s50, -1
	s_cselect_b32 s0, s50, 0
	s_cselect_b32 s1, s55, 0
	s_add_i32 s51, 0, 0x23f4c
	s_cmp_lg_u32 s51, -1
	v_mov_b32_e32 v2, s0
	v_mov_b32_e32 v3, s1
	s_cselect_b32 s0, s51, 0
	s_cselect_b32 s1, s55, 0
	s_waitcnt lgkmcnt(0)
	ds_read_b32 v1, v2
	s_waitcnt vmcnt(0) lgkmcnt(0)
	v_mov_b32_e32 v2, s0
	v_mov_b32_e32 v3, s1
	ds_read_b32 v2, v2
	s_waitcnt vmcnt(0) lgkmcnt(0)
	v_readlane_b32 s6, v253, 11
	v_readlane_b32 s7, v253, 12
	s_andn2_b64 vcc, exec, s[6:7]
	s_waitcnt lgkmcnt(0)
	v_readfirstlane_b32 s4, v1
	v_mov_b32_e32 v1, v224
	v_readfirstlane_b32 s5, v2
	v_cndmask_b32_e64 v2, 0, 1, s[6:7]
	v_readlane_b32 s6, v253, 13
	v_readlane_b32 s7, v253, 14
	v_cmp_ne_u32_e64 s[0:1], 1, v2
	v_readfirstlane_b32 s22, v1
	v_cndmask_b32_e64 v2, 0, 1, s[6:7]
	v_cmp_ne_u32_e64 s[6:7], 1, v2
	s_nop 1
	v_writelane_b32 v254, s6, 34
	s_nop 1
	v_writelane_b32 v254, s7, 35
	s_cbranch_vccnz .LBB0_292
	v_readlane_b32 s6, v254, 34
	v_readlane_b32 s7, v254, 35
	s_mov_b32 s70, 4
	s_and_b64 vcc, exec, s[6:7]
	v_readlane_b32 s68, v253, 15
	v_readlane_b32 s69, v253, 16
	v_readlane_b32 s6, v253, 17
	s_cbranch_vccnz .LBB0_292
	v_readlane_b32 s16, v253, 32
	s_mov_b32 s70, 44
	s_mov_b32 s6, 0
	s_mov_b32 s68, s16
	v_readlane_b32 s69, v253, 31
	v_readlane_b32 s17, v253, 33

.LBB0_413:
	s_cmp_lg_u32 s57, -1
	s_cselect_b32 s0, s57, 0
	s_cselect_b32 s1, s55, 0
	s_cmp_lg_u32 s58, -1
	v_mov_b32_e32 v2, s0
	s_waitcnt lgkmcnt(0)
	v_mov_b32_e32 v3, s1
	s_cselect_b32 s0, s58, 0
	s_cselect_b32 s1, s55, 0
	ds_read_b32 v1, v2
	s_waitcnt vmcnt(0) lgkmcnt(0)
	v_mov_b32_e32 v2, s0
	v_mov_b32_e32 v3, s1
	ds_read_b32 v2, v2
	s_waitcnt vmcnt(0) lgkmcnt(0)
	s_getreg_b32 s6, hwreg(HW_REG_XCC_ID, 0, 4)
	s_waitcnt vmcnt(0)
	s_waitcnt lgkmcnt(0)
	s_barrier
	v_readfirstlane_b32 s4, v1
	v_readfirstlane_b32 s5, v2
	s_and_saveexec_b64 s[0:1], s[78:79]
	s_cbranch_execz .LBB0_465
	v_readlane_b32 s7, v253, 59
	s_waitcnt vmcnt(0) expcnt(0) lgkmcnt(0)
	s_and_b32 s33, s6, 15
	v_mov_b32_e32 v1, s7
	ds_read_b32 v3, v1
	v_readlane_b32 s7, v253, 60
	s_waitcnt lgkmcnt(0)
	v_cmp_ne_u32_e32 vcc, 0, v3
	v_mov_b32_e32 v1, s7
	ds_read_b32 v2, v1
	s_cbranch_vccnz .LBB0_429
	s_add_u32 s6, s4, 0x3c0200
	s_addc_u32 s7, s5, 0
	s_add_u32 s8, s4, 0x3c0400
	s_addc_u32 s9, s5, 0
	s_add_u32 s12, s4, 0x3c0500
	s_addc_u32 s13, s5, 0
	s_add_u32 s14, s4, 0x3c0600
	s_addc_u32 s15, s5, 0
	s_add_u32 s16, s4, 0x3c0700
	s_addc_u32 s17, s5, 0
	s_add_u32 s18, s4, 0x3c0800
	s_addc_u32 s19, s5, 0
	s_add_u32 s20, s4, 0x3c0900
	s_addc_u32 s21, s5, 0
	s_add_u32 s22, s4, 0x3c0a00
	s_addc_u32 s23, s5, 0
	s_add_u32 s24, s4, 0x3c0b00
	s_addc_u32 s25, s5, 0
	s_add_u32 s26, s4, 0x3c0c00
	s_addc_u32 s27, s5, 0
	s_add_u32 s28, s4, 0x3c0d00
	s_addc_u32 s29, s5, 0
	s_add_u32 s30, s4, 0x3c0e00
	s_addc_u32 s31, s5, 0
	s_add_u32 s34, s4, 0x3c0f00
	s_addc_u32 s35, s5, 0
	s_add_u32 s36, s4, 0x3c1000
	s_addc_u32 s37, s5, 0
	s_add_u32 s38, s4, 0x3c1100
	s_addc_u32 s39, s5, 0
	s_add_u32 s40, s4, 0x3c1200
	s_addc_u32 s41, s5, 0
	s_add_u32 s42, s4, 0x3c1300
	s_addc_u32 s43, s5, 0
	s_mov_b32 s54, 1
	s_branch .LBB0_417

.LBB0_465:
	s_or_b64 exec, exec, s[0:1]
	s_mov_b64 s[0:1], -1
	s_and_b64 vcc, exec, s[10:11]
	s_waitcnt lgkmcnt(0)
	s_barrier
	s_cbranch_vccz .LBB0_467
	s_cmp_lg_u32 s57, -1
	s_cselect_b32 s0, s57, 0
	s_cselect_b32 s1, s55, 0
	s_cmp_lg_u32 s58, -1
	v_mov_b32_e32 v2, s0
	v_mov_b32_e32 v3, s1
	s_cselect_b32 s0, s58, 0
	s_cselect_b32 s1, s55, 0
	ds_read_b32 v1, v2
	s_waitcnt vmcnt(0) lgkmcnt(0)
	v_mov_b32_e32 v2, s0
	v_mov_b32_e32 v3, s1
	ds_read_b32 v2, v2
	s_waitcnt vmcnt(0) lgkmcnt(0)
	v_readfirstlane_b32 s0, v1
	s_add_u32 s6, s0, 0x400000
	v_readfirstlane_b32 s1, v2
	s_addc_u32 s7, s1, 0
	s_mov_b64 s[0:1], 0
.LBB0_467:
	s_andn2_b64 vcc, exec, s[0:1]
	s_cbranch_vccnz .LBB0_469
	v_readlane_b32 s0, v253, 2
	s_cmp_lg_u32 s0, -1
	s_cselect_b32 s0, s0, 0
	v_mov_b32_e32 v2, s0
	v_readlane_b32 s0, v253, 3
	s_cselect_b32 s1, s55, 0
	s_cmp_lg_u32 s0, -1
	v_mov_b32_e32 v3, s1
	s_cselect_b32 s0, s0, 0
	s_cselect_b32 s1, s55, 0
	ds_read_b32 v1, v2
	s_waitcnt vmcnt(0) lgkmcnt(0)
	v_mov_b32_e32 v2, s0
	v_mov_b32_e32 v3, s1
	ds_read_b32 v2, v2
	s_waitcnt vmcnt(0) lgkmcnt(0)
	v_readfirstlane_b32 s6, v1
	v_readfirstlane_b32 s7, v2
.LBB0_469:
	s_cmp_lg_u32 s50, -1
	s_cselect_b32 s0, s50, 0
	s_cselect_b32 s1, s55, 0
	s_cmp_lg_u32 s51, -1
	v_mov_b32_e32 v2, s0
	v_mov_b32_e32 v3, s1
	s_cselect_b32 s0, s51, 0
	s_cselect_b32 s1, s55, 0
	s_cmp_lg_u32 s57, -1
	ds_read_b32 v4, v2
	s_waitcnt vmcnt(0) lgkmcnt(0)
	v_mov_b32_e32 v2, s0
	v_mov_b32_e32 v3, s1
	s_cselect_b32 s0, s57, 0
	s_cselect_b32 s1, s55, 0
	s_cmp_lg_u32 s58, -1
	ds_read_b32 v5, v2
	s_waitcnt vmcnt(0) lgkmcnt(0)
	v_mov_b32_e32 v1, v224
	v_mov_b32_e32 v2, s0
	v_mov_b32_e32 v3, s1
	s_cselect_b32 s0, s58, 0
	s_cselect_b32 s1, s55, 0
	ds_read_b32 v7, v2
	s_waitcnt vmcnt(0) lgkmcnt(0)
	v_mov_b32_e32 v2, s0
	v_mov_b32_e32 v3, s1
	ds_read_b32 v2, v2
	s_waitcnt vmcnt(0) lgkmcnt(0)
	v_ashrrev_i32_e32 v3, 6, v1
	v_readlane_b32 s0, v253, 6
	s_movk_i32 s4, 0x400
	s_waitcnt lgkmcnt(0)
	v_readfirstlane_b32 s1, v5
	v_mul_lo_u32 v6, v3, s76
	v_add_u32_e32 v6, s75, v6
	v_readfirstlane_b32 s0, v4
	v_cmp_gt_i32_e32 vcc, s4, v6
	v_readfirstlane_b32 s8, v7
	v_readfirstlane_b32 s9, v2
	s_and_saveexec_b64 s[4:5], vcc
	s_cbranch_execz .LBB0_474
	v_and_b32_e32 v4, 63, v1
	v_and_b32_e32 v1, 64, v230
	v_add_u32_e32 v2, 64, v1
	v_xor_b32_e32 v1, 1, v230
	v_cmp_lt_i32_e32 vcc, v1, v2
	v_xor_b32_e32 v3, 2, v230
	v_readlane_b32 s12, v254, 36
	v_cndmask_b32_e32 v1, v230, v1, vcc
	v_cmp_lt_i32_e32 vcc, v3, v2
	v_readlane_b32 s13, v254, 37
	s_lshl_b64 s[12:13], s[12:13], 2
	v_cndmask_b32_e32 v3, v230, v3, vcc
	v_lshlrev_b32_e32 v68, 2, v3
	v_xor_b32_e32 v3, 4, v230
	v_cmp_lt_i32_e32 vcc, v3, v2
	s_add_u32 s12, s0, s12
	s_addc_u32 s13, s1, s13
	v_cndmask_b32_e32 v3, v230, v3, vcc
	v_lshlrev_b32_e32 v69, 2, v3
	v_xor_b32_e32 v3, 8, v230
	v_cmp_lt_i32_e32 vcc, v3, v2
	s_add_u32 s0, s8, s53
	s_addc_u32 s1, s9, 0
	v_cndmask_b32_e32 v3, v230, v3, vcc
	v_lshlrev_b32_e32 v70, 2, v3
	v_xor_b32_e32 v3, 16, v230
	s_add_u32 s14, s0, 0x24000
	v_cmp_lt_i32_e32 vcc, v3, v2
	s_addc_u32 s15, s1, 0
	s_add_u32 s0, s8, s52
	v_cndmask_b32_e32 v3, v230, v3, vcc
	v_lshlrev_b32_e32 v71, 2, v3
	v_xor_b32_e32 v3, 32, v230
	s_addc_u32 s1, s9, 0
	v_cmp_lt_i32_e32 vcc, v3, v2
	s_add_u32 s16, s0, 0x24000
	v_lshlrev_b32_e32 v8, 4, v4
	v_cndmask_b32_e32 v2, v230, v3, vcc
	s_addc_u32 s17, s1, 0
	v_lshlrev_b32_e32 v72, 2, v2
	v_or_b32_e32 v2, 0x400, v8
	v_mov_b32_e32 v3, v0
	v_lshl_add_u64 v[16:17], s[16:17], 0, v[2:3]
	v_lshl_add_u64 v[18:19], s[14:15], 0, v[2:3]
	v_or_b32_e32 v2, 0x800, v8
	v_lshl_add_u64 v[20:21], s[16:17], 0, v[2:3]
	v_lshl_add_u64 v[22:23], s[14:15], 0, v[2:3]
	v_or_b32_e32 v2, 0xc00, v8
	v_mov_b32_e32 v9, v0
	v_lshl_add_u64 v[24:25], s[16:17], 0, v[2:3]
	v_lshl_add_u64 v[26:27], s[14:15], 0, v[2:3]
	v_lshlrev_b32_e32 v2, 3, v4
	v_lshl_add_u64 v[12:13], s[12:13], 0, v[8:9]
	v_lshl_add_u64 v[2:3], s[8:9], 0, v[2:3]
	s_mov_b64 s[12:13], 0x5a00000
	v_lshl_add_u64 v[28:29], v[2:3], 0, s[12:13]
	v_readlane_b32 s12, v254, 28
	s_mul_hi_u32 s13, s12, 0x33000
	v_readlane_b32 s12, v254, 26
	s_add_u32 s12, s8, s12
	v_ashrrev_i32_e32 v7, 31, v6
	s_addc_u32 s13, s9, s13
	v_lshl_add_u64 v[2:3], v[6:7], 2, s[12:13]
	s_mov_b64 s[12:13], 0x1a1000
	v_lshl_add_u64 v[30:31], v[2:3], 0, s[12:13]
	v_lshlrev_b64 v[2:3], 12, v[6:7]
	v_lshlrev_b32_e32 v1, 2, v1
	v_cmp_eq_u32_e64 s[0:1], 0, v4
	v_lshl_add_u64 v[10:11], s[16:17], 0, v[8:9]
	v_lshl_add_u64 v[14:15], s[14:15], 0, v[8:9]
	v_lshl_add_u64 v[32:33], s[8:9], 0, v[2:3]
	v_lshl_add_u64 v[34:35], s[6:7], 0, v[2:3]
	s_mov_b64 s[6:7], 0
	s_branch .LBB0_472

.LBB0_474:
	s_or_b64 exec, exec, s[4:5]
	s_cmp_lg_u32 s57, -1
	s_cselect_b32 s0, s57, 0
	s_cselect_b32 s1, s55, 0
	s_cmp_lg_u32 s58, -1
	v_mov_b32_e32 v2, s0
	s_waitcnt lgkmcnt(0)
	v_mov_b32_e32 v3, s1
	s_cselect_b32 s0, s58, 0
	s_cselect_b32 s1, s55, 0
	ds_read_b32 v1, v2
	s_waitcnt vmcnt(0) lgkmcnt(0)
	v_mov_b32_e32 v2, s0
	v_mov_b32_e32 v3, s1
	ds_read_b32 v2, v2
	s_waitcnt vmcnt(0) lgkmcnt(0)
	s_getreg_b32 s6, hwreg(HW_REG_XCC_ID, 0, 4)
	s_waitcnt vmcnt(0)
	s_waitcnt lgkmcnt(0)
	s_barrier
	v_readfirstlane_b32 s4, v1
	v_readfirstlane_b32 s5, v2
	s_and_saveexec_b64 s[0:1], s[78:79]
	s_cbranch_execz .LBB0_526
	v_readlane_b32 s7, v253, 59
	s_waitcnt vmcnt(0) expcnt(0) lgkmcnt(0)
	s_and_b32 s33, s6, 15
	v_mov_b32_e32 v1, s7
	ds_read_b32 v3, v1
	v_readlane_b32 s7, v253, 60
	s_waitcnt lgkmcnt(0)
	v_cmp_ne_u32_e32 vcc, 0, v3
	v_mov_b32_e32 v1, s7
	ds_read_b32 v2, v1
	s_cbranch_vccnz .LBB0_490
	s_add_u32 s6, s4, 0x3c0200
	s_addc_u32 s7, s5, 0
	s_add_u32 s8, s4, 0x3c0400
	s_addc_u32 s9, s5, 0
	s_add_u32 s12, s4, 0x3c0500
	s_addc_u32 s13, s5, 0
	s_add_u32 s14, s4, 0x3c0600
	s_addc_u32 s15, s5, 0
	s_add_u32 s16, s4, 0x3c0700
	s_addc_u32 s17, s5, 0
	s_add_u32 s18, s4, 0x3c0800
	s_addc_u32 s19, s5, 0
	s_add_u32 s20, s4, 0x3c0900
	s_addc_u32 s21, s5, 0
	s_add_u32 s22, s4, 0x3c0a00
	s_addc_u32 s23, s5, 0
	s_add_u32 s24, s4, 0x3c0b00
	s_addc_u32 s25, s5, 0
	s_add_u32 s26, s4, 0x3c0c00
	s_addc_u32 s27, s5, 0
	s_add_u32 s28, s4, 0x3c0d00
	s_addc_u32 s29, s5, 0
	s_add_u32 s30, s4, 0x3c0e00
	s_addc_u32 s31, s5, 0
	s_add_u32 s34, s4, 0x3c0f00
	s_addc_u32 s35, s5, 0
	s_add_u32 s36, s4, 0x3c1000
	s_addc_u32 s37, s5, 0
	s_add_u32 s38, s4, 0x3c1100
	s_addc_u32 s39, s5, 0
	s_add_u32 s40, s4, 0x3c1200
	s_addc_u32 s41, s5, 0
	s_add_u32 s42, s4, 0x3c1300
	s_addc_u32 s43, s5, 0
	s_mov_b32 s52, 1
	s_branch .LBB0_478

.LBB0_526:
	s_or_b64 exec, exec, s[0:1]
	s_mov_b64 s[0:1], -1
	s_and_b64 vcc, exec, s[10:11]
	s_waitcnt lgkmcnt(0)
	s_barrier
	s_cbranch_vccz .LBB0_862
	s_add_i32 s0, 0, 0x23fa0
	s_cmp_lg_u32 s0, -1
	s_cselect_b32 s0, s0, 0
	s_cselect_b32 s1, s55, 0
	v_mov_b32_e32 v2, s0
	s_add_i32 s0, 0, 0x23fa4
	s_cmp_lg_u32 s0, -1
	v_mov_b32_e32 v10, v224
	v_mov_b32_e32 v3, s1
	s_cselect_b32 s0, s0, 0
	s_cselect_b32 s1, s55, 0
	ds_read_b32 v4, v2
	s_waitcnt vmcnt(0) lgkmcnt(0)
	v_mov_b32_e32 v2, s0
	v_mov_b32_e32 v3, s1
	ds_read_b32 v2, v2
	s_waitcnt vmcnt(0) lgkmcnt(0)
	v_and_b32_e32 v1, 15, v10
	s_movk_i32 s4, 0x1010
	v_mad_u32_u24 v18, v1, s4, 0
	v_ashrrev_i32_e32 v8, 4, v10
	s_movk_i32 s4, 0x4040
	v_mov_b32_e32 v3, v0
	s_movk_i32 s6, 0x4000
	v_add_u32_e32 v12, 0x200, v10
	v_add_u32_e32 v11, 0x400, v10
	v_add_u32_e32 v13, 0x600, v10
	s_cmp_lg_u32 s57, -1
	s_movk_i32 s7, 0x3000
	s_mov_b32 s8, 0
	s_waitcnt lgkmcnt(0)
	v_readfirstlane_b32 s0, v4
	v_readfirstlane_b32 s1, v2
	s_nop 1
	v_mov_b64_e32 v[4:5], s[0:1]
	v_mad_i64_i32 v[6:7], s[0:1], v8, s4, v[4:5]
	v_lshlrev_b32_e32 v2, 2, v1
	v_lshl_add_u64 v[6:7], v[6:7], 0, v[2:3]
	v_add_co_u32_e32 v6, vcc, s6, v6
	s_nop 1
	v_addc_co_u32_e32 v7, vcc, 0, v7, vcc
	global_load_dword v100, v[6:7], off
	v_lshl_add_u32 v7, v8, 2, v18
	v_mov_b32_e32 v99, v7
	v_ashrrev_i32_e32 v8, 4, v12
	v_mad_i64_i32 v[6:7], s[0:1], v8, s4, v[4:5]
	v_lshl_add_u64 v[6:7], v[6:7], 0, v[2:3]
	v_add_co_u32_e32 v6, vcc, s6, v6
	s_nop 1
	v_addc_co_u32_e32 v7, vcc, 0, v7, vcc
	global_load_dword v101, v[6:7], off
	v_lshl_add_u32 v7, v8, 2, v18
	v_ashrrev_i32_e32 v8, 4, v11
	v_ashrrev_i32_e32 v11, 10, v11
	v_mad_i64_i32 v[6:7], s[0:1], v8, s4, v[4:5]
	v_lshl_add_u64 v[6:7], v[6:7], 0, v[2:3]
	v_add_co_u32_e32 v6, vcc, s6, v6
	s_nop 1
	v_addc_co_u32_e32 v7, vcc, 0, v7, vcc
	global_load_dword v102, v[6:7], off
	v_lshl_add_u32 v7, v8, 2, v18
	v_ashrrev_i32_e32 v8, 4, v13
	v_mad_i64_i32 v[6:7], s[0:1], v8, s4, v[4:5]
	v_lshl_add_u64 v[6:7], v[6:7], 0, v[2:3]
	v_add_co_u32_e32 v6, vcc, s6, v6
	s_nop 1
	v_addc_co_u32_e32 v7, vcc, 0, v7, vcc
	global_load_dword v103, v[6:7], off
	v_lshl_add_u32 v7, v8, 2, v18
	v_add_u32_e32 v6, 0x800, v10
	v_ashrrev_i32_e32 v7, 4, v6
	v_mad_i64_i32 v[8:9], s[0:1], v7, s4, v[4:5]
	v_lshl_add_u64 v[8:9], v[8:9], 0, v[2:3]
	v_add_co_u32_e32 v8, vcc, s6, v8
	v_lshl_add_u32 v7, v7, 2, v18
	s_nop 0
	v_addc_co_u32_e32 v9, vcc, 0, v9, vcc
	global_load_dword v104, v[8:9], off
	v_ashrrev_i32_e32 v6, 10, v6
	v_add_u32_e32 v8, 0xa00, v10
	v_ashrrev_i32_e32 v7, 4, v8
	v_mad_i64_i32 v[14:15], s[0:1], v7, s4, v[4:5]
	v_lshl_add_u64 v[14:15], v[14:15], 0, v[2:3]
	v_add_co_u32_e32 v14, vcc, s6, v14
	v_lshl_add_u32 v7, v7, 2, v18
	s_nop 0
	v_addc_co_u32_e32 v15, vcc, 0, v15, vcc
	global_load_dword v105, v[14:15], off
	v_add_u32_e32 v7, 0xc00, v10
	v_ashrrev_i32_e32 v9, 4, v7
	v_mad_i64_i32 v[14:15], s[0:1], v9, s4, v[4:5]
	v_lshl_add_u64 v[14:15], v[14:15], 0, v[2:3]
	v_add_co_u32_e32 v14, vcc, s6, v14
	v_lshl_add_u32 v9, v9, 2, v18
	s_nop 0
	v_addc_co_u32_e32 v15, vcc, 0, v15, vcc
	global_load_dword v106, v[14:15], off
	v_add_u32_e32 v9, 0xe00, v10
	v_ashrrev_i32_e32 v16, 4, v9
	v_mad_i64_i32 v[14:15], s[0:1], v16, s4, v[4:5]
	v_lshl_add_u64 v[14:15], v[14:15], 0, v[2:3]
	v_add_co_u32_e32 v14, vcc, s6, v14
	s_nop 1
	v_addc_co_u32_e32 v15, vcc, 0, v15, vcc
	global_load_dword v107, v[14:15], off
	v_lshl_add_u32 v15, v16, 2, v18
	v_add_u32_e32 v15, 0x1000, v10
	v_ashrrev_i32_e32 v14, 4, v15
	v_mad_i64_i32 v[16:17], s[0:1], v14, s4, v[4:5]
	v_lshl_add_u64 v[16:17], v[16:17], 0, v[2:3]
	v_add_co_u32_e32 v16, vcc, s6, v16
	v_lshl_add_u32 v14, v14, 2, v18
	s_nop 0
	v_addc_co_u32_e32 v17, vcc, 0, v17, vcc
	global_load_dword v108, v[16:17], off
	v_add_u32_e32 v14, 0x1200, v10
	v_ashrrev_i32_e32 v19, 4, v14
	v_mad_i64_i32 v[16:17], s[0:1], v19, s4, v[4:5]
	v_lshl_add_u64 v[16:17], v[16:17], 0, v[2:3]
	v_add_co_u32_e32 v16, vcc, s6, v16
	s_nop 1
	v_addc_co_u32_e32 v17, vcc, 0, v17, vcc
	global_load_dword v109, v[16:17], off
	v_lshl_add_u32 v17, v19, 2, v18
	v_add_u32_e32 v16, 0x1400, v10
	v_ashrrev_i32_e32 v19, 4, v16
	v_mad_i64_i32 v[16:17], s[0:1], v19, s4, v[4:5]
	v_lshl_add_u64 v[16:17], v[16:17], 0, v[2:3]
	v_add_co_u32_e32 v16, vcc, s6, v16
	s_nop 1
	v_addc_co_u32_e32 v17, vcc, 0, v17, vcc
	global_load_dword v110, v[16:17], off
	v_lshl_add_u32 v17, v19, 2, v18
	v_add_u32_e32 v16, 0x1600, v10
	v_ashrrev_i32_e32 v19, 4, v16
	v_mad_i64_i32 v[16:17], s[0:1], v19, s4, v[4:5]
	v_lshl_add_u64 v[16:17], v[16:17], 0, v[2:3]
	v_add_co_u32_e32 v16, vcc, s6, v16
	s_nop 1
	v_addc_co_u32_e32 v17, vcc, 0, v17, vcc
	global_load_dword v111, v[16:17], off
	v_lshl_add_u32 v17, v19, 2, v18
	v_add_u32_e32 v16, 0x1800, v10
	v_ashrrev_i32_e32 v19, 4, v16
	v_mad_i64_i32 v[16:17], s[0:1], v19, s4, v[4:5]
	v_lshl_add_u64 v[16:17], v[16:17], 0, v[2:3]
	v_add_co_u32_e32 v16, vcc, s6, v16
	s_nop 1
	v_addc_co_u32_e32 v17, vcc, 0, v17, vcc
	global_load_dword v112, v[16:17], off
	v_lshl_add_u32 v17, v19, 2, v18
	v_add_u32_e32 v16, 0x1a00, v10
	v_ashrrev_i32_e32 v19, 4, v16
	v_mad_i64_i32 v[16:17], s[0:1], v19, s4, v[4:5]
	v_lshl_add_u64 v[16:17], v[16:17], 0, v[2:3]
	v_add_co_u32_e32 v16, vcc, s6, v16
	s_nop 1
	v_addc_co_u32_e32 v17, vcc, 0, v17, vcc
	global_load_dword v113, v[16:17], off
	v_lshl_add_u32 v17, v19, 2, v18
	v_add_u32_e32 v16, 0x1c00, v10
	v_ashrrev_i32_e32 v19, 4, v16
	v_mad_i64_i32 v[16:17], s[0:1], v19, s4, v[4:5]
	v_lshl_add_u64 v[16:17], v[16:17], 0, v[2:3]
	v_add_co_u32_e32 v16, vcc, s6, v16
	s_nop 1
	v_addc_co_u32_e32 v17, vcc, 0, v17, vcc
	global_load_dword v114, v[16:17], off
	v_lshl_add_u32 v17, v19, 2, v18
	v_add_u32_e32 v16, 0x1e00, v10
	v_ashrrev_i32_e32 v19, 4, v16
	v_mad_i64_i32 v[16:17], s[0:1], v19, s4, v[4:5]
	v_lshl_add_u64 v[16:17], v[16:17], 0, v[2:3]
	v_add_co_u32_e32 v16, vcc, s6, v16
	s_nop 1
	v_addc_co_u32_e32 v17, vcc, 0, v17, vcc
	global_load_dword v115, v[16:17], off
	v_lshl_add_u32 v17, v19, 2, v18
	v_add_u32_e32 v16, 0x2000, v10
	v_ashrrev_i32_e32 v19, 4, v16
	v_mad_i64_i32 v[16:17], s[0:1], v19, s4, v[4:5]
	v_lshl_add_u64 v[16:17], v[16:17], 0, v[2:3]
	v_add_co_u32_e32 v16, vcc, s6, v16
	s_nop 1
	v_addc_co_u32_e32 v17, vcc, 0, v17, vcc
	global_load_dword v116, v[16:17], off
	v_lshl_add_u32 v17, v19, 2, v18
	v_add_u32_e32 v16, 0x2200, v10
	v_ashrrev_i32_e32 v19, 4, v16
	v_mad_i64_i32 v[16:17], s[0:1], v19, s4, v[4:5]
	v_lshl_add_u64 v[16:17], v[16:17], 0, v[2:3]
	v_add_co_u32_e32 v16, vcc, s6, v16
	s_nop 1
	v_addc_co_u32_e32 v17, vcc, 0, v17, vcc
	global_load_dword v117, v[16:17], off
	v_lshl_add_u32 v17, v19, 2, v18
	v_add_u32_e32 v16, 0x2400, v10
	v_ashrrev_i32_e32 v19, 4, v16
	v_mad_i64_i32 v[16:17], s[0:1], v19, s4, v[4:5]
	v_lshl_add_u64 v[16:17], v[16:17], 0, v[2:3]
	v_add_co_u32_e32 v16, vcc, s6, v16
	s_nop 1
	v_addc_co_u32_e32 v17, vcc, 0, v17, vcc
	global_load_dword v118, v[16:17], off
	v_lshl_add_u32 v17, v19, 2, v18
	v_add_u32_e32 v16, 0x2600, v10
	v_ashrrev_i32_e32 v19, 4, v16
	v_mad_i64_i32 v[16:17], s[0:1], v19, s4, v[4:5]
	v_lshl_add_u64 v[16:17], v[16:17], 0, v[2:3]
	v_add_co_u32_e32 v16, vcc, s6, v16
	s_nop 1
	v_addc_co_u32_e32 v17, vcc, 0, v17, vcc
	global_load_dword v119, v[16:17], off
	v_lshl_add_u32 v17, v19, 2, v18
	v_add_u32_e32 v16, 0x2800, v10
	v_ashrrev_i32_e32 v19, 4, v16
	v_mad_i64_i32 v[16:17], s[0:1], v19, s4, v[4:5]
	v_lshl_add_u64 v[16:17], v[16:17], 0, v[2:3]
	v_add_co_u32_e32 v16, vcc, s6, v16
	s_nop 1
	v_addc_co_u32_e32 v17, vcc, 0, v17, vcc
	global_load_dword v120, v[16:17], off
	v_lshl_add_u32 v17, v19, 2, v18
	v_add_u32_e32 v16, 0x2a00, v10
	v_ashrrev_i32_e32 v19, 4, v16
	v_mad_i64_i32 v[16:17], s[0:1], v19, s4, v[4:5]
	v_lshl_add_u64 v[16:17], v[16:17], 0, v[2:3]
	v_add_co_u32_e32 v16, vcc, s6, v16
	s_nop 1
	v_addc_co_u32_e32 v17, vcc, 0, v17, vcc
	global_load_dword v121, v[16:17], off
	v_lshl_add_u32 v17, v19, 2, v18
	v_add_u32_e32 v16, 0x2c00, v10
	v_ashrrev_i32_e32 v19, 4, v16
	v_mad_i64_i32 v[16:17], s[0:1], v19, s4, v[4:5]
	v_lshl_add_u64 v[16:17], v[16:17], 0, v[2:3]
	v_add_co_u32_e32 v16, vcc, s6, v16
	s_nop 1
	v_addc_co_u32_e32 v17, vcc, 0, v17, vcc
	global_load_dword v122, v[16:17], off
	v_lshl_add_u32 v17, v19, 2, v18
	v_add_u32_e32 v16, 0x2e00, v10
	v_ashrrev_i32_e32 v19, 4, v16
	v_mad_i64_i32 v[16:17], s[0:1], v19, s4, v[4:5]
	v_lshl_add_u64 v[16:17], v[16:17], 0, v[2:3]
	v_add_co_u32_e32 v16, vcc, s6, v16
	s_nop 1
	v_addc_co_u32_e32 v17, vcc, 0, v17, vcc
	global_load_dword v123, v[16:17], off
	v_lshl_add_u32 v17, v19, 2, v18
	v_add_u32_e32 v16, 0x3000, v10
	v_ashrrev_i32_e32 v19, 4, v16
	v_mad_i64_i32 v[16:17], s[0:1], v19, s4, v[4:5]
	v_lshl_add_u64 v[16:17], v[16:17], 0, v[2:3]
	v_add_co_u32_e32 v16, vcc, s6, v16
	s_nop 1
	v_addc_co_u32_e32 v17, vcc, 0, v17, vcc
	global_load_dword v124, v[16:17], off
	v_lshl_add_u32 v17, v19, 2, v18
	v_add_u32_e32 v16, 0x3200, v10
	v_ashrrev_i32_e32 v19, 4, v16
	v_mad_i64_i32 v[16:17], s[0:1], v19, s4, v[4:5]
	v_lshl_add_u64 v[16:17], v[16:17], 0, v[2:3]
	v_add_co_u32_e32 v16, vcc, s6, v16
	s_nop 1
	v_addc_co_u32_e32 v17, vcc, 0, v17, vcc
	global_load_dword v125, v[16:17], off
	v_lshl_add_u32 v17, v19, 2, v18
	v_add_u32_e32 v16, 0x3400, v10
	v_ashrrev_i32_e32 v19, 4, v16
	v_mad_i64_i32 v[16:17], s[0:1], v19, s4, v[4:5]
	v_lshl_add_u64 v[16:17], v[16:17], 0, v[2:3]
	v_add_co_u32_e32 v16, vcc, s6, v16
	s_nop 1
	v_addc_co_u32_e32 v17, vcc, 0, v17, vcc
	global_load_dword v126, v[16:17], off
	v_lshl_add_u32 v17, v19, 2, v18
	v_add_u32_e32 v16, 0x3600, v10
	v_ashrrev_i32_e32 v19, 4, v16
	v_mad_i64_i32 v[16:17], s[0:1], v19, s4, v[4:5]
	v_lshl_add_u64 v[16:17], v[16:17], 0, v[2:3]
	v_add_co_u32_e32 v16, vcc, s6, v16
	s_nop 1
	v_addc_co_u32_e32 v17, vcc, 0, v17, vcc
	global_load_dword v127, v[16:17], off
	v_lshl_add_u32 v17, v19, 2, v18
	v_add_u32_e32 v16, 0x3800, v10
	v_ashrrev_i32_e32 v19, 4, v16
	v_mad_i64_i32 v[16:17], s[0:1], v19, s4, v[4:5]
	v_lshl_add_u64 v[16:17], v[16:17], 0, v[2:3]
	v_add_co_u32_e32 v16, vcc, s6, v16
	s_nop 1
	v_addc_co_u32_e32 v17, vcc, 0, v17, vcc
	global_load_dword v128, v[16:17], off
	v_lshl_add_u32 v17, v19, 2, v18
	v_add_u32_e32 v16, 0x3a00, v10
	v_ashrrev_i32_e32 v19, 4, v16
	v_mad_i64_i32 v[16:17], s[0:1], v19, s4, v[4:5]
	v_lshl_add_u64 v[16:17], v[16:17], 0, v[2:3]
	v_add_co_u32_e32 v16, vcc, s6, v16
	s_nop 1
	v_addc_co_u32_e32 v17, vcc, 0, v17, vcc
	global_load_dword v129, v[16:17], off
	v_lshl_add_u32 v17, v19, 2, v18
	v_add_u32_e32 v16, 0x3c00, v10
	v_ashrrev_i32_e32 v19, 4, v16
	v_mad_i64_i32 v[16:17], s[0:1], v19, s4, v[4:5]
	v_lshl_add_u64 v[16:17], v[16:17], 0, v[2:3]
	v_add_co_u32_e32 v16, vcc, s6, v16
	s_nop 1
	v_addc_co_u32_e32 v17, vcc, 0, v17, vcc
	global_load_dword v130, v[16:17], off
	v_lshl_add_u32 v17, v19, 2, v18
	v_add_u32_e32 v16, 0x3e00, v10
	v_ashrrev_i32_e32 v16, 4, v16
	v_mad_i64_i32 v[4:5], s[0:1], v16, s4, v[4:5]
	v_lshl_add_u64 v[4:5], v[4:5], 0, v[2:3]
	v_add_co_u32_e32 v4, vcc, s6, v4
	s_cselect_b32 s0, s57, 0
	s_nop 0
	v_addc_co_u32_e32 v5, vcc, 0, v5, vcc
	global_load_dword v131, v[4:5], off
	v_lshl_add_u32 v4, v16, 2, v18
	s_cselect_b32 s1, s55, 0
	s_cmp_lg_u32 s58, -1
	v_mov_b32_e32 v5, s1
	s_cselect_b32 s1, s55, 0
	s_waitcnt vmcnt(31)
	ds_write_b32 v99, v100
	s_waitcnt vmcnt(30)
	ds_write_b32 v99, v101 offset:128
	s_waitcnt vmcnt(29)
	ds_write_b32 v99, v102 offset:256
	s_waitcnt vmcnt(28)
	ds_write_b32 v99, v103 offset:384
	s_waitcnt vmcnt(27)
	ds_write_b32 v99, v104 offset:512
	s_waitcnt vmcnt(26)
	ds_write_b32 v99, v105 offset:640
	s_waitcnt vmcnt(25)
	ds_write_b32 v99, v106 offset:768
	s_waitcnt vmcnt(24)
	ds_write_b32 v99, v107 offset:896
	s_waitcnt vmcnt(23)
	ds_write_b32 v99, v108 offset:1024
	s_waitcnt vmcnt(22)
	ds_write_b32 v99, v109 offset:1152
	s_waitcnt vmcnt(21)
	ds_write_b32 v99, v110 offset:1280
	s_waitcnt vmcnt(20)
	ds_write_b32 v99, v111 offset:1408
	s_waitcnt vmcnt(19)
	ds_write_b32 v99, v112 offset:1536
	s_waitcnt vmcnt(18)
	ds_write_b32 v99, v113 offset:1664
	s_waitcnt vmcnt(17)
	ds_write_b32 v99, v114 offset:1792
	s_waitcnt vmcnt(16)
	ds_write_b32 v99, v115 offset:1920
	s_waitcnt vmcnt(15)
	ds_write_b32 v99, v116 offset:2048
	s_waitcnt vmcnt(14)
	ds_write_b32 v99, v117 offset:2176
	s_waitcnt vmcnt(13)
	ds_write_b32 v99, v118 offset:2304
	s_waitcnt vmcnt(12)
	ds_write_b32 v99, v119 offset:2432
	s_waitcnt vmcnt(11)
	ds_write_b32 v99, v120 offset:2560
	s_waitcnt vmcnt(10)
	ds_write_b32 v99, v121 offset:2688
	s_waitcnt vmcnt(9)
	ds_write_b32 v99, v122 offset:2816
	s_waitcnt vmcnt(8)
	ds_write_b32 v99, v123 offset:2944
	s_waitcnt vmcnt(7)
	ds_write_b32 v99, v124 offset:3072
	s_waitcnt vmcnt(6)
	ds_write_b32 v99, v125 offset:3200
	s_waitcnt vmcnt(5)
	ds_write_b32 v99, v126 offset:3328
	s_waitcnt vmcnt(4)
	ds_write_b32 v99, v127 offset:3456
	s_waitcnt vmcnt(3)
	ds_write_b32 v99, v128 offset:3584
	s_waitcnt vmcnt(2)
	ds_write_b32 v99, v129 offset:3712
	s_waitcnt vmcnt(1)
	ds_write_b32 v99, v130 offset:3840
	s_waitcnt vmcnt(0)
	ds_write_b32 v99, v131 offset:3968
	v_mov_b32_e32 v4, s0
	s_cselect_b32 s0, s58, 0
	ds_read_b32 v3, v4
	s_waitcnt vmcnt(0) lgkmcnt(0)
	v_mov_b32_e32 v4, s0
	v_mov_b32_e32 v5, s1
	ds_read_b32 v4, v4
	s_waitcnt vmcnt(0) lgkmcnt(0)
	v_readfirstlane_b32 s0, v3
	s_add_u32 s0, s0, 0x2d000
	v_readfirstlane_b32 s1, v4
	s_addc_u32 s1, s1, 0
	s_cmp_lg_u32 s50, -1
	s_cselect_b32 s4, s50, 0
	s_cselect_b32 s5, s55, 0
	s_cmp_lg_u32 s51, -1
	v_mov_b32_e32 v4, s4
	v_mov_b32_e32 v5, s5
	s_cselect_b32 s4, s51, 0
	s_cselect_b32 s5, s55, 0
	ds_read_b32 v3, v4
	s_waitcnt vmcnt(0) lgkmcnt(0)
	v_mov_b32_e32 v4, s4
	v_mov_b32_e32 v5, s5
	ds_read_b32 v4, v4
	s_waitcnt vmcnt(0) lgkmcnt(0)
	v_mov_b32_e32 v5, v0
	s_waitcnt lgkmcnt(0)
	v_readfirstlane_b32 s4, v3
	v_ashrrev_i32_e32 v3, 10, v10
	v_mul_hi_i32_i24_e32 v17, 0x9000, v3
	v_readfirstlane_b32 s5, v4
	v_and_b32_e32 v4, 0x3ff, v10
	v_mul_i32_i24_e32 v16, 0x9000, v3
	v_lshlrev_b32_e32 v4, 2, v4
	v_lshl_add_u64 v[16:17], s[0:1], 0, v[16:17]
	v_lshl_add_u64 v[16:17], v[16:17], 0, v[4:5]
	v_add_co_u32_e32 v20, vcc, s6, v16
	s_add_u32 s4, s4, 0x1000
	s_nop 0
	v_addc_co_u32_e32 v21, vcc, 0, v17, vcc
	v_add_co_u32_e32 v16, vcc, s7, v16
	global_load_dword v3, v[20:21], off
	s_nop 0
	v_addc_co_u32_e32 v17, vcc, 0, v17, vcc
	global_load_dword v24, v[16:17], off
	v_ashrrev_i32_e32 v20, 10, v12
	v_and_b32_e32 v12, 0x3ff, v12
	v_mul_hi_i32_i24_e32 v21, 0x9000, v20
	v_mul_i32_i24_e32 v20, 0x9000, v20
	s_addc_u32 s5, s5, 0
	v_lshlrev_b32_e32 v16, 2, v12
	v_mov_b32_e32 v17, v0
	v_lshl_add_u64 v[20:21], s[0:1], 0, v[20:21]
	global_load_dword v19, v4, s[4:5]
	global_load_dword v12, v16, s[4:5]
	v_lshl_add_u64 v[16:17], v[20:21], 0, v[16:17]
	v_add_co_u32_e32 v20, vcc, s6, v16
	s_waitcnt vmcnt(3)
	v_add_f32_e32 v3, 1.0, v3
	v_addc_co_u32_e32 v21, vcc, 0, v17, vcc
	global_load_dword v20, v[20:21], off
	v_add_co_u32_e32 v16, vcc, s7, v16
	s_waitcnt vmcnt(2)
	v_mul_f32_e32 v22, v19, v3
	v_lshl_add_u32 v3, v10, 2, 0
	v_add_u32_e32 v23, 0x10200, v3
	v_addc_co_u32_e32 v17, vcc, 0, v17, vcc
	v_add_u32_e32 v3, 0x15200, v3
	s_waitcnt vmcnt(0)
	v_add_f32_e32 v20, 1.0, v20
	v_mul_f32_e32 v12, v12, v20
	ds_write2st64_b32 v23, v22, v12 offset1:8
	global_load_dword v12, v[16:17], off
	v_mul_hi_i32_i24_e32 v17, 0x9000, v11
	v_mul_i32_i24_e32 v16, 0x9000, v11
	v_lshl_add_u64 v[16:17], s[0:1], 0, v[16:17]
	v_lshl_add_u64 v[16:17], v[16:17], 0, v[4:5]
	v_add_co_u32_e32 v20, vcc, s6, v16
	s_waitcnt vmcnt(0)
	ds_write2st64_b32 v3, v24, v12 offset1:8
	v_addc_co_u32_e32 v21, vcc, 0, v17, vcc
	v_add_co_u32_e32 v16, vcc, s7, v16
	global_load_dword v11, v[20:21], off
	s_nop 0
	v_addc_co_u32_e32 v17, vcc, 0, v17, vcc
	global_load_dword v20, v[16:17], off
	v_ashrrev_i32_e32 v16, 10, v13
	v_and_b32_e32 v12, 0x3ff, v13
	v_mul_hi_i32_i24_e32 v17, 0x9000, v16
	v_mul_i32_i24_e32 v16, 0x9000, v16
	v_lshlrev_b32_e32 v12, 2, v12
	v_mov_b32_e32 v13, v0
	v_lshl_add_u64 v[16:17], s[0:1], 0, v[16:17]
	global_load_dword v21, v12, s[4:5]
	v_lshl_add_u64 v[12:13], v[16:17], 0, v[12:13]
	v_add_co_u32_e32 v16, vcc, s6, v12
	s_waitcnt vmcnt(2)
	v_add_f32_e32 v11, 1.0, v11
	v_addc_co_u32_e32 v17, vcc, 0, v13, vcc
	global_load_dword v16, v[16:17], off
	v_add_co_u32_e32 v12, vcc, s7, v12
	v_mul_f32_e32 v11, v19, v11
	s_nop 0
	v_addc_co_u32_e32 v13, vcc, 0, v13, vcc
	s_waitcnt vmcnt(0)
	v_add_f32_e32 v16, 1.0, v16
	v_mul_f32_e32 v16, v21, v16
	ds_write2st64_b32 v23, v11, v16 offset0:16 offset1:24
	global_load_dword v11, v[12:13], off
	v_mul_hi_i32_i24_e32 v13, 0x9000, v6
	v_mul_i32_i24_e32 v12, 0x9000, v6
	v_lshl_add_u64 v[12:13], s[0:1], 0, v[12:13]
	v_lshl_add_u64 v[12:13], v[12:13], 0, v[4:5]
	v_add_co_u32_e32 v16, vcc, s6, v12
	s_waitcnt vmcnt(0)
	ds_write2st64_b32 v3, v20, v11 offset0:16 offset1:24
	v_addc_co_u32_e32 v17, vcc, 0, v13, vcc
	v_add_co_u32_e32 v12, vcc, s7, v12
	global_load_dword v6, v[16:17], off
	s_nop 0
	v_addc_co_u32_e32 v13, vcc, 0, v13, vcc
	global_load_dword v11, v[12:13], off
	v_ashrrev_i32_e32 v16, 10, v8
	v_and_b32_e32 v8, 0x3ff, v8
	v_mul_hi_i32_i24_e32 v17, 0x9000, v16
	v_mul_i32_i24_e32 v16, 0x9000, v16
	v_lshlrev_b32_e32 v12, 2, v8
	v_mov_b32_e32 v13, v0
	v_lshl_add_u64 v[16:17], s[0:1], 0, v[16:17]
	global_load_dword v8, v12, s[4:5]
	v_lshl_add_u64 v[12:13], v[16:17], 0, v[12:13]
	v_add_co_u32_e32 v16, vcc, s6, v12
	s_waitcnt vmcnt(2)
	v_add_f32_e32 v6, 1.0, v6
	v_addc_co_u32_e32 v17, vcc, 0, v13, vcc
	global_load_dword v16, v[16:17], off
	v_add_co_u32_e32 v12, vcc, s7, v12
	v_mul_f32_e32 v6, v19, v6
	s_nop 0
	v_addc_co_u32_e32 v13, vcc, 0, v13, vcc
	s_waitcnt vmcnt(0)
	v_add_f32_e32 v16, 1.0, v16
	v_mul_f32_e32 v8, v8, v16
	ds_write2st64_b32 v23, v6, v8 offset0:32 offset1:40
	global_load_dword v6, v[12:13], off
	s_waitcnt vmcnt(0)
	ds_write2st64_b32 v3, v11, v6 offset0:32 offset1:40
	v_ashrrev_i32_e32 v6, 10, v7
	v_mul_hi_i32_i24_e32 v7, 0x9000, v6
	v_mul_i32_i24_e32 v6, 0x9000, v6
	v_lshl_add_u64 v[6:7], s[0:1], 0, v[6:7]
	v_lshl_add_u64 v[6:7], v[6:7], 0, v[4:5]
	v_add_co_u32_e32 v12, vcc, s6, v6
	s_nop 1
	v_addc_co_u32_e32 v13, vcc, 0, v7, vcc
	global_load_dword v8, v[12:13], off
	v_add_co_u32_e32 v6, vcc, s7, v6
	s_waitcnt vmcnt(0)
	v_add_f32_e32 v8, 1.0, v8
	v_mul_f32_e32 v11, v19, v8
	v_addc_co_u32_e32 v7, vcc, 0, v7, vcc
	v_ashrrev_i32_e32 v8, 10, v9
	global_load_dword v12, v[6:7], off
	v_and_b32_e32 v6, 0x3ff, v9
	v_mul_hi_i32_i24_e32 v9, 0x9000, v8
	v_mul_i32_i24_e32 v8, 0x9000, v8
	v_lshlrev_b32_e32 v6, 2, v6
	v_mov_b32_e32 v7, v0
	v_lshl_add_u64 v[8:9], s[0:1], 0, v[8:9]
	global_load_dword v13, v6, s[4:5]
	v_lshl_add_u64 v[6:7], v[8:9], 0, v[6:7]
	v_add_co_u32_e32 v8, vcc, s6, v6
	s_nop 1
	v_addc_co_u32_e32 v9, vcc, 0, v7, vcc
	v_add_co_u32_e32 v6, vcc, s7, v6
	global_load_dword v8, v[8:9], off
	s_nop 0
	v_addc_co_u32_e32 v7, vcc, 0, v7, vcc
	global_load_dword v6, v[6:7], off
	s_waitcnt vmcnt(1)
	v_add_f32_e32 v8, 1.0, v8
	v_mul_f32_e32 v8, v13, v8
	ds_write2st64_b32 v23, v11, v8 offset0:48 offset1:56
	s_waitcnt vmcnt(0)
	ds_write2st64_b32 v3, v12, v6 offset0:48 offset1:56
	v_ashrrev_i32_e32 v6, 10, v15
	v_mul_hi_i32_i24_e32 v7, 0x9000, v6
	v_mul_i32_i24_e32 v6, 0x9000, v6
	v_lshl_add_u64 v[6:7], s[0:1], 0, v[6:7]
	v_lshl_add_u64 v[4:5], v[6:7], 0, v[4:5]
	v_add_co_u32_e32 v6, vcc, s6, v4
	s_nop 1
	v_addc_co_u32_e32 v7, vcc, 0, v5, vcc
	global_load_dword v6, v[6:7], off
	v_add_co_u32_e32 v4, vcc, s7, v4
	s_nop 1
	v_addc_co_u32_e32 v5, vcc, 0, v5, vcc
	global_load_dword v9, v[4:5], off
	v_and_b32_e32 v4, 0x3ff, v14
	v_lshlrev_b32_e32 v4, 2, v4
	v_mov_b32_e32 v5, v0
	global_load_dword v11, v4, s[4:5]
	s_waitcnt vmcnt(2)
	v_add_f32_e32 v6, 1.0, v6
	v_mul_f32_e32 v8, v19, v6
	v_ashrrev_i32_e32 v6, 10, v14
	v_mul_hi_i32_i24_e32 v7, 0x9000, v6
	v_mul_i32_i24_e32 v6, 0x9000, v6
	v_lshl_add_u64 v[6:7], s[0:1], 0, v[6:7]
	v_lshl_add_u64 v[4:5], v[6:7], 0, v[4:5]
	v_add_co_u32_e32 v6, vcc, s6, v4
	v_readlane_b32 s0, v253, 18
	s_nop 0
	v_addc_co_u32_e32 v7, vcc, 0, v5, vcc
	global_load_dword v6, v[6:7], off
	v_add_co_u32_e32 v4, vcc, 0x3000, v4
	v_readlane_b32 s1, v253, 19
	s_nop 0
	v_addc_co_u32_e32 v5, vcc, 0, v5, vcc
	global_load_dword v4, v[4:5], off
	s_andn2_b64 vcc, exec, s[0:1]
	s_waitcnt vmcnt(1)
	v_add_f32_e32 v6, 1.0, v6
	v_mul_f32_e32 v6, v11, v6
	ds_write2st64_b32 v23, v8, v6 offset0:64 offset1:72
	s_waitcnt vmcnt(0)
	ds_write2st64_b32 v3, v9, v4 offset0:64 offset1:72
	s_waitcnt lgkmcnt(0)
	s_barrier
	s_cbranch_vccnz .LBB0_529
	v_readlane_b32 s8, v253, 56
.LBB0_529:
	s_sub_i32 s0, s75, s8
	v_ashrrev_i32_e32 v3, 6, v10
	s_cmp_lg_u32 s57, -1
	v_lshl_add_u32 v19, s0, 3, v3
	s_cselect_b32 s0, s57, 0
	s_cselect_b32 s1, s55, 0
	s_cmp_lg_u32 s58, -1
	v_mov_b64_e32 v[4:5], s[0:1]
	s_cselect_b32 s0, s58, 0
	s_cselect_b32 s1, s55, 0
	v_mov_b64_e32 v[6:7], s[0:1]
	ds_read_b32 v3, v4
	s_waitcnt vmcnt(0) lgkmcnt(0)
	ds_read_b32 v3, v6
	s_waitcnt vmcnt(0) lgkmcnt(0)
	ds_read_b32 v3, v4
	s_waitcnt vmcnt(0) lgkmcnt(0)
	ds_read_b32 v8, v6
	s_waitcnt vmcnt(0) lgkmcnt(0)
	v_readlane_b32 s4, v254, 24
	s_cmp_lg_u32 s4, -1
	s_cselect_b32 s4, s4, 0
	s_cselect_b32 s5, s55, 0
	v_mov_b32_e32 v9, s5
	s_waitcnt lgkmcnt(0)
	v_readfirstlane_b32 s9, v3
	v_readfirstlane_b32 s10, v8
	ds_read_b32 v3, v4
	s_waitcnt vmcnt(0) lgkmcnt(0)
	ds_read_b32 v8, v6
	s_waitcnt vmcnt(0) lgkmcnt(0)
	v_readfirstlane_b32 s0, v3
	v_readfirstlane_b32 s1, v8
	v_mov_b32_e32 v8, s4
	ds_read_b32 v3, v8
	s_waitcnt vmcnt(0) lgkmcnt(0)
	v_readlane_b32 s4, v254, 25
	s_cmp_lg_u32 s4, -1
	s_cselect_b32 s4, s4, 0
	s_cselect_b32 s5, s55, 0
	v_mov_b32_e32 v8, s4
	v_mov_b32_e32 v9, s5
	ds_read_b32 v8, v8
	s_waitcnt vmcnt(0) lgkmcnt(0)
	s_cmp_lg_u32 s50, -1
	s_cselect_b32 s6, s50, 0
	s_cselect_b32 s7, s55, 0
	s_cmp_lg_u32 s51, -1
	s_waitcnt lgkmcnt(0)
	v_readfirstlane_b32 s4, v3
	ds_read_b32 v3, v4
	s_waitcnt vmcnt(0) lgkmcnt(0)
	ds_read_b32 v4, v6
	s_waitcnt vmcnt(0) lgkmcnt(0)
	v_mov_b32_e32 v5, s7
	s_cselect_b32 s7, s55, 0
	v_readfirstlane_b32 s5, v8
	s_waitcnt lgkmcnt(0)
	v_readfirstlane_b32 s11, v3
	v_readfirstlane_b32 s15, v4
	v_mov_b32_e32 v4, s6
	s_cselect_b32 s6, s51, 0
	ds_read_b32 v3, v4
	s_waitcnt vmcnt(0) lgkmcnt(0)
	v_mov_b32_e32 v4, s6
	s_add_i32 s6, 0, 0x23fa8
	s_cmp_lg_u32 s6, -1
	v_mov_b32_e32 v5, s7
	s_cselect_b32 s6, s6, 0
	s_waitcnt lgkmcnt(0)
	ds_read_b32 v3, v4
	s_waitcnt vmcnt(0) lgkmcnt(0)
	s_cselect_b32 s7, s55, 0
	v_mov_b32_e32 v4, s6
	s_add_i32 s6, 0, 0x23fac
	s_cmp_lg_u32 s6, -1
	v_mov_b32_e32 v5, s7
	s_cselect_b32 s6, s6, 0
	s_cselect_b32 s7, s55, 0
	s_waitcnt lgkmcnt(0)
	ds_read_b32 v3, v4
	s_waitcnt vmcnt(0) lgkmcnt(0)
	v_mov_b32_e32 v4, s6
	v_mov_b32_e32 v5, s7
	ds_read_b32 v4, v4
	s_waitcnt vmcnt(0) lgkmcnt(0)
	s_movk_i32 s6, 0x440
	v_cmp_gt_u32_e32 vcc, s6, v19
	s_waitcnt lgkmcnt(0)
	v_readfirstlane_b32 s12, v3
	v_readfirstlane_b32 s13, v4
	s_and_saveexec_b64 s[6:7], vcc
	v_readlane_b32 s50, v254, 10
	v_readlane_b32 s51, v254, 11
	s_cbranch_execz .LBB0_538
	s_sub_i32 s8, s76, s8
	s_lshl_b32 s14, s8, 3
	s_add_u32 s8, s9, 0x1c4000
	v_lshrrev_b32_e32 v3, 2, v10
	s_addc_u32 s9, s10, 0
	v_and_b32_e32 v20, 12, v3
	v_mov_b32_e32 v3, v0
	s_add_u32 s10, s11, 0x400000
	v_lshl_add_u64 v[6:7], s[12:13], 0, v[2:3]
	v_lshl_add_u64 v[2:3], s[0:1], 0, v[2:3]
	s_mov_b64 s[0:1], 0x200000
	s_addc_u32 s11, s15, 0
	v_lshl_add_u64 v[8:9], v[2:3], 0, s[0:1]
	v_and_b32_e32 v10, 48, v10
	v_mov_b32_e32 v11, v0
	s_mov_b64 s[12:13], 0

.LBB0_538:
	s_or_b64 exec, exec, s[6:7]
	s_cmp_lg_u32 s57, -1
	s_cselect_b32 s0, s57, 0
	s_cselect_b32 s1, s55, 0
	s_cmp_lg_u32 s58, -1
	v_mov_b32_e32 v2, s0
	v_mov_b32_e32 v3, s1
	s_cselect_b32 s0, s58, 0
	s_cselect_b32 s1, s55, 0
	s_barrier
	ds_read_b32 v1, v2
	s_waitcnt vmcnt(0) lgkmcnt(0)
	v_mov_b32_e32 v2, s0
	v_mov_b32_e32 v3, s1
	ds_read_b32 v2, v2
	s_waitcnt vmcnt(0) lgkmcnt(0)
	v_readlane_b32 s0, v253, 20
	v_mov_b32_e32 v10, v224
	v_readlane_b32 s1, v253, 21
	s_andn2_b64 vcc, exec, s[0:1]
	s_waitcnt lgkmcnt(0)
	v_readfirstlane_b32 s9, v1
	v_readfirstlane_b32 s0, v10
	v_readfirstlane_b32 s10, v2
	s_cbranch_vccnz .LBB0_557
	v_lshlrev_b32_e32 v1, 4, v10
	v_add_u32_e32 v2, 0x2000, v1
	v_ashrrev_i32_e32 v3, 31, v2
	v_lshrrev_b32_e32 v3, 22, v3
	v_add_u32_e32 v3, v2, v3
	v_ashrrev_i32_e32 v11, 10, v3
	v_mul_i32_i24_e32 v3, 0x400, v11
	v_sub_u32_e32 v2, v2, v3
	v_lshrrev_b32_e32 v3, 4, v2
	v_bitop3_b32 v2, v3, v2, 32 bitop3:0x6c
	v_ashrrev_i32_e32 v3, 31, v2
	v_lshrrev_b32_e32 v3, 26, v3
	v_add_u32_e32 v3, v2, v3
	v_lshlrev_b32_e32 v4, 3, v11
	v_ashrrev_i32_e32 v12, 6, v3
	v_and_b32_e32 v4, -16, v4
	v_add_u32_e32 v4, v12, v4
	v_and_b32_e32 v5, 3, v12
	s_mov_b32 s4, 0x1fffe0
	v_lshrrev_b32_e32 v6, 2, v4
	v_lshlrev_b32_e32 v7, 1, v4
	v_and_or_b32 v5, v4, s4, v5
	v_and_b32_e32 v6, 4, v6
	v_and_b32_e32 v7, 24, v7
	v_and_b32_e32 v3, 0xc0, v3
	v_or3_b32 v5, v5, v6, v7
	v_sub_u32_e32 v2, v2, v3
	v_mov_b32_e32 v7, 1
	v_lshlrev_b32_e32 v6, 5, v11
	v_ashrrev_i16_sdwa v2, v7, sext(v2) dst_sel:DWORD dst_unused:UNUSED_PAD src0_sel:DWORD src1_sel:BYTE_0
	v_and_b32_e32 v6, 32, v6
	v_bfe_i32 v13, v2, 0, 16
	v_add_lshl_u32 v2, v6, v13, 1
	v_lshl_add_u32 v148, v5, 11, v2
	v_lshl_add_u32 v150, v4, 11, v2
	v_bfe_i32 v2, v10, 27, 1
	v_lshrrev_b32_e32 v2, 22, v2
	v_add_u32_e32 v2, v1, v2
	v_and_b32_e32 v2, 0xfffffc00, v2
	v_sub_u32_e32 v1, v1, v2
	v_lshrrev_b32_e32 v2, 4, v1
	v_bitop3_b32 v2, v2, v1, 32 bitop3:0x6c
	v_ashrrev_i32_e32 v1, 31, v1
	v_lshrrev_b32_e32 v1, 26, v1
	v_add_u32_e32 v1, v2, v1
	v_ashrrev_i32_e32 v14, 6, v1
	v_ashrrev_i32_e32 v1, 31, v10
	v_lshrrev_b32_e32 v1, 26, v1
	v_add_u32_e32 v1, v10, v1
	v_ashrrev_i32_e32 v15, 6, v1
	v_lshlrev_b32_e32 v1, 3, v15
	s_add_u32 s24, s9, 0x5a00000
	v_and_b32_e32 v1, -16, v1
	s_addc_u32 s25, s10, 0
	v_add_u32_e32 v1, v14, v1
	s_add_u32 s26, s9, 0x4f80000
	v_and_b32_e32 v3, 3, v14
	v_lshrrev_b32_e32 v4, 2, v1
	v_lshlrev_b32_e32 v5, 1, v1
	s_addc_u32 s27, s10, 0
	s_ashr_i32 s8, s0, 6
	v_and_or_b32 v3, v1, s4, v3
	v_and_b32_e32 v4, 4, v4
	v_and_b32_e32 v5, 24, v5
	s_ashr_i32 s1, s0, 8
	s_lshl_b32 s28, s8, 10
	v_or3_b32 v3, v3, v4, v5
	v_mul_i32_i24_e32 v5, 64, v14
	v_readlane_b32 s4, v253, 41
	v_sub_u32_e32 v2, v2, v5
	v_readlane_b32 s5, v253, 42
	s_add_u32 s18, s24, s4
	v_lshlrev_b32_e32 v4, 5, v15
	v_ashrrev_i16_sdwa v2, v7, sext(v2) dst_sel:DWORD dst_unused:UNUSED_PAD src0_sel:DWORD src1_sel:BYTE_0
	s_addc_u32 s19, s25, s5
	v_readlane_b32 s4, v253, 45
	v_and_b32_e32 v4, 32, v4
	v_bfe_i32 v16, v2, 0, 16
	v_readlane_b32 s5, v253, 46
	s_add_u32 s20, s26, s4
	v_add_lshl_u32 v2, v4, v16, 1
	s_addc_u32 s21, s27, s5
	s_add_i32 s29, s28, 0
	v_lshl_add_u32 v152, v3, 11, v2
	s_add_i32 m0, s29, 0x10000
	v_lshl_add_u32 v154, v1, 11, v2
	global_load_lds_dwordx4 v152, s[20:21]
	s_add_i32 m0, s29, 0x12000
	s_add_u32 s4, s20, 0x40000
	global_load_lds_dwordx4 v148, s[20:21]
	s_addc_u32 s5, s21, 0
	s_add_i32 m0, s29, 0x14000
	s_add_i32 s30, s29, 0x2000
	global_load_lds_dwordx4 v152, s[4:5]
	s_add_i32 m0, s29, 0x16000
	v_mov_b32_e32 v153, v0
	global_load_lds_dwordx4 v148, s[4:5]
	s_mov_b32 m0, s29
	s_add_u32 s4, s18, 0x40000
	global_load_lds_dwordx4 v154, s[18:19]
	s_mov_b32 m0, s30
	s_addc_u32 s5, s19, 0
	s_add_i32 s31, s29, 0x4000
	global_load_lds_dwordx4 v150, s[18:19]
	s_mov_b32 m0, s31
	s_add_i32 s33, s29, 0x6000
	global_load_lds_dwordx4 v154, s[4:5]
	s_mov_b32 m0, s33
	v_mov_b32_e32 v149, v0
	global_load_lds_dwordx4 v150, s[4:5]
	v_mov_b32_e32 v155, v0
	v_mov_b32_e32 v151, v0
	s_cmp_eq_u32 s1, 1
	v_lshl_add_u64 v[8:9], s[20:21], 0, v[152:153]
	v_lshl_add_u64 v[6:7], s[20:21], 0, v[148:149]
	v_lshl_add_u64 v[2:3], s[18:19], 0, v[154:155]
	s_cselect_b64 s[4:5], -1, 0
	s_cmp_lg_u32 s1, 1
	v_lshl_add_u64 v[4:5], s[18:19], 0, v[150:151]
	s_cbranch_scc1 .LBB0_541
	s_barrier

.LBB0_609:
	s_or_b64 exec, exec, s[0:1]
	s_cmp_lg_u32 s57, -1
	s_cselect_b32 s0, s57, 0
	s_cselect_b32 s1, s55, 0
	s_cmp_lg_u32 s58, -1
	v_mov_b32_e32 v1, v224
	s_waitcnt lgkmcnt(0)
	v_mov_b32_e32 v2, s0
	v_mov_b32_e32 v3, s1
	s_cselect_b32 s0, s58, 0
	s_cselect_b32 s1, s55, 0
	s_barrier
	ds_read_b32 v4, v2
	s_waitcnt vmcnt(0) lgkmcnt(0)
	v_mov_b32_e32 v2, s0
	v_mov_b32_e32 v3, s1
	ds_read_b32 v2, v2
	s_waitcnt vmcnt(0) lgkmcnt(0)
	v_readlane_b32 s0, v254, 34
	v_readlane_b32 s1, v254, 35
	s_and_b64 vcc, exec, s[0:1]
	s_waitcnt lgkmcnt(0)
	v_readfirstlane_b32 s52, v4
	v_readfirstlane_b32 s53, v2
	s_cbranch_vccnz .LBB0_682
	s_add_u32 s0, s52, 0xc000000
	s_addc_u32 s1, s53, 0
	v_writelane_b32 v254, s0, 38
	v_ashrrev_i32_e32 v2, 6, v1
	v_cmp_gt_i32_e32 vcc, 4, v2
	v_writelane_b32 v254, s1, 39
	s_add_u32 s0, s52, 0x200000
	s_addc_u32 s1, s53, 0
	v_writelane_b32 v254, s0, 40
	v_sub_u32_e32 v3, 11, v2
	v_cndmask_b32_e32 v6, v3, v2, vcc
	v_writelane_b32 v254, s1, 41
	s_movk_i32 s0, 0x2580
	v_cmp_gt_i32_e64 s[0:1], s0, v1
	v_lshlrev_b32_e32 v2, 4, v1
	v_lshlrev_b32_e32 v10, 3, v1
	v_writelane_b32 v254, s0, 42
	v_and_b32_e32 v2, 0x1f0, v2
	v_mov_b32_e32 v3, v0
	v_writelane_b32 v254, s1, 43
	v_readlane_b32 s0, v253, 62
	v_bfe_u32 v9, v1, 4, 2
	v_lshl_add_u64 v[4:5], s[52:53], 0, v[2:3]
	v_and_b32_e32 v160, 0x7f, v1
	v_ashrrev_i32_e32 v3, 7, v1
	v_add_u32_e32 v164, s0, v10
	s_movk_i32 s0, 0x880
	v_lshl_add_u64 v[136:137], v[4:5], 0, s[82:83]
	s_movk_i32 s4, 0x7f
	v_lshlrev_b32_e32 v138, 3, v3
	v_add_u32_e32 v4, 0, v2
	v_mul_lo_u32 v2, v3, s0
	v_lshlrev_b32_e32 v3, 1, v160
	v_readlane_b32 s5, v253, 63
	v_readlane_b32 s46, v254, 0
	v_bfe_u32 v5, v1, 2, 2
	v_lshlrev_b32_e32 v12, 3, v9
	s_add_i32 s0, 0, 0x15400
	v_and_b32_e32 v141, 15, v1
	v_add3_u32 v165, s5, v2, v3
	v_add3_u32 v166, s46, v2, v3
	v_or_b32_e32 v5, v12, v5
	v_add_u32_e32 v167, s0, v3
	v_cmp_lt_i32_e64 s[16:17], -1, v6
	v_cmp_lt_i32_e64 s[18:19], 0, v6
	v_cmp_lt_i32_e64 s[20:21], 1, v6
	v_cmp_lt_i32_e64 s[22:23], 2, v6
	v_cmp_lt_i32_e64 s[24:25], 3, v6
	v_cmp_lt_i32_e64 s[26:27], 4, v6
	v_cmp_lt_i32_e64 s[28:29], 5, v6
	v_cmp_lt_i32_e64 s[30:31], 6, v6
	v_lshlrev_b32_e32 v3, 4, v6
	v_add_u32_e32 v6, s5, v12
	v_bitop3_b32 v12, v1, s4, 15 bitop3:0x6c
	v_or_b32_e32 v170, v3, v141
	v_sub_u32_e32 v172, v12, v3
	v_add_u32_e32 v3, 0x200, v1
	v_ashrrev_i32_e32 v174, 5, v3
	v_add_u32_e32 v3, 0x400, v1
	v_ashrrev_i32_e32 v175, 5, v3
	v_add_u32_e32 v3, 0x600, v1
	v_ashrrev_i32_e32 v176, 5, v3
	v_add_u32_e32 v3, 0x800, v1
	v_ashrrev_i32_e32 v177, 5, v3
	v_add_u32_e32 v3, 0xa00, v1
	v_ashrrev_i32_e32 v178, 5, v3
	v_add_u32_e32 v3, 0xc00, v1
	v_ashrrev_i32_e32 v179, 5, v3
	v_add_u32_e32 v3, 0xe00, v1
	v_and_b32_e32 v7, 63, v1
	v_lshlrev_b32_e32 v8, 1, v141
	v_and_b32_e32 v2, 48, v1
	v_and_b32_e32 v13, 0xffffffc0, v1
	v_and_b32_e32 v10, 24, v10
	v_lshlrev_b32_e32 v140, 2, v9
	v_readlane_b32 s1, v253, 61
	v_ashrrev_i32_e32 v173, 5, v1
	v_ashrrev_i32_e32 v180, 5, v3
	s_movk_i32 s0, 0x210
	v_cmp_eq_u32_e64 s[12:13], 0, v7
	v_add3_u32 v10, 0, v13, v10
	v_add3_u32 v8, s1, v8, v13
	v_add_u32_e32 v171, s1, v2
	v_cmp_gt_u32_e64 s[34:35], 2, v7
	v_cmp_gt_u32_e64 s[36:37], 4, v7
	v_cmp_gt_u32_e64 s[38:39], 8, v7
	v_cmp_gt_u32_e64 s[40:41], 16, v7
	v_cmp_gt_u32_e64 s[42:43], 32, v7
	v_mul_lo_u32 v7, v173, s0
	v_mul_lo_u32 v12, v174, s0
	v_mul_lo_u32 v13, v175, s0
	v_mul_lo_u32 v14, v176, s0
	v_mul_lo_u32 v15, v177, s0
	v_mul_lo_u32 v16, v178, s0
	v_mul_lo_u32 v17, v179, s0
	v_mul_lo_u32 v18, v180, s0
	v_cmp_gt_i32_e64 s[0:1], v140, v170
	v_or_b32_e32 v3, 3, v140
	v_or_b32_e32 v19, 2, v140
	v_writelane_b32 v254, s0, 44
	v_cmp_gt_u32_e64 s[14:15], s77, v1
	s_mov_b32 s33, s75
	v_writelane_b32 v254, s1, 45
	v_cmp_lt_i32_e64 s[0:1], v140, v170
	v_bitop3_b32 v161, v1, s4, v1 bitop3:0xc
	v_mul_u32_u24_e32 v168, 0x210, v141
	v_writelane_b32 v254, s0, 46
	v_lshlrev_b32_e32 v162, 1, v1
	v_add_u32_e32 v11, s46, v2
	v_writelane_b32 v254, s1, 47
	v_cmp_gt_i32_e64 s[0:1], v3, v170
	v_or_b32_e32 v3, 17, v140
	v_add3_u32 v169, 0, v168, v2
	v_writelane_b32 v254, s0, 48
	s_mov_b64 s[50:51], 0x7c00000
	v_mul_u32_u24_e32 v5, 0x210, v5
	v_writelane_b32 v254, s1, 49
	v_cmp_gt_i32_e64 s[0:1], v19, v170
	v_or_b32_e32 v19, 16, v140
	v_mul_u32_u24_e32 v9, 0x840, v9
	v_writelane_b32 v254, s0, 50
	v_ashrrev_i32_e32 v139, 31, v138
	v_cmp_lt_u32_e64 s[8:9], 63, v1
	v_writelane_b32 v254, s1, 51
	v_cmp_gt_i32_e64 s[0:1], v3, v170
	v_or_b32_e32 v3, 19, v140
	v_cmp_gt_u32_e64 s[10:11], 64, v1
	v_writelane_b32 v254, s0, 52
	v_or_b32_e32 v163, 1, v162
	v_sub_u32_e32 v181, 0x7f, v180
	v_writelane_b32 v254, s1, 53
	v_cmp_gt_i32_e64 s[0:1], v19, v170
	v_or_b32_e32 v19, 18, v140
	v_add_u32_e32 v182, 0xfffffe00, v1
	v_writelane_b32 v254, s0, 54
	v_lshl_add_u32 v183, v1, 2, s46
	v_lshlrev_b32_e32 v144, 1, v140
	v_writelane_b32 v254, s1, 55
	v_cmp_gt_i32_e64 s[0:1], v3, v170
	v_or_b32_e32 v3, 33, v140
	v_add_u32_e32 v184, v4, v7
	v_writelane_b32 v254, s0, 56
	v_add_u32_e32 v185, v4, v12
	v_add_u32_e32 v186, v4, v13
	v_writelane_b32 v254, s1, 57
	v_cmp_gt_i32_e64 s[0:1], v19, v170
	v_or_b32_e32 v19, 32, v140
	v_add_u32_e32 v187, v4, v14
	v_writelane_b32 v254, s0, 58
	v_add_u32_e32 v188, v4, v15
	v_add_u32_e32 v189, v4, v16
	v_writelane_b32 v254, s1, 59
	v_cmp_gt_i32_e64 s[0:1], v3, v170
	v_or_b32_e32 v3, 35, v140
	v_add_u32_e32 v190, v4, v17
	v_writelane_b32 v254, s0, 60
	v_add_u32_e32 v191, v4, v18
	v_add_u32_e32 v194, v10, v5
	v_writelane_b32 v254, s1, 61
	v_cmp_gt_i32_e64 s[0:1], v19, v170
	v_or_b32_e32 v19, 34, v140
	v_cmp_gt_i32_e64 s[66:67], v19, v170
	v_writelane_b32 v254, s0, 62
	v_or_b32_e32 v19, 48, v140
	v_cmp_gt_i32_e64 s[70:71], v19, v170
	v_writelane_b32 v254, s1, 63
	v_cmp_gt_i32_e64 s[0:1], v3, v170
	v_or_b32_e32 v3, 49, v140
	v_cmp_gt_i32_e64 s[68:69], v3, v170
	v_or_b32_e32 v3, 51, v140
	v_cmp_gt_i32_e64 s[72:73], v3, v170
	v_or_b32_e32 v3, 0x41, v140
	v_or_b32_e32 v19, 50, v140
	v_cmp_gt_i32_e64 s[76:77], v3, v170
	v_or_b32_e32 v3, 0x43, v140
	v_cmp_gt_i32_e64 s[74:75], v19, v170
	v_or_b32_e32 v19, 64, v140
	v_cmp_gt_i32_e64 s[80:81], v3, v170
	v_or_b32_e32 v3, 0x51, v140
	v_cmp_gt_i32_e64 s[78:79], v19, v170
	v_or_b32_e32 v19, 0x42, v140
	v_cmp_gt_i32_e64 s[84:85], v3, v170
	v_or_b32_e32 v3, 0x53, v140
	v_cmp_gt_i32_e64 s[82:83], v19, v170
	v_or_b32_e32 v19, 0x50, v140
	v_cmp_gt_i32_e64 s[88:89], v3, v170
	v_or_b32_e32 v3, 0x61, v140
	v_cmp_gt_i32_e64 s[86:87], v19, v170
	v_or_b32_e32 v19, 0x52, v140
	v_cmp_gt_i32_e64 s[92:93], v3, v170
	v_or_b32_e32 v3, 0x63, v140
	v_cmp_gt_i32_e64 s[90:91], v19, v170
	v_or_b32_e32 v19, 0x60, v140
	v_cmp_gt_i32_e64 s[96:97], v3, v170
	v_or_b32_e32 v3, 0x71, v140
	v_cmp_gt_i32_e64 s[94:95], v19, v170
	v_or_b32_e32 v19, 0x62, v140
	v_cmp_gt_i32_e64 s[48:49], v3, v170
	v_or_b32_e32 v3, 0x73, v140
	v_writelane_b32 v255, s0, 0
	v_cmp_gt_i32_e64 s[4:5], v19, v170
	v_or_b32_e32 v19, 0x70, v140
	v_cmp_gt_i32_e64 s[6:7], v3, v170
	v_or_b32_e32 v3, 16, v141
	v_writelane_b32 v255, s1, 1
	v_cmp_gt_i32_e64 s[0:1], v19, v170
	v_or_b32_e32 v19, 0x72, v140
	v_mul_u32_u24_e32 v20, 0x210, v3
	v_mov_b32_e32 v3, v0
	v_cmp_gt_i32_e64 s[44:45], v19, v170
	v_mul_u32_u24_e32 v19, 0x110, v141
	v_writelane_b32 v255, s52, 2
	v_add_u32_e32 v192, v171, v20
	v_add_u32_e32 v193, v11, v19
	v_lshl_add_u64 v[2:3], s[52:53], 0, v[2:3]
	v_writelane_b32 v255, s53, 3
	v_lshl_add_u64 v[142:143], v[2:3], 0, s[50:51]
	v_add_u32_e32 v195, v8, v9
	v_add_u32_e32 v196, v6, v19
	s_branch .LBB0_612

.LBB0_734:
	s_or_b64 exec, exec, s[0:1]
	s_cmp_lg_u32 s57, -1
	s_cselect_b32 s0, s57, 0
	s_cselect_b32 s1, s55, 0
	s_cmp_lg_u32 s58, -1
	v_mov_b64_e32 v[4:5], s[0:1]
	s_cselect_b32 s0, s58, 0
	s_cselect_b32 s1, s55, 0
	v_mov_b32_e32 v3, v224
	v_mov_b64_e32 v[6:7], s[0:1]
	s_waitcnt lgkmcnt(0)
	s_barrier
	ds_read_b32 v1, v4
	s_waitcnt vmcnt(0) lgkmcnt(0)
	ds_read_b32 v2, v6
	s_waitcnt vmcnt(0) lgkmcnt(0)
	s_add_i32 s0, 0, 0x23fb0
	s_cmp_lg_u32 s0, -1
	s_cselect_b32 s0, s0, 0
	s_cselect_b32 s1, s55, 0
	s_waitcnt lgkmcnt(0)
	v_readfirstlane_b32 s4, v1
	v_readfirstlane_b32 s5, v2
	ds_read_b32 v1, v4
	s_waitcnt vmcnt(0) lgkmcnt(0)
	ds_read_b32 v2, v6
	s_waitcnt vmcnt(0) lgkmcnt(0)
	v_readfirstlane_b32 s6, v1
	v_readfirstlane_b32 s7, v2
	ds_read_b32 v1, v4
	s_waitcnt vmcnt(0) lgkmcnt(0)
	ds_read_b32 v2, v6
	s_waitcnt vmcnt(0) lgkmcnt(0)
	v_mov_b32_e32 v4, s0
	s_add_i32 s0, 0, 0x23fb4
	v_mov_b32_e32 v5, s1
	s_cmp_lg_u32 s0, -1
	s_cselect_b32 s0, s0, 0
	s_cselect_b32 s1, s55, 0
	s_waitcnt lgkmcnt(0)
	v_readfirstlane_b32 s8, v1
	ds_read_b32 v1, v4
	s_waitcnt vmcnt(0) lgkmcnt(0)
	v_mov_b32_e32 v4, s0
	v_mov_b32_e32 v5, s1
	v_readfirstlane_b32 s9, v2
	ds_read_b32 v2, v4
	s_waitcnt vmcnt(0) lgkmcnt(0)
	v_readlane_b32 s0, v253, 22
	s_waitcnt lgkmcnt(0)
	v_readfirstlane_b32 s10, v1
	v_ashrrev_i32_e32 v1, 5, v3
	v_and_b32_e32 v1, -2, v1
	v_readfirstlane_b32 s11, v2
	v_add_u32_e32 v2, s0, v1
	s_movk_i32 s0, 0x4000
	v_cmp_gt_i32_e32 vcc, s0, v2
	s_and_saveexec_b64 s[0:1], vcc
	v_readlane_b32 s14, v254, 8
	v_readlane_b32 s15, v254, 9
	s_cbranch_execz .LBB0_737
	v_and_b32_e32 v1, 64, v230
	v_add_u32_e32 v4, 64, v1
	v_xor_b32_e32 v1, 1, v230
	v_cmp_lt_i32_e32 vcc, v1, v4
	v_xor_b32_e32 v5, 2, v230
	v_mov_b32_e32 v7, v0
	v_cndmask_b32_e32 v1, v230, v1, vcc
	v_cmp_lt_i32_e32 vcc, v5, v4
	v_lshlrev_b32_e32 v1, 2, v1
	s_nop 0
	v_cndmask_b32_e32 v5, v230, v5, vcc
	v_lshlrev_b32_e32 v44, 2, v5
	v_xor_b32_e32 v5, 4, v230
	v_cmp_lt_i32_e32 vcc, v5, v4
	s_nop 1
	v_cndmask_b32_e32 v5, v230, v5, vcc
	v_lshlrev_b32_e32 v45, 2, v5
	v_xor_b32_e32 v5, 8, v230
	v_cmp_lt_i32_e32 vcc, v5, v4
	s_nop 1
	v_cndmask_b32_e32 v5, v230, v5, vcc
	v_lshlrev_b32_e32 v46, 2, v5
	v_xor_b32_e32 v5, 16, v230
	v_cmp_lt_i32_e32 vcc, v5, v4
	s_nop 1
	v_cndmask_b32_e32 v5, v230, v5, vcc
	v_lshlrev_b32_e32 v47, 2, v5
	v_xor_b32_e32 v5, 32, v230
	v_cmp_lt_i32_e32 vcc, v5, v4
	s_nop 1
	v_cndmask_b32_e32 v4, v230, v5, vcc
	v_lshlrev_b32_e32 v48, 2, v4
	v_lshlrev_b32_e32 v4, 4, v3
	v_and_b32_e32 v3, 63, v3
	v_lshlrev_b32_e32 v6, 3, v3
	v_ashrrev_i32_e32 v3, 31, v2
	v_and_b32_e32 v4, 0x3f0, v4
	v_mov_b32_e32 v5, v0
	v_lshlrev_b64 v[12:13], 11, v[2:3]
	v_lshl_add_u64 v[4:5], s[10:11], 0, v[4:5]
	v_lshl_add_u64 v[8:9], s[8:9], 0, v[12:13]
	v_lshl_add_u64 v[10:11], s[6:7], 0, v[12:13]
	v_lshl_add_u64 v[12:13], s[4:5], 0, v[12:13]
	s_mov_b64 s[4:5], 0

.LBB0_737:
	s_or_b64 exec, exec, s[0:1]
	s_cmp_lg_u32 s57, -1
	s_cselect_b32 s0, s57, 0
	s_cselect_b32 s1, s55, 0
	s_cmp_lg_u32 s58, -1
	v_mov_b32_e32 v2, s0
	v_mov_b32_e32 v3, s1
	s_cselect_b32 s0, s58, 0
	s_cselect_b32 s1, s55, 0
	ds_read_b32 v1, v2
	s_waitcnt vmcnt(0) lgkmcnt(0)
	v_mov_b32_e32 v2, s0
	v_mov_b32_e32 v3, s1
	ds_read_b32 v2, v2
	s_waitcnt vmcnt(0) lgkmcnt(0)
	s_getreg_b32 s6, hwreg(HW_REG_XCC_ID, 0, 4)
	s_waitcnt vmcnt(0)
	s_waitcnt lgkmcnt(0)
	s_barrier
	v_readfirstlane_b32 s4, v1
	v_readfirstlane_b32 s5, v2
	s_and_saveexec_b64 s[0:1], s[78:79]
	s_cbranch_execz .LBB0_789
	v_readlane_b32 s7, v253, 59
	s_waitcnt vmcnt(0) expcnt(0) lgkmcnt(0)
	s_and_b32 s33, s6, 15
	v_mov_b32_e32 v1, s7
	ds_read_b32 v3, v1
	v_readlane_b32 s7, v253, 60
	s_waitcnt lgkmcnt(0)
	v_cmp_ne_u32_e32 vcc, 0, v3
	v_mov_b32_e32 v1, s7
	ds_read_b32 v2, v1
	s_cbranch_vccnz .LBB0_753
	s_add_u32 s6, s4, 0x3c0200
	s_addc_u32 s7, s5, 0
	s_add_u32 s8, s4, 0x3c0400
	s_addc_u32 s9, s5, 0
	s_add_u32 s10, s4, 0x3c0500
	s_addc_u32 s11, s5, 0
	s_add_u32 s12, s4, 0x3c0600
	s_addc_u32 s13, s5, 0
	s_add_u32 s14, s4, 0x3c0700
	s_addc_u32 s15, s5, 0
	s_add_u32 s16, s4, 0x3c0800
	s_addc_u32 s17, s5, 0
	s_add_u32 s18, s4, 0x3c0900
	s_addc_u32 s19, s5, 0
	s_add_u32 s20, s4, 0x3c0a00
	s_addc_u32 s21, s5, 0
	s_add_u32 s22, s4, 0x3c0b00
	s_addc_u32 s23, s5, 0
	s_add_u32 s24, s4, 0x3c0c00
	s_addc_u32 s25, s5, 0
	s_add_u32 s26, s4, 0x3c0d00
	s_addc_u32 s27, s5, 0
	s_add_u32 s28, s4, 0x3c0e00
	s_addc_u32 s29, s5, 0
	s_add_u32 s30, s4, 0x3c0f00
	s_addc_u32 s31, s5, 0
	s_add_u32 s34, s4, 0x3c1000
	s_addc_u32 s35, s5, 0
	s_add_u32 s36, s4, 0x3c1100
	s_addc_u32 s37, s5, 0
	s_add_u32 s38, s4, 0x3c1200
	s_addc_u32 s39, s5, 0
	s_add_u32 s40, s4, 0x3c1300
	s_addc_u32 s41, s5, 0
	s_mov_b32 s48, 1
	s_branch .LBB0_741

.LBB0_789:
	s_or_b64 exec, exec, s[0:1]
	s_cmp_lg_u32 s57, -1
	s_cselect_b32 s0, s57, 0
	s_cselect_b32 s1, s55, 0
	s_cmp_lg_u32 s58, -1
	s_waitcnt lgkmcnt(0)
	v_mov_b32_e32 v2, s0
	v_mov_b32_e32 v3, s1
	s_cselect_b32 s0, s58, 0
	s_cselect_b32 s1, s55, 0
	s_barrier
	ds_read_b32 v1, v2
	s_waitcnt vmcnt(0) lgkmcnt(0)
	v_mov_b32_e32 v2, s0
	v_mov_b32_e32 v3, s1
	ds_read_b32 v2, v2
	s_waitcnt vmcnt(0) lgkmcnt(0)
	v_readlane_b32 s0, v254, 34
	v_mov_b32_e32 v10, v224
	v_readlane_b32 s1, v254, 35
	s_and_b64 vcc, exec, s[0:1]
	s_waitcnt lgkmcnt(0)
	v_readfirstlane_b32 s28, v1
	v_readfirstlane_b32 s6, v10
	v_readfirstlane_b32 s29, v2
	s_cbranch_vccnz .LBB0_809
	v_lshlrev_b32_e32 v1, 4, v10
	v_add_u32_e32 v2, 0x2000, v1
	v_ashrrev_i32_e32 v3, 31, v2
	v_lshrrev_b32_e32 v3, 22, v3
	v_add_u32_e32 v3, v2, v3
	v_ashrrev_i32_e32 v11, 10, v3
	v_mul_i32_i24_e32 v3, 0x400, v11
	v_sub_u32_e32 v2, v2, v3
	v_lshrrev_b32_e32 v3, 4, v2
	v_bitop3_b32 v2, v3, v2, 32 bitop3:0x6c
	v_ashrrev_i32_e32 v3, 31, v2
	v_lshrrev_b32_e32 v3, 26, v3
	v_add_u32_e32 v3, v2, v3
	v_lshlrev_b32_e32 v4, 3, v11
	v_ashrrev_i32_e32 v12, 6, v3
	v_and_b32_e32 v4, -16, v4
	v_add_u32_e32 v4, v12, v4
	v_and_b32_e32 v5, 3, v12
	s_mov_b32 s0, 0x1fffe0
	v_lshrrev_b32_e32 v6, 2, v4
	v_lshlrev_b32_e32 v7, 1, v4
	v_and_or_b32 v5, v4, s0, v5
	v_and_b32_e32 v6, 4, v6
	v_and_b32_e32 v7, 24, v7
	v_and_b32_e32 v3, 0xc0, v3
	v_or3_b32 v5, v5, v6, v7
	v_sub_u32_e32 v2, v2, v3
	v_mov_b32_e32 v7, 1
	v_lshlrev_b32_e32 v6, 5, v11
	v_ashrrev_i16_sdwa v2, v7, sext(v2) dst_sel:DWORD dst_unused:UNUSED_PAD src0_sel:DWORD src1_sel:BYTE_0
	v_and_b32_e32 v6, 32, v6
	v_bfe_i32 v13, v2, 0, 16
	v_add_lshl_u32 v2, v6, v13, 1
	v_lshl_add_u32 v148, v5, 11, v2
	v_lshl_add_u32 v150, v4, 11, v2
	v_bfe_i32 v2, v10, 27, 1
	v_lshrrev_b32_e32 v2, 22, v2
	v_add_u32_e32 v2, v1, v2
	v_and_b32_e32 v2, 0xfffffc00, v2
	v_sub_u32_e32 v1, v1, v2
	v_lshrrev_b32_e32 v2, 4, v1
	v_bitop3_b32 v2, v2, v1, 32 bitop3:0x6c
	v_ashrrev_i32_e32 v1, 31, v1
	v_lshrrev_b32_e32 v1, 26, v1
	v_add_u32_e32 v1, v2, v1
	v_ashrrev_i32_e32 v14, 6, v1
	v_ashrrev_i32_e32 v1, 31, v10
	v_lshrrev_b32_e32 v1, 26, v1
	v_add_u32_e32 v1, v10, v1
	v_ashrrev_i32_e32 v15, 6, v1
	v_lshlrev_b32_e32 v1, 3, v15
	s_add_u32 s30, s28, 0x5a00000
	v_and_b32_e32 v1, -16, v1
	s_addc_u32 s31, s29, 0
	v_add_u32_e32 v1, v14, v1
	s_add_u32 s34, s28, 0x5580000
	v_and_b32_e32 v3, 3, v14
	v_lshrrev_b32_e32 v4, 2, v1
	v_lshlrev_b32_e32 v5, 1, v1
	s_addc_u32 s35, s29, 0
	s_ashr_i32 s12, s6, 6
	v_and_or_b32 v3, v1, s0, v3
	v_and_b32_e32 v4, 4, v4
	v_and_b32_e32 v5, 24, v5
	s_ashr_i32 s7, s6, 8
	s_lshl_b32 s36, s12, 10
	v_or3_b32 v3, v3, v4, v5
	v_mul_i32_i24_e32 v5, 64, v14
	v_readlane_b32 s0, v253, 34
	v_sub_u32_e32 v2, v2, v5
	v_readlane_b32 s1, v253, 35
	s_add_u32 s22, s30, s0
	v_lshlrev_b32_e32 v4, 5, v15
	v_ashrrev_i16_sdwa v2, v7, sext(v2) dst_sel:DWORD dst_unused:UNUSED_PAD src0_sel:DWORD src1_sel:BYTE_0
	s_addc_u32 s23, s31, s1
	v_readlane_b32 s0, v253, 36
	v_and_b32_e32 v4, 32, v4
	v_bfe_i32 v16, v2, 0, 16
	v_readlane_b32 s1, v253, 37
	s_add_u32 s24, s34, s0
	v_add_lshl_u32 v2, v4, v16, 1
	s_addc_u32 s25, s35, s1
	s_add_i32 s37, s36, 0
	v_lshl_add_u32 v152, v3, 11, v2
	s_add_i32 m0, s37, 0x10000
	v_lshl_add_u32 v154, v1, 11, v2
	global_load_lds_dwordx4 v152, s[24:25]
	s_add_i32 m0, s37, 0x12000
	s_add_u32 s0, s24, 0x40000
	global_load_lds_dwordx4 v148, s[24:25]
	s_addc_u32 s1, s25, 0
	s_add_i32 m0, s37, 0x14000
	s_add_i32 s38, s37, 0x2000
	global_load_lds_dwordx4 v152, s[0:1]
	s_add_i32 m0, s37, 0x16000
	v_mov_b32_e32 v153, v0
	global_load_lds_dwordx4 v148, s[0:1]
	s_mov_b32 m0, s37
	s_add_u32 s0, s22, 0x40000
	global_load_lds_dwordx4 v154, s[22:23]
	s_mov_b32 m0, s38
	s_addc_u32 s1, s23, 0
	s_add_i32 s39, s37, 0x4000
	global_load_lds_dwordx4 v150, s[22:23]
	s_mov_b32 m0, s39
	s_add_i32 s40, s37, 0x6000
	global_load_lds_dwordx4 v154, s[0:1]
	s_mov_b32 m0, s40
	v_mov_b32_e32 v149, v0
	global_load_lds_dwordx4 v150, s[0:1]
	v_mov_b32_e32 v155, v0
	v_mov_b32_e32 v151, v0
	s_cmp_eq_u32 s7, 1
	v_lshl_add_u64 v[8:9], s[24:25], 0, v[152:153]
	v_lshl_add_u64 v[6:7], s[24:25], 0, v[148:149]
	v_lshl_add_u64 v[2:3], s[22:23], 0, v[154:155]
	s_cselect_b64 s[0:1], -1, 0
	s_cmp_lg_u32 s7, 1
	v_lshl_add_u64 v[4:5], s[22:23], 0, v[150:151]
	s_cbranch_scc1 .LBB0_792
	s_barrier

.LBB0_862:
	s_and_b64 vcc, exec, s[0:1]
	s_cbranch_vccz .LBB0_966
	s_cmp_lg_u32 s57, -1
	s_cselect_b32 s0, s57, 0
	s_cselect_b32 s1, s55, 0
	s_cmp_lg_u32 s58, -1
	v_mov_b32_e32 v2, s0
	v_mov_b32_e32 v3, s1
	s_cselect_b32 s0, s58, 0
	s_cselect_b32 s1, s55, 0
	ds_read_b32 v1, v2
	s_waitcnt vmcnt(0) lgkmcnt(0)
	v_mov_b32_e32 v2, s0
	v_mov_b32_e32 v3, s1
	ds_read_b32 v2, v2
	s_waitcnt vmcnt(0) lgkmcnt(0)
	v_readlane_b32 s4, v253, 23
	v_readlane_b32 s5, v253, 24
	v_mov_b32_e32 v10, v224
	s_andn2_b64 vcc, exec, s[4:5]
	v_cndmask_b32_e64 v3, 0, 1, s[4:5]
	v_cmp_ne_u32_e64 s[0:1], 1, v3
	s_waitcnt lgkmcnt(0)
	v_readfirstlane_b32 s8, v1
	v_readfirstlane_b32 s6, v10
	v_readfirstlane_b32 s9, v2
	s_cbranch_vccnz .LBB0_865
	v_readlane_b32 s5, v253, 58
	v_readlane_b32 s4, v253, 57
	s_mov_b32 s28, s5

.LBB0_1020:
	s_or_b64 exec, exec, s[0:1]
	s_cmp_lg_u32 s57, -1
	s_cselect_b32 s0, s57, 0
	s_cselect_b32 s1, s55, 0
	s_cmp_lg_u32 s58, -1
	s_waitcnt lgkmcnt(0)
	v_mov_b32_e32 v2, s0
	v_mov_b32_e32 v3, s1
	s_cselect_b32 s0, s58, 0
	s_cselect_b32 s1, s55, 0
	s_barrier
	ds_read_b32 v1, v2
	s_waitcnt vmcnt(0) lgkmcnt(0)
	v_mov_b32_e32 v2, s0
	v_mov_b32_e32 v3, s1
	ds_read_b32 v2, v2
	s_waitcnt vmcnt(0) lgkmcnt(0)
	s_mov_b64 s[10:11], 0
	s_waitcnt lgkmcnt(0)
	v_readfirstlane_b32 s0, v1
	s_add_u32 s8, s0, 0x3e0000
	v_readfirstlane_b32 s1, v2
	s_addc_u32 s9, s1, 0
	s_branch .LBB0_1024

.LBB0_1028:
	s_or_b64 exec, exec, s[0:1]
	s_add_i32 s0, 0, 0x23e80
	s_cmp_lg_u32 s0, -1
	s_cselect_b32 s0, s0, 0
	s_cselect_b32 s1, s55, 0
	v_mov_b32_e32 v2, s0
	v_mov_b32_e32 v3, s1
	s_waitcnt lgkmcnt(0)
	s_barrier
	ds_read_b32 v2, v2
	s_waitcnt vmcnt(0) lgkmcnt(0)
	s_movk_i32 s0, 0x330
	s_waitcnt lgkmcnt(0)
	v_cmp_gt_i32_e32 vcc, s0, v2
	s_mov_b64 s[0:1], -1
	s_and_saveexec_b64 s[12:13], vcc
	s_cbranch_execz .LBB0_1023
	s_movk_i32 s0, 0x21f
	v_cmp_lt_i32_e32 vcc, s0, v2
	s_and_saveexec_b64 s[0:1], vcc
	s_xor_b64 s[4:5], exec, s[0:1]
	s_cbranch_execz .LBB0_1167
	s_movk_i32 s0, 0x31f
	v_cmp_lt_u32_e32 vcc, s0, v2
	v_lshlrev_b32_e32 v2, 6, v2
	s_and_saveexec_b64 s[0:1], vcc
	s_xor_b64 s[0:1], exec, s[0:1]
	v_add_u32_e32 v1, 0x7fff3800, v2
	v_and_b32_e32 v1, 0x7fffff00, v1
	v_add_u32_e32 v1, 0x4000, v1
	v_and_b32_e32 v136, 0xc0, v2
	s_or_saveexec_b64 s[0:1], s[0:1]
	v_mov_b32_e32 v138, 0x100
	s_xor_b64 exec, exec, s[0:1]
	v_add_u32_e32 v2, 0xffff7800, v2
	v_and_b32_e32 v1, 0x7ffff000, v2
	v_and_b32_e32 v136, 0xfc0, v2
	v_mov_b32_e32 v138, 0x1000
	s_or_b64 exec, exec, s[0:1]
	s_cmp_lg_u32 s57, -1
	s_cselect_b32 s0, s57, 0
	s_cselect_b32 s1, s55, 0
	s_cmp_lg_u32 s58, -1
	v_mov_b32_e32 v137, v224
	v_mov_b32_e32 v2, s0
	v_mov_b32_e32 v3, s1
	s_cselect_b32 s0, s58, 0
	ds_read_b32 v68, v2
	s_waitcnt vmcnt(0) lgkmcnt(0)
	s_cselect_b32 s1, s55, 0
	v_mov_b32_e32 v2, s0
	s_add_i32 s0, 0, 0x23f70
	s_cmp_lg_u32 s0, -1
	v_mov_b32_e32 v3, s1
	s_cselect_b32 s0, s0, 0
	ds_read_b32 v69, v2
	s_waitcnt vmcnt(0) lgkmcnt(0)
	s_cselect_b32 s1, s55, 0
	v_mov_b32_e32 v2, s0
	s_add_i32 s0, 0, 0x23f74
	s_cmp_lg_u32 s0, -1
	v_mov_b32_e32 v3, s1
	s_cselect_b32 s0, s0, 0
	s_cselect_b32 s1, s55, 0
	ds_read_b32 v4, v2
	s_waitcnt vmcnt(0) lgkmcnt(0)
	v_mov_b32_e32 v2, s0
	v_mov_b32_e32 v3, s1
	ds_read_b32 v5, v2
	s_waitcnt vmcnt(0) lgkmcnt(0)
	v_lshlrev_b32_e32 v2, 1, v137
	v_and_b32_e32 v70, 0x1fe, v2
	v_mov_b32_e32 v3, v0
	v_lshlrev_b32_e32 v2, 2, v70
	s_movk_i32 s6, 0x1000
	v_ashrrev_i32_e32 v71, 8, v137
	v_lshl_add_u32 v139, v71, 16, 0
	s_mov_b32 s43, 0
	v_add_u32_e32 v140, v139, v2
	s_mov_b64 s[16:17], 0
	s_mov_b64 s[14:15], -1
	v_mov_b32_e32 v72, 0
	v_mov_b32_e32 v73, 0
	s_waitcnt lgkmcnt(0)
	v_readfirstlane_b32 s7, v69
	v_mov_b32_e32 v69, v0
	v_readfirstlane_b32 s0, v4
	v_readfirstlane_b32 s1, v5
	s_nop 1
	v_lshl_add_u64 v[58:59], s[0:1], 0, v[2:3]
	v_add_co_u32_e32 v28, vcc, s6, v58
	s_movk_i32 s6, 0x2000
	s_nop 0
	v_addc_co_u32_e32 v29, vcc, 0, v59, vcc
	v_add_co_u32_e32 v12, vcc, s6, v58
	s_movk_i32 s6, 0x3000
	s_nop 0
	v_addc_co_u32_e32 v13, vcc, 0, v59, vcc
	v_add_co_u32_e32 v30, vcc, s6, v58
	s_movk_i32 s6, 0x4000
	s_nop 0
	v_addc_co_u32_e32 v31, vcc, 0, v59, vcc
	v_add_co_u32_e32 v18, vcc, s6, v58
	s_movk_i32 s6, 0x5000
	s_nop 0
	v_addc_co_u32_e32 v19, vcc, 0, v59, vcc
	v_add_co_u32_e32 v32, vcc, s6, v58
	s_movk_i32 s6, 0x6000
	s_nop 0
	v_addc_co_u32_e32 v33, vcc, 0, v59, vcc
	v_add_co_u32_e32 v24, vcc, s6, v58
	s_movk_i32 s6, 0x7000
	s_nop 0
	v_addc_co_u32_e32 v25, vcc, 0, v59, vcc
	v_add_co_u32_e32 v34, vcc, s6, v58
	s_mov_b32 s6, 0x8000
	s_nop 0
	v_addc_co_u32_e32 v35, vcc, 0, v59, vcc
	v_add_co_u32_e32 v38, vcc, s6, v58
	s_mov_b32 s6, 0x9000
	s_nop 0
	v_addc_co_u32_e32 v39, vcc, 0, v59, vcc
	v_add_co_u32_e32 v60, vcc, s6, v58
	s_mov_b32 s6, 0xa000
	s_nop 0
	v_addc_co_u32_e32 v61, vcc, 0, v59, vcc
	v_add_co_u32_e32 v44, vcc, s6, v58
	v_readfirstlane_b32 s6, v68
	s_nop 0
	v_addc_co_u32_e32 v45, vcc, 0, v59, vcc
	global_load_dwordx2 v[4:5], v2, s[0:1]
	global_load_dwordx2 v[6:7], v2, s[0:1] offset:2048
	global_load_dwordx2 v[8:9], v[12:13], off offset:-4096
	global_load_dwordx2 v[10:11], v[12:13], off
	s_nop 0
	global_load_dwordx2 v[12:13], v[12:13], off offset:2048
	s_nop 0
	global_load_dwordx2 v[14:15], v[18:19], off offset:-4096
	global_load_dwordx2 v[16:17], v[18:19], off
	s_nop 0
	global_load_dwordx2 v[18:19], v[18:19], off offset:2048
	s_nop 0
	global_load_dwordx2 v[20:21], v[24:25], off offset:-4096
	global_load_dwordx2 v[22:23], v[24:25], off
	s_nop 0
	global_load_dwordx2 v[24:25], v[24:25], off offset:2048
	s_nop 0
	global_load_dwordx2 v[26:27], v[38:39], off offset:-4096
	s_nop 0
	global_load_dwordx2 v[28:29], v[28:29], off offset:2048
	s_nop 0
	global_load_dwordx2 v[30:31], v[30:31], off offset:2048
	s_nop 0
	global_load_dwordx2 v[32:33], v[32:33], off offset:2048
	s_nop 0
	global_load_dwordx2 v[34:35], v[34:35], off offset:2048
	s_nop 0
	global_load_dwordx2 v[36:37], v[38:39], off
	s_nop 0
	global_load_dwordx2 v[38:39], v[38:39], off offset:2048
	s_nop 0
	global_load_dwordx2 v[40:41], v[44:45], off offset:-4096
	global_load_dwordx2 v[42:43], v[44:45], off
	s_mov_b32 s0, 0xb000
	v_add_co_u32_e32 v62, vcc, s0, v58
	s_mov_b32 s0, 0xc000
	s_nop 0
	v_addc_co_u32_e32 v63, vcc, 0, v59, vcc
	v_add_co_u32_e32 v50, vcc, s0, v58
	s_mov_b32 s0, 0xd000
	s_nop 0
	v_addc_co_u32_e32 v51, vcc, 0, v59, vcc
	v_add_co_u32_e32 v64, vcc, s0, v58
	s_mov_b32 s0, 0xe000
	s_nop 0
	v_addc_co_u32_e32 v65, vcc, 0, v59, vcc
	v_add_co_u32_e32 v56, vcc, s0, v58
	s_mov_b32 s0, 0xf000
	s_nop 0
	v_addc_co_u32_e32 v57, vcc, 0, v59, vcc
	v_add_co_u32_e32 v66, vcc, s0, v58
	s_add_i32 s0, 0, 0x23f78
	s_cmp_lg_u32 s0, -1
	s_cselect_b32 s0, s0, 0
	global_load_dwordx2 v[44:45], v[44:45], off offset:2048
	s_nop 0
	global_load_dwordx2 v[46:47], v[50:51], off offset:-4096
	global_load_dwordx2 v[48:49], v[50:51], off
	s_nop 0
	global_load_dwordx2 v[50:51], v[50:51], off offset:2048
	s_nop 0
	global_load_dwordx2 v[52:53], v[56:57], off offset:-4096
	global_load_dwordx2 v[54:55], v[56:57], off
	s_nop 0
	global_load_dwordx2 v[56:57], v[56:57], off offset:2048
	v_addc_co_u32_e32 v67, vcc, 0, v59, vcc
	global_load_dwordx2 v[58:59], v[60:61], off offset:2048
	s_nop 0
	global_load_dwordx2 v[60:61], v[62:63], off offset:2048
	s_nop 0
	global_load_dwordx2 v[62:63], v[64:65], off offset:2048
	s_nop 0
	global_load_dwordx2 v[64:65], v[66:67], off
	s_cselect_b32 s1, s55, 0
	v_mov_b32_e32 v66, s0
	s_add_i32 s0, 0, 0x23f7c
	s_cmp_lg_u32 s0, -1
	v_mov_b32_e32 v67, s1
	s_cselect_b32 s0, s0, 0
	s_cselect_b32 s1, s55, 0
	ds_read_b32 v3, v66
	s_waitcnt vmcnt(0) lgkmcnt(0)
	v_mov_b32_e32 v66, s0
	v_mov_b32_e32 v67, s1
	ds_read_b32 v66, v66
	s_waitcnt vmcnt(0) lgkmcnt(0)
	v_lshlrev_b32_e32 v68, 1, v70
	v_lshl_add_u64 v[68:69], s[6:7], 0, v[68:69]
	v_mov_b32_e32 v70, 0
	v_lshl_add_u64 v[68:69], v[68:69], 0, s[80:81]
	v_mov_b32_e32 v74, v70
	v_mov_b32_e32 v75, v70
	v_mov_b32_e32 v76, v70
	v_mov_b32_e32 v77, v70
	v_mov_b32_e32 v78, v70
	v_mov_b32_e32 v79, v70
	v_mov_b32_e32 v80, v70
	v_mov_b32_e32 v81, v70
	v_mov_b32_e32 v82, v70
	v_mov_b32_e32 v83, v70
	v_mov_b32_e32 v84, v70
	v_mov_b32_e32 v85, v70
	v_mov_b32_e32 v86, v70
	v_mov_b32_e32 v87, v70
	v_mov_b32_e32 v88, v70
	v_mov_b32_e32 v89, v70
	v_mov_b32_e32 v90, v70
	v_mov_b32_e32 v91, v70
	v_mov_b32_e32 v92, v70
	v_mov_b32_e32 v93, v70
	v_mov_b32_e32 v94, v70
	v_mov_b32_e32 v95, v70
	v_mov_b32_e32 v96, v70
	v_mov_b32_e32 v97, v70
	v_mov_b32_e32 v98, v70
	v_mov_b32_e32 v99, v70
	v_mov_b32_e32 v100, v70
	v_mov_b32_e32 v101, v70
	v_mov_b32_e32 v102, v70
	v_mov_b32_e32 v103, v70
	v_mov_b32_e32 v104, v70
	v_mov_b32_e32 v105, v70
	v_mov_b32_e32 v106, v70
	v_mov_b32_e32 v107, v70
	v_mov_b32_e32 v108, v70
	v_mov_b32_e32 v109, v70
	v_mov_b32_e32 v110, v70
	v_mov_b32_e32 v111, v70
	v_mov_b32_e32 v112, v70
	v_mov_b32_e32 v113, v70
	v_mov_b32_e32 v114, v70
	v_mov_b32_e32 v115, v70
	v_mov_b32_e32 v116, v70
	v_mov_b32_e32 v117, v70
	v_mov_b32_e32 v118, v70
	v_mov_b32_e32 v119, v70
	v_mov_b32_e32 v120, v70
	v_mov_b32_e32 v121, v70
	v_mov_b32_e32 v122, v70
	v_mov_b32_e32 v123, v70
	v_mov_b32_e32 v124, v70
	v_mov_b32_e32 v125, v70
	v_mov_b32_e32 v126, v70
	v_mov_b32_e32 v127, v70
	v_mov_b32_e32 v128, v70
	v_mov_b32_e32 v129, v70
	v_mov_b32_e32 v134, v70
	v_mov_b32_e32 v135, v70
	s_waitcnt lgkmcnt(0)
	v_readfirstlane_b32 s0, v3
	v_lshlrev_b32_e32 v3, 5, v71
	v_add3_u32 v3, v136, v3, -15
	v_readfirstlane_b32 s1, v66
	v_mov_b32_e32 v71, v70
	s_nop 3
	global_load_dwordx2 v[66:67], v2, s[0:1]
	s_branch .LBB0_1036

.LBB0_1164:
	s_add_i32 s0, 0, 0x23f80
	s_cmp_lg_u32 s0, -1
	s_cselect_b32 s0, s0, 0
	s_cselect_b32 s1, s55, 0
	v_mov_b32_e32 v2, s0
	s_add_i32 s0, 0, 0x23f84
	s_cmp_lg_u32 s0, -1
	v_mov_b32_e32 v3, s1
	s_cselect_b32 s0, s0, 0
	s_waitcnt lgkmcnt(0)
	s_barrier
	ds_read_b32 v4, v2
	s_waitcnt vmcnt(0) lgkmcnt(0)
	s_cselect_b32 s1, s55, 0
	v_mov_b32_e32 v2, s0
	s_add_i32 s0, 0, 0x23f88
	s_cmp_lg_u32 s0, -1
	v_mov_b32_e32 v3, s1
	s_cselect_b32 s0, s0, 0
	ds_read_b32 v5, v2
	s_waitcnt vmcnt(0) lgkmcnt(0)
	s_cselect_b32 s1, s55, 0
	v_mov_b32_e32 v2, s0
	s_add_i32 s0, 0, 0x23f8c
	s_cmp_lg_u32 s0, -1
	v_mov_b32_e32 v3, s1
	s_cselect_b32 s0, s0, 0
	s_cselect_b32 s1, s55, 0
	ds_read_b32 v10, v2
	s_waitcnt vmcnt(0) lgkmcnt(0)
	v_mov_b32_e32 v2, s0
	v_mov_b32_e32 v3, s1
	ds_read_b32 v11, v2
	s_waitcnt vmcnt(0) lgkmcnt(0)
	v_lshlrev_b32_e32 v2, 2, v137
	v_and_b32_e32 v18, 0xfc, v2
	v_lshlrev_b32_e32 v14, 2, v18
	v_and_b32_e32 v19, 64, v230
	v_add_u32_e32 v19, 64, v19
	v_xor_b32_e32 v22, 1, v230
	v_cmp_lt_i32_e32 vcc, v22, v19
	v_ashrrev_i32_e32 v21, 3, v137
	v_and_b32_e32 v20, -8, v21
	v_cndmask_b32_e32 v22, v230, v22, vcc
	v_lshlrev_b32_e32 v30, 2, v22
	v_xor_b32_e32 v22, 2, v230
	v_cmp_lt_i32_e32 vcc, v22, v19
	v_add3_u32 v20, v136, v1, v20
	v_lshlrev_b32_e32 v1, 11, v21
	v_cndmask_b32_e32 v22, v230, v22, vcc
	v_lshlrev_b32_e32 v31, 2, v22
	v_xor_b32_e32 v22, 4, v230
	v_cmp_lt_i32_e32 vcc, v22, v19
	v_and_b32_e32 v21, 63, v137
	v_lshlrev_b32_e32 v18, 1, v18
	v_cndmask_b32_e32 v22, v230, v22, vcc
	v_lshlrev_b32_e32 v32, 2, v22
	v_xor_b32_e32 v22, 8, v230
	v_cmp_lt_i32_e32 vcc, v22, v19
	v_lshlrev_b32_e32 v21, 4, v21
	s_waitcnt lgkmcnt(0)
	v_readfirstlane_b32 s0, v4
	v_cndmask_b32_e32 v22, v230, v22, vcc
	v_lshlrev_b32_e32 v33, 2, v22
	v_xor_b32_e32 v22, 16, v230
	v_cmp_lt_i32_e32 vcc, v22, v19
	v_readfirstlane_b32 s1, v5
	s_nop 4
	global_load_dwordx4 v[2:5], v14, s[0:1]
	global_load_dwordx4 v[6:9], v14, s[0:1] offset:1024
	v_cndmask_b32_e32 v22, v230, v22, vcc
	v_lshlrev_b32_e32 v34, 2, v22
	v_xor_b32_e32 v22, 32, v230
	v_cmp_lt_i32_e32 vcc, v22, v19
	v_readfirstlane_b32 s0, v10
	s_nop 0
	v_cndmask_b32_e32 v19, v230, v22, vcc
	v_lshlrev_b32_e32 v35, 2, v19
	v_readfirstlane_b32 s1, v11
	s_nop 4
	global_load_dwordx4 v[10:13], v14, s[0:1]
	s_nop 0
	global_load_dwordx4 v[14:17], v14, s[0:1] offset:1024
	v_mov_b32_e32 v19, v0
	s_movk_i32 s1, 0xc000
	v_lshl_add_u64 v[18:19], s[6:7], 0, v[18:19]
	s_mov_b64 s[6:7], 0xa700000
	v_and_or_b32 v1, v1, s1, v21
	s_mov_b32 s0, 0
	v_lshl_add_u64 v[18:19], v[18:19], 0, s[6:7]
	v_add_u32_e32 v1, 0, v1
	s_waitcnt vmcnt(0)

.LBB0_1180:
	s_or_b64 exec, exec, s[0:1]
	s_cmp_lg_u32 s57, -1
	s_cselect_b32 s0, s57, 0
	s_cselect_b32 s1, s55, 0
	s_cmp_lg_u32 s58, -1
	v_and_b32_e32 v24, 1, v4
	v_mov_b64_e32 v[4:5], s[0:1]
	s_cselect_b32 s0, s58, 0
	s_cselect_b32 s1, s55, 0
	v_mov_b32_e32 v28, v224
	v_mov_b64_e32 v[6:7], s[0:1]
	ds_read_b32 v8, v4
	s_waitcnt vmcnt(0) lgkmcnt(0)
	ds_read_b32 v9, v6
	s_waitcnt vmcnt(0) lgkmcnt(0)
	ds_read_b32 v10, v4
	s_waitcnt vmcnt(0) lgkmcnt(0)
	ds_read_b32 v11, v6
	s_waitcnt vmcnt(0) lgkmcnt(0)
	v_lshlrev_b32_e32 v2, 1, v2
	v_and_b32_e32 v2, 2, v2
	ds_read_b32 v122, v4
	s_waitcnt vmcnt(0) lgkmcnt(0)
	ds_read_b32 v123, v6
	s_waitcnt vmcnt(0) lgkmcnt(0)
	v_ashrrev_i32_e32 v4, 8, v28
	v_lshl_or_b32 v2, v24, 2, v2
	v_add_u32_e32 v20, v2, v4
	v_bfe_u32 v42, v28, 6, 2
	v_lshlrev_b32_e32 v100, 6, v20
	v_and_b32_e32 v36, 15, v28
	v_bfe_u32 v37, v28, 4, 2
	v_lshlrev_b32_e32 v2, 5, v42
	v_ashrrev_i32_e32 v101, 31, v100
	v_add3_u32 v102, v36, v3, v2
	v_lshlrev_b32_e32 v2, 4, v37
	v_mov_b32_e32 v3, v0
	s_mov_b64 s[4:5], 0x8d00000
	v_add_u32_e32 v104, 16, v102
	v_ashrrev_i32_e32 v103, 31, v102
	v_ashrrev_i32_e32 v105, 31, v104
	v_lshlrev_b64 v[14:15], 10, v[104:105]
	v_and_b32_e32 v124, 0x7f, v28
	v_ashrrev_i32_e32 v125, 3, v28
	v_mov_b32_e32 v39, v0
	v_add_u32_e32 v40, 0, v2
	v_lshlrev_b32_e32 v127, 2, v37
	v_lshlrev_b32_e32 v41, 3, v37
	v_sub_u32_e32 v41, v40, v41
	v_mul_u32_u24_e32 v45, 0x110, v36
	v_mul_u32_u24_e32 v46, 0x90, v36
	v_add_u32_e32 v202, v40, v46
	v_add_u32_e32 v203, v41, v45
	s_mov_b32 s20, 0
	v_mov_b32_e32 v197, 1.0
	s_mov_b64 s[16:17], 0
	v_mov_b32_e32 v205, 1.0
	s_waitcnt lgkmcnt(0)
	v_readfirstlane_b32 s0, v8
	v_readfirstlane_b32 s1, v9
	s_nop 0
	v_mov_b32_e32 v8, s0
	v_readfirstlane_b32 s0, v10
	v_mov_b32_e32 v9, s1
	v_lshl_add_u64 v[4:5], v[100:101], 1, v[8:9]
	v_readfirstlane_b32 s1, v11
	v_lshl_add_u64 v[4:5], v[4:5], 0, v[2:3]
	s_add_u32 s0, s0, 0x9e00000
	v_lshl_add_u64 v[12:13], v[4:5], 0, s[4:5]
	s_addc_u32 s1, s1, 0
	s_add_i32 s4, 0, 0x23f90
	s_cmp_lg_u32 s4, -1
	s_cselect_b32 s4, s4, 0
	s_cselect_b32 s5, s55, 0
	v_mov_b32_e32 v22, s4
	s_add_i32 s4, 0, 0x23f94
	v_lshlrev_b64 v[4:5], 10, v[102:103]
	s_cmp_lg_u32 s4, -1
	v_lshl_add_u64 v[8:9], v[12:13], 0, v[4:5]
	v_lshl_add_u64 v[16:17], v[12:13], 0, v[14:15]
	v_mov_b32_e32 v23, s5
	s_cselect_b32 s4, s4, 0
	s_cselect_b32 s5, s55, 0
	global_load_dwordx4 v[4:7], v[8:9], off
	s_nop 0
	global_load_dwordx4 v[8:11], v[8:9], off offset:64
	s_nop 0
	global_load_dwordx4 v[12:15], v[16:17], off
	s_nop 0
	global_load_dwordx4 v[16:19], v[16:17], off offset:64
	v_xor_b32_e32 v2, 16, v230
	ds_read_b32 v3, v22
	s_waitcnt vmcnt(0) lgkmcnt(0)
	v_mov_b32_e32 v22, s4
	v_mov_b32_e32 v23, s5
	ds_read_b32 v21, v22
	s_waitcnt vmcnt(0) lgkmcnt(0)
	v_readfirstlane_b32 s4, v3
	s_nop 1
	v_mov_b32_e32 v22, s4
	v_readfirstlane_b32 s5, v21
	v_ashrrev_i32_e32 v21, 31, v20
	s_nop 0
	v_mov_b32_e32 v23, s5
	v_lshl_add_u64 v[20:21], v[20:21], 2, v[22:23]
	global_load_dword v3, v[20:21], off
	v_add_u32_e32 v22, v124, v1
	v_ashrrev_i32_e32 v23, 31, v22
	v_lshlrev_b64 v[22:23], 9, v[22:23]
	v_lshlrev_b32_e32 v20, 7, v24
	v_mov_b32_e32 v21, v0
	v_lshl_add_u64 v[22:23], s[0:1], 0, v[22:23]
	v_lshl_add_u64 v[106:107], s[0:1], 0, v[20:21]
	v_lshl_add_u64 v[32:33], v[22:23], 0, v[20:21]
	v_add_u32_e32 v20, v125, v1
	v_ashrrev_i32_e32 v21, 31, v20
	v_lshlrev_b64 v[20:21], 9, v[20:21]
	s_movk_i32 s0, 0x90
	s_movk_i32 s1, 0x110
	v_mul_lo_u32 v37, v125, s0
	s_waitcnt vmcnt(0)
	v_mul_f32_e32 v196, 0x3fb8aa3b, v3
	v_lshlrev_b32_e32 v3, 4, v28
	v_and_b32_e32 v38, 0x70, v3
	v_ashrrev_i32_e32 v3, 4, v28
	v_and_b32_e32 v110, -8, v3
	v_add_u32_e32 v3, 0x200, v28
	v_ashrrev_i32_e32 v126, 3, v3
	v_add_u32_e32 v28, v126, v1
	v_ashrrev_i32_e32 v1, 4, v3
	v_ashrrev_i32_e32 v29, 31, v28
	v_and_b32_e32 v112, -8, v1
	v_lshl_add_u64 v[108:109], v[106:107], 0, v[38:39]
	v_ashrrev_i32_e32 v111, 31, v110
	v_lshlrev_b64 v[28:29], 9, v[28:29]
	v_ashrrev_i32_e32 v113, 31, v112
	v_lshl_add_u64 v[20:21], v[108:109], 0, v[20:21]
	v_lshl_add_u64 v[24:25], v[110:111], 1, v[32:33]
	v_lshl_add_u64 v[28:29], v[108:109], 0, v[28:29]
	v_lshl_add_u64 v[32:33], v[112:113], 1, v[32:33]
	global_load_dwordx4 v[20:23], v[20:21], off
	v_and_b32_e32 v3, 64, v230
	global_load_dwordx4 v[24:27], v[24:25], off offset:256
	v_add_u32_e32 v3, 64, v3
	global_load_dwordx4 v[28:31], v[28:29], off
	v_cmp_lt_i32_e32 vcc, v2, v3
	global_load_dwordx4 v[32:35], v[32:33], off offset:256
	v_mul_i32_i24_e32 v1, 0xffffffe0, v42
	v_cndmask_b32_e32 v2, v230, v2, vcc
	v_lshlrev_b32_e32 v128, 2, v2
	v_xor_b32_e32 v2, 32, v230
	v_cmp_lt_i32_e32 vcc, v2, v3
	v_or_b32_e32 v1, v1, v127
	v_add_u32_e32 v38, 0, v38
	v_cndmask_b32_e32 v2, v230, v2, vcc
	v_lshlrev_b32_e32 v129, 2, v2
	v_or_b32_e32 v2, 16, v36
	v_lshl_add_u32 v39, v124, 1, 0
	v_mul_lo_u32 v42, v110, s1
	v_mul_lo_u32 v43, v126, s0
	v_mul_lo_u32 v44, v112, s1
	v_sub_u32_e32 v130, v1, v36
	v_mul_u32_u24_e32 v36, 0x110, v2
	v_sub_u32_e32 v164, v1, v2
	v_mov_b32_e32 v2, v0
	v_mov_b32_e32 v3, v0
	v_mov_b32_e32 v1, v0
	v_add_u32_e32 v198, v38, v37
	v_add_u32_e32 v199, v39, v42
	v_add_u32_e32 v200, v38, v43
	v_add_u32_e32 v201, v39, v44
	v_add_u32_e32 v204, v41, v36
	v_mov_b64_e32 v[38:39], v[2:3]
	v_mov_b64_e32 v[42:43], v[2:3]
	v_mov_b64_e32 v[46:47], v[2:3]
	v_mov_b64_e32 v[50:51], v[2:3]
	v_mov_b64_e32 v[54:55], v[2:3]
	v_mov_b64_e32 v[58:59], v[2:3]
	v_mov_b64_e32 v[62:63], v[2:3]
	v_mov_b64_e32 v[66:67], v[2:3]
	v_add_u32_e32 v131, 1, v130
	v_add_u32_e32 v132, 2, v130
	v_add_u32_e32 v133, 3, v130
	v_add_u32_e32 v134, 16, v130
	v_add_u32_e32 v135, 17, v130
	v_add_u32_e32 v136, 18, v130
	v_add_u32_e32 v137, 19, v130
	v_add_u32_e32 v138, 32, v130
	v_add_u32_e32 v139, 33, v130
	v_add_u32_e32 v140, 34, v130
	v_add_u32_e32 v141, 35, v130
	v_add_u32_e32 v142, 48, v130
	v_add_u32_e32 v143, 49, v130
	v_add_u32_e32 v144, 50, v130
	v_add_u32_e32 v145, 51, v130
	v_add_u32_e32 v148, 64, v130
	v_add_u32_e32 v149, 0x41, v130
	v_add_u32_e32 v150, 0x42, v130
	v_add_u32_e32 v151, 0x43, v130
	v_add_u32_e32 v152, 0x50, v130
	v_add_u32_e32 v153, 0x51, v130
	v_add_u32_e32 v154, 0x52, v130
	v_add_u32_e32 v155, 0x53, v130
	v_add_u32_e32 v156, 0x60, v130
	v_add_u32_e32 v157, 0x61, v130
	v_add_u32_e32 v158, 0x62, v130
	v_add_u32_e32 v159, 0x63, v130
	v_add_u32_e32 v160, 0x70, v130
	v_add_u32_e32 v161, 0x71, v130
	v_add_u32_e32 v162, 0x72, v130
	v_add_u32_e32 v163, 0x73, v130
	v_add_u32_e32 v165, 1, v164
	v_add_u32_e32 v166, 2, v164
	v_add_u32_e32 v167, 3, v164
	v_add_u32_e32 v168, 16, v164
	v_add_u32_e32 v169, 17, v164
	v_add_u32_e32 v170, 18, v164
	v_add_u32_e32 v171, 19, v164
	v_add_u32_e32 v172, 32, v164
	v_add_u32_e32 v173, 33, v164
	v_add_u32_e32 v174, 34, v164
	v_add_u32_e32 v175, 35, v164
	v_add_u32_e32 v176, 48, v164
	v_add_u32_e32 v177, 49, v164
	v_add_u32_e32 v178, 50, v164
	v_add_u32_e32 v179, 51, v164
	v_add_u32_e32 v180, 64, v164
	v_add_u32_e32 v181, 0x41, v164
	v_add_u32_e32 v182, 0x42, v164
	v_add_u32_e32 v183, 0x43, v164
	v_add_u32_e32 v184, 0x50, v164
	v_add_u32_e32 v185, 0x51, v164
	v_add_u32_e32 v186, 0x52, v164
	v_add_u32_e32 v187, 0x53, v164
	v_add_u32_e32 v188, 0x60, v164
	v_add_u32_e32 v189, 0x61, v164
	v_add_u32_e32 v190, 0x62, v164
	v_add_u32_e32 v191, 0x63, v164
	v_add_u32_e32 v192, 0x70, v164
	v_add_u32_e32 v193, 0x71, v164
	v_add_u32_e32 v194, 0x72, v164
	v_add_u32_e32 v195, 0x73, v164
	v_mov_b32_e32 v206, v196
	v_mov_b64_e32 v[36:37], v[0:1]
	v_mov_b64_e32 v[40:41], v[0:1]
	v_mov_b64_e32 v[44:45], v[0:1]
	v_mov_b64_e32 v[48:49], v[0:1]
	v_mov_b64_e32 v[52:53], v[0:1]
	v_mov_b64_e32 v[56:57], v[0:1]
	v_mov_b64_e32 v[60:61], v[0:1]
	v_mov_b64_e32 v[64:65], v[0:1]
	s_branch .LBB0_1182

.LBB0_1192:
	s_or_b64 exec, exec, s[10:11]
	s_cmp_lg_u32 s57, -1
	s_cselect_b32 s0, s57, 0
	s_cselect_b32 s1, s55, 0
	s_cmp_lg_u32 s58, -1
	v_mov_b32_e32 v2, s0
	v_mov_b32_e32 v3, s1
	s_cselect_b32 s0, s58, 0
	s_cselect_b32 s1, s55, 0
	ds_read_b32 v1, v2
	s_waitcnt vmcnt(0) lgkmcnt(0)
	v_mov_b32_e32 v2, s0
	v_mov_b32_e32 v3, s1
	ds_read_b32 v2, v2
	s_waitcnt vmcnt(0) lgkmcnt(0)
	s_getreg_b32 s6, hwreg(HW_REG_XCC_ID, 0, 4)
	s_waitcnt vmcnt(0)
	s_waitcnt lgkmcnt(0)
	s_barrier
	v_readfirstlane_b32 s4, v1
	v_readfirstlane_b32 s5, v2
	s_and_saveexec_b64 s[0:1], s[78:79]
	s_cbranch_execz .LBB0_1244
	v_readlane_b32 s7, v253, 59
	s_waitcnt vmcnt(0) expcnt(0) lgkmcnt(0)
	s_and_b32 s33, s6, 15
	v_mov_b32_e32 v1, s7
	ds_read_b32 v3, v1
	v_readlane_b32 s7, v253, 60
	s_waitcnt lgkmcnt(0)
	v_cmp_ne_u32_e32 vcc, 0, v3
	v_mov_b32_e32 v1, s7
	ds_read_b32 v2, v1
	s_cbranch_vccnz .LBB0_1208
	s_add_u32 s6, s4, 0x3c0200
	s_addc_u32 s7, s5, 0
	s_add_u32 s8, s4, 0x3c0400
	s_addc_u32 s9, s5, 0
	s_add_u32 s10, s4, 0x3c0500
	s_addc_u32 s11, s5, 0
	s_add_u32 s12, s4, 0x3c0600
	s_addc_u32 s13, s5, 0
	s_add_u32 s14, s4, 0x3c0700
	s_addc_u32 s15, s5, 0
	s_add_u32 s16, s4, 0x3c0800
	s_addc_u32 s17, s5, 0
	s_add_u32 s18, s4, 0x3c0900
	s_addc_u32 s19, s5, 0
	s_add_u32 s20, s4, 0x3c0a00
	s_addc_u32 s21, s5, 0
	s_add_u32 s22, s4, 0x3c0b00
	s_addc_u32 s23, s5, 0
	s_add_u32 s24, s4, 0x3c0c00
	s_addc_u32 s25, s5, 0
	s_add_u32 s26, s4, 0x3c0d00
	s_addc_u32 s27, s5, 0
	s_add_u32 s28, s4, 0x3c0e00
	s_addc_u32 s29, s5, 0
	s_add_u32 s30, s4, 0x3c0f00
	s_addc_u32 s31, s5, 0
	s_add_u32 s34, s4, 0x3c1000
	s_addc_u32 s35, s5, 0
	s_add_u32 s36, s4, 0x3c1100
	s_addc_u32 s37, s5, 0
	s_add_u32 s38, s4, 0x3c1200
	s_addc_u32 s39, s5, 0
	s_add_u32 s40, s4, 0x3c1300
	s_addc_u32 s41, s5, 0
	s_mov_b32 s48, 1
	s_branch .LBB0_1196

.LBB0_1245:
	s_cmp_lg_u32 s57, -1
	s_cselect_b32 s4, s57, 0
	s_cselect_b32 s5, s55, 0
	s_cmp_lg_u32 s58, -1
	v_mov_b32_e32 v2, s4
	v_mov_b32_e32 v3, s5
	s_cselect_b32 s4, s58, 0
	s_cselect_b32 s5, s55, 0
	ds_read_b32 v1, v2
	s_waitcnt vmcnt(0) lgkmcnt(0)
	v_mov_b32_e32 v2, s4
	v_mov_b32_e32 v3, s5
	ds_read_b32 v2, v2
	s_waitcnt vmcnt(0) lgkmcnt(0)
	v_readlane_b32 s4, v254, 24
	s_cmp_lg_u32 s4, -1
	s_cselect_b32 s4, s4, 0
	s_cselect_b32 s5, s55, 0
	v_mov_b32_e32 v3, s5
	s_waitcnt lgkmcnt(0)
	v_readfirstlane_b32 s16, v1
	v_readfirstlane_b32 s17, v2
	v_mov_b32_e32 v2, s4
	v_readlane_b32 s4, v254, 25
	s_cmp_lg_u32 s4, -1
	s_cselect_b32 s4, s4, 0
	s_cselect_b32 s5, s55, 0
	ds_read_b32 v1, v2
	s_waitcnt vmcnt(0) lgkmcnt(0)
	v_mov_b32_e32 v2, s4
	v_mov_b32_e32 v3, s5
	ds_read_b32 v2, v2
	s_waitcnt vmcnt(0) lgkmcnt(0)
	s_add_i32 s50, 0, 0x23f50
	s_cmp_lg_u32 s50, -1
	s_cselect_b32 s4, s50, 0
	s_cselect_b32 s5, s55, 0
	s_add_i32 s51, 0, 0x23f54
	s_cmp_lg_u32 s51, -1
	v_mov_b32_e32 v3, s5
	s_cselect_b32 s5, s55, 0
	s_waitcnt lgkmcnt(0)
	v_readfirstlane_b32 s33, v1
	v_readfirstlane_b32 s46, v2
	v_mov_b32_e32 v2, s4
	s_cselect_b32 s4, s51, 0
	ds_read_b32 v1, v2
	s_waitcnt vmcnt(0) lgkmcnt(0)
	v_mov_b32_e32 v2, s4
	v_mov_b32_e32 v3, s5
	ds_read_b32 v2, v2
	s_waitcnt vmcnt(0) lgkmcnt(0)
	v_readlane_b32 s4, v254, 2
	s_cmp_lt_i32 s75, s4
	s_cselect_b64 s[12:13], -1, 0
	s_cmp_ge_i32 s75, s4
	v_readlane_b32 s5, v254, 3
	s_waitcnt lgkmcnt(0)
	v_readfirstlane_b32 s8, v1
	v_mov_b32_e32 v1, v224
	v_readfirstlane_b32 s9, v2
	v_readfirstlane_b32 s18, v1
	s_cbranch_scc1 .LBB0_1248
	v_readlane_b32 s4, v254, 34
	v_readlane_b32 s5, v254, 35
	s_and_b64 vcc, exec, s[4:5]
	v_readlane_b32 s4, v253, 25
	v_readlane_b32 s5, v253, 27
	s_mov_b32 s74, 4
	s_mov_b32 s6, s4
	v_readlane_b32 s4, v253, 26
	s_mov_b32 s30, s5
	s_cbranch_vccnz .LBB0_1248
	s_mov_b32 s74, 16
	s_mov_b32 s30, 0
	v_readlane_b32 s6, v253, 32
	v_readlane_b32 s4, v253, 31
	v_readlane_b32 s7, v253, 33

.LBB0_1365:
	s_cmp_lg_u32 s57, -1
	s_cselect_b32 s0, s57, 0
	s_cselect_b32 s1, s55, 0
	s_cmp_lg_u32 s58, -1
	v_mov_b32_e32 v2, s0
	s_waitcnt lgkmcnt(0)
	v_mov_b32_e32 v3, s1
	s_cselect_b32 s0, s58, 0
	s_cselect_b32 s1, s55, 0
	ds_read_b32 v1, v2
	s_waitcnt vmcnt(0) lgkmcnt(0)
	v_mov_b32_e32 v2, s0
	v_mov_b32_e32 v3, s1
	ds_read_b32 v2, v2
	s_waitcnt vmcnt(0) lgkmcnt(0)
	s_getreg_b32 s6, hwreg(HW_REG_XCC_ID, 0, 4)
	s_waitcnt vmcnt(0)
	s_waitcnt lgkmcnt(0)
	s_barrier
	v_readfirstlane_b32 s4, v1
	v_readfirstlane_b32 s5, v2
	s_and_saveexec_b64 s[0:1], s[78:79]
	s_cbranch_execz .LBB0_1417
	v_readlane_b32 s7, v253, 59
	s_waitcnt vmcnt(0) expcnt(0) lgkmcnt(0)
	s_and_b32 s33, s6, 15
	v_mov_b32_e32 v1, s7
	ds_read_b32 v3, v1
	v_readlane_b32 s7, v253, 60
	s_waitcnt lgkmcnt(0)
	v_cmp_ne_u32_e32 vcc, 0, v3
	v_mov_b32_e32 v1, s7
	ds_read_b32 v2, v1
	s_cbranch_vccnz .LBB0_1381
	s_add_u32 s6, s4, 0x3c0200
	s_addc_u32 s7, s5, 0
	s_add_u32 s8, s4, 0x3c0400
	s_addc_u32 s9, s5, 0
	s_add_u32 s10, s4, 0x3c0500
	s_addc_u32 s11, s5, 0
	s_add_u32 s12, s4, 0x3c0600
	s_addc_u32 s13, s5, 0
	s_add_u32 s14, s4, 0x3c0700
	s_addc_u32 s15, s5, 0
	s_add_u32 s16, s4, 0x3c0800
	s_addc_u32 s17, s5, 0
	s_add_u32 s18, s4, 0x3c0900
	s_addc_u32 s19, s5, 0
	s_add_u32 s20, s4, 0x3c0a00
	s_addc_u32 s21, s5, 0
	s_add_u32 s22, s4, 0x3c0b00
	s_addc_u32 s23, s5, 0
	s_add_u32 s24, s4, 0x3c0c00
	s_addc_u32 s25, s5, 0
	s_add_u32 s26, s4, 0x3c0d00
	s_addc_u32 s27, s5, 0
	s_add_u32 s28, s4, 0x3c0e00
	s_addc_u32 s29, s5, 0
	s_add_u32 s30, s4, 0x3c0f00
	s_addc_u32 s31, s5, 0
	s_add_u32 s34, s4, 0x3c1000
	s_addc_u32 s35, s5, 0
	s_add_u32 s36, s4, 0x3c1100
	s_addc_u32 s37, s5, 0
	s_add_u32 s38, s4, 0x3c1200
	s_addc_u32 s39, s5, 0
	s_add_u32 s40, s4, 0x3c1300
	s_addc_u32 s41, s5, 0
	s_mov_b32 s54, 1
	s_branch .LBB0_1369

.LBB0_1417:
	s_or_b64 exec, exec, s[0:1]
	v_readlane_b32 s0, v254, 28
	s_mul_i32 s33, s0, 3
	v_readlane_b32 s0, v254, 30
	v_readlane_b32 s1, v254, 31
	s_add_i32 s33, s33, 2
	s_and_b64 vcc, exec, s[0:1]
	s_movk_i32 s10, 0x100
	s_waitcnt lgkmcnt(0)
	s_barrier
	s_cbranch_vccnz .LBB0_1476
	s_cmp_lg_u32 s57, -1
	s_cselect_b32 s0, s57, 0
	s_cselect_b32 s1, s55, 0
	s_cmp_lg_u32 s58, -1
	v_mov_b64_e32 v[4:5], s[0:1]
	s_cselect_b32 s0, s58, 0
	s_cselect_b32 s1, s55, 0
	v_mov_b64_e32 v[6:7], s[0:1]
	ds_read_b32 v1, v4
	s_waitcnt vmcnt(0) lgkmcnt(0)
	ds_read_b32 v2, v6
	s_waitcnt vmcnt(0) lgkmcnt(0)
	s_cmp_lg_u32 s50, -1
	s_cselect_b32 s0, s50, 0
	s_cselect_b32 s1, s55, 0
	v_mov_b32_e32 v3, s1
	s_cmp_lg_u32 s51, -1
	s_cselect_b32 s1, s55, 0
	v_readlane_b32 s4, v253, 6
	s_waitcnt lgkmcnt(0)
	v_readfirstlane_b32 s6, v1
	v_readfirstlane_b32 s7, v2
	v_mov_b32_e32 v2, s0
	ds_read_b32 v1, v2
	s_waitcnt vmcnt(0) lgkmcnt(0)
	s_cselect_b32 s0, s51, 0
	v_mov_b32_e32 v2, s0
	v_mov_b32_e32 v3, s1
	ds_read_b32 v2, v2
	s_waitcnt vmcnt(0) lgkmcnt(0)
	v_readfirstlane_b32 s0, v1
	v_mov_b32_e32 v1, v224
	ds_read_b32 v3, v4
	s_waitcnt vmcnt(0) lgkmcnt(0)
	ds_read_b32 v4, v6
	s_waitcnt vmcnt(0) lgkmcnt(0)
	v_readfirstlane_b32 s1, v2
	v_ashrrev_i32_e32 v2, 6, v1
	v_add_u32_e32 v2, s4, v2
	s_movk_i32 s4, 0x400
	v_cmp_gt_i32_e32 vcc, s4, v2
	s_waitcnt lgkmcnt(0)
	v_readfirstlane_b32 s8, v3
	v_readfirstlane_b32 s9, v4
	s_and_saveexec_b64 s[4:5], vcc
	s_cbranch_execz .LBB0_1423
	v_and_b32_e32 v3, 63, v1
	v_and_b32_e32 v1, 64, v230
	v_add_u32_e32 v4, 64, v1
	v_xor_b32_e32 v1, 1, v230
	v_cmp_lt_i32_e32 vcc, v1, v4
	v_xor_b32_e32 v5, 2, v230
	v_readlane_b32 s10, v254, 36
	v_cndmask_b32_e32 v1, v230, v1, vcc
	v_cmp_lt_i32_e32 vcc, v5, v4
	v_readlane_b32 s11, v254, 37
	s_lshl_b64 s[10:11], s[10:11], 2
	v_cndmask_b32_e32 v5, v230, v5, vcc
	v_lshlrev_b32_e32 v46, 2, v5
	v_xor_b32_e32 v5, 4, v230
	v_cmp_lt_i32_e32 vcc, v5, v4
	s_add_u32 s10, s0, s10
	s_addc_u32 s11, s1, s11
	v_cndmask_b32_e32 v5, v230, v5, vcc
	v_lshlrev_b32_e32 v47, 2, v5
	v_xor_b32_e32 v5, 8, v230
	v_cmp_lt_i32_e32 vcc, v5, v4
	s_add_u32 s0, s8, s53
	s_addc_u32 s1, s9, 0
	v_cndmask_b32_e32 v5, v230, v5, vcc
	v_lshlrev_b32_e32 v48, 2, v5
	v_xor_b32_e32 v5, 16, v230
	v_cmp_lt_i32_e32 vcc, v5, v4
	s_add_u32 s12, s0, 0x24000
	s_addc_u32 s13, s1, 0
	v_cndmask_b32_e32 v5, v230, v5, vcc
	v_lshlrev_b32_e32 v49, 2, v5
	v_xor_b32_e32 v5, 32, v230
	v_cmp_lt_i32_e32 vcc, v5, v4
	s_add_u32 s0, s8, s52
	v_lshlrev_b32_e32 v24, 3, v3
	v_cndmask_b32_e32 v4, v230, v5, vcc
	v_lshlrev_b32_e32 v50, 2, v4
	v_lshlrev_b32_e32 v4, 4, v3
	v_mov_b32_e32 v5, v0
	v_mov_b32_e32 v25, v0
	s_addc_u32 s1, s9, 0
	v_lshl_add_u64 v[8:9], s[10:11], 0, v[4:5]
	v_lshl_add_u64 v[24:25], s[8:9], 0, v[24:25]
	s_mov_b64 s[10:11], 0x5a00000
	s_add_u32 s14, s0, 0x24000
	v_lshl_add_u64 v[24:25], v[24:25], 0, s[10:11]
	v_readlane_b32 s10, v254, 28
	s_addc_u32 s15, s1, 0
	s_mul_hi_u32 s11, s10, 0x33000
	v_readlane_b32 s10, v254, 26
	s_add_u32 s10, s8, s10
	v_cmp_eq_u32_e64 s[0:1], 0, v3
	v_ashrrev_i32_e32 v3, 31, v2
	s_addc_u32 s11, s9, s11
	v_or_b32_e32 v14, 0x400, v4
	v_mov_b32_e32 v15, v0
	v_or_b32_e32 v18, 0x800, v4
	v_mov_b32_e32 v19, v0
	v_or_b32_e32 v22, 0xc00, v4
	v_mov_b32_e32 v23, v0
	v_lshl_add_u64 v[26:27], v[2:3], 2, s[10:11]
	s_mov_b64 s[10:11], 0x1b2000
	v_lshlrev_b64 v[30:31], 12, v[2:3]
	v_lshlrev_b32_e32 v1, 2, v1
	v_lshl_add_u64 v[6:7], s[14:15], 0, v[4:5]
	v_lshl_add_u64 v[10:11], s[12:13], 0, v[4:5]
	v_lshl_add_u64 v[12:13], s[14:15], 0, v[14:15]
	v_lshl_add_u64 v[14:15], s[12:13], 0, v[14:15]
	v_lshl_add_u64 v[16:17], s[14:15], 0, v[18:19]
	v_lshl_add_u64 v[18:19], s[12:13], 0, v[18:19]
	v_lshl_add_u64 v[20:21], s[14:15], 0, v[22:23]
	v_lshl_add_u64 v[22:23], s[12:13], 0, v[22:23]
	v_lshl_add_u64 v[26:27], v[26:27], 0, s[10:11]
	v_lshl_add_u64 v[28:29], s[8:9], 0, v[30:31]
	v_lshl_add_u64 v[30:31], s[6:7], 0, v[30:31]
	s_mov_b64 s[6:7], 0
	s_branch .LBB0_1421

.LBB0_1423:
	s_or_b64 exec, exec, s[4:5]
	s_cmp_lg_u32 s57, -1
	s_cselect_b32 s0, s57, 0
	s_cselect_b32 s1, s55, 0
	s_cmp_lg_u32 s58, -1
	v_mov_b32_e32 v2, s0
	v_mov_b32_e32 v3, s1
	s_cselect_b32 s0, s58, 0
	s_cselect_b32 s1, s55, 0
	ds_read_b32 v1, v2
	s_waitcnt vmcnt(0) lgkmcnt(0)
	v_mov_b32_e32 v2, s0
	v_mov_b32_e32 v3, s1
	ds_read_b32 v2, v2
	s_waitcnt vmcnt(0) lgkmcnt(0)
	s_getreg_b32 s6, hwreg(HW_REG_XCC_ID, 0, 4)
	s_waitcnt vmcnt(0)
	s_waitcnt lgkmcnt(0)
	s_barrier
	v_readfirstlane_b32 s4, v1
	v_readfirstlane_b32 s5, v2
	s_and_saveexec_b64 s[0:1], s[78:79]
	s_cbranch_execz .LBB0_1475
	v_readlane_b32 s7, v253, 59
	s_waitcnt vmcnt(0) expcnt(0) lgkmcnt(0)
	s_and_b32 s50, s6, 15
	v_mov_b32_e32 v1, s7
	ds_read_b32 v3, v1
	v_readlane_b32 s7, v253, 60
	s_waitcnt lgkmcnt(0)
	v_cmp_ne_u32_e32 vcc, 0, v3
	v_mov_b32_e32 v1, s7
	ds_read_b32 v2, v1
	s_cbranch_vccnz .LBB0_1439
	s_add_u32 s6, s4, 0x3c0200
	s_addc_u32 s7, s5, 0
	s_add_u32 s8, s4, 0x3c0400
	s_addc_u32 s9, s5, 0
	s_add_u32 s10, s4, 0x3c0500
	s_addc_u32 s11, s5, 0
	s_add_u32 s12, s4, 0x3c0600
	s_addc_u32 s13, s5, 0
	s_add_u32 s14, s4, 0x3c0700
	s_addc_u32 s15, s5, 0
	s_add_u32 s16, s4, 0x3c0800
	s_addc_u32 s17, s5, 0
	s_add_u32 s18, s4, 0x3c0900
	s_addc_u32 s19, s5, 0
	s_add_u32 s20, s4, 0x3c0a00
	s_addc_u32 s21, s5, 0
	s_add_u32 s22, s4, 0x3c0b00
	s_addc_u32 s23, s5, 0
	s_add_u32 s24, s4, 0x3c0c00
	s_addc_u32 s25, s5, 0
	s_add_u32 s26, s4, 0x3c0d00
	s_addc_u32 s27, s5, 0
	s_add_u32 s28, s4, 0x3c0e00
	s_addc_u32 s29, s5, 0
	s_add_u32 s30, s4, 0x3c0f00
	s_addc_u32 s31, s5, 0
	s_add_u32 s34, s4, 0x3c1000
	s_addc_u32 s35, s5, 0
	s_add_u32 s36, s4, 0x3c1100
	s_addc_u32 s37, s5, 0
	s_add_u32 s38, s4, 0x3c1200
	s_addc_u32 s39, s5, 0
	s_add_u32 s40, s4, 0x3c1300
	s_addc_u32 s41, s5, 0
	s_mov_b32 s51, 1
	s_branch .LBB0_1427

.LBB0_1476:
	s_cmp_lg_u32 s57, -1
	s_cselect_b32 s0, s57, 0
	s_cselect_b32 s1, s55, 0
	s_cmp_lg_u32 s58, -1
	v_mov_b32_e32 v2, s0
	v_mov_b32_e32 v3, s1
	s_cselect_b32 s0, s58, 0
	s_cselect_b32 s1, s55, 0
	ds_read_b32 v1, v2
	s_waitcnt vmcnt(0) lgkmcnt(0)
	v_mov_b32_e32 v2, s0
	v_mov_b32_e32 v3, s1
	ds_read_b32 v2, v2
	s_waitcnt vmcnt(0) lgkmcnt(0)
	v_readlane_b32 s0, v254, 2
	v_readlane_b32 s1, v254, 3
	s_mul_i32 s0, s48, 22
	v_readlane_b32 s4, v254, 27
	v_mov_b32_e32 v16, v224
	s_or_b32 s11, s4, 1
	v_writelane_b32 v254, s0, 2
	s_cmp_ge_i32 s75, s0
	s_waitcnt lgkmcnt(0)
	v_readfirstlane_b32 s8, v1
	v_writelane_b32 v254, s1, 3
	v_readfirstlane_b32 s6, v16
	v_readfirstlane_b32 s9, v2
	s_cbranch_scc1 .LBB0_1492
	v_lshlrev_b32_e32 v1, 4, v16
	v_add_u32_e32 v2, 0x2000, v1
	v_ashrrev_i32_e32 v3, 31, v2
	v_lshrrev_b32_e32 v3, 22, v3
	v_add_u32_e32 v3, v2, v3
	v_ashrrev_i32_e32 v10, 10, v3
	v_mul_i32_i24_e32 v3, 0x400, v10
	v_sub_u32_e32 v2, v2, v3
	v_lshrrev_b32_e32 v3, 4, v2
	v_bitop3_b32 v2, v3, v2, 32 bitop3:0x6c
	v_ashrrev_i32_e32 v3, 31, v2
	s_add_u32 s34, s8, 0x5a00000
	v_lshrrev_b32_e32 v3, 26, v3
	s_addc_u32 s35, s9, 0
	s_mul_i32 s0, s11, 0xb00000
	v_add_u32_e32 v3, v2, v3
	v_lshlrev_b32_e32 v4, 3, v10
	s_add_u32 s0, s8, s0
	v_ashrrev_i32_e32 v11, 6, v3
	v_and_b32_e32 v4, -16, v4
	s_addc_u32 s1, s9, 0
	v_add_u32_e32 v4, v11, v4
	s_add_u32 s36, s0, 0x800000
	v_and_b32_e32 v5, 3, v11
	s_mov_b32 s0, 0x1fffe0
	v_lshrrev_b32_e32 v6, 2, v4
	v_lshlrev_b32_e32 v7, 1, v4
	v_and_or_b32 v5, v4, s0, v5
	v_and_b32_e32 v6, 4, v6
	v_and_b32_e32 v7, 24, v7
	v_and_b32_e32 v3, 0xc0, v3
	v_or3_b32 v5, v5, v6, v7
	v_sub_u32_e32 v2, v2, v3
	v_mov_b32_e32 v7, 1
	v_lshlrev_b32_e32 v6, 5, v10
	v_ashrrev_i16_sdwa v2, v7, sext(v2) dst_sel:DWORD dst_unused:UNUSED_PAD src0_sel:DWORD src1_sel:BYTE_0
	v_and_b32_e32 v6, 32, v6
	v_bfe_i32 v12, v2, 0, 16
	v_add_lshl_u32 v2, v6, v12, 1
	v_lshl_add_u32 v148, v5, 11, v2
	v_lshl_add_u32 v150, v4, 11, v2
	v_bfe_i32 v2, v16, 27, 1
	v_lshrrev_b32_e32 v2, 22, v2
	v_add_u32_e32 v2, v1, v2
	v_and_b32_e32 v2, 0xfffffc00, v2
	v_sub_u32_e32 v1, v1, v2
	v_lshrrev_b32_e32 v2, 4, v1
	v_bitop3_b32 v2, v2, v1, 32 bitop3:0x6c
	v_ashrrev_i32_e32 v1, 31, v1
	v_lshrrev_b32_e32 v1, 26, v1
	v_add_u32_e32 v1, v2, v1
	v_ashrrev_i32_e32 v13, 6, v1
	v_ashrrev_i32_e32 v1, 31, v16
	v_lshrrev_b32_e32 v1, 26, v1
	v_add_u32_e32 v1, v16, v1
	v_ashrrev_i32_e32 v14, 6, v1
	v_lshlrev_b32_e32 v1, 3, v14
	v_and_b32_e32 v1, -16, v1
	v_add_u32_e32 v1, v13, v1
	v_and_b32_e32 v3, 3, v13
	s_addc_u32 s37, s1, 0
	v_and_or_b32 v3, v1, s0, v3
	v_readlane_b32 s0, v254, 2
	v_readlane_b32 s1, v254, 3
	s_lshr_b32 s39, s0, 3
	v_readlane_b32 s0, v253, 48
	s_add_i32 s0, s39, s0
	v_readlane_b32 s1, v253, 47
	s_mul_i32 s0, s0, s1
	v_readlane_b32 s1, v253, 38
	s_add_i32 s0, s0, s1
	s_mul_hi_i32 s1, s0, 0x2e8ba2e9
	s_lshr_b32 s4, s1, 31
	s_ashr_i32 s1, s1, 5
	v_lshrrev_b32_e32 v4, 2, v1
	v_lshlrev_b32_e32 v5, 1, v1
	s_add_i32 s1, s1, s4
	v_and_b32_e32 v4, 4, v4
	v_and_b32_e32 v5, 24, v5
	s_lshl_b32 s4, s1, 3
	v_or3_b32 v3, v3, v4, v5
	v_mul_i32_i24_e32 v5, 64, v13
	s_sub_i32 s5, s48, s4
	v_sub_u32_e32 v2, v2, v5
	s_min_i32 s5, s5, 8
	v_ashrrev_i16_sdwa v2, v7, sext(v2) dst_sel:DWORD dst_unused:UNUSED_PAD src0_sel:DWORD src1_sel:BYTE_0
	s_abs_i32 s13, s5
	v_bfe_i32 v15, v2, 0, 16
	v_cvt_f32_u32_e32 v2, s13
	v_lshlrev_b32_e32 v4, 5, v14
	v_and_b32_e32 v4, 32, v4
	v_add_lshl_u32 v4, v4, v15, 1
	v_lshl_add_u32 v154, v1, 11, v4
	v_rcp_iflag_f32_e32 v1, v2
	s_sub_i32 s15, 0, s13
	s_mulk_i32 s1, 0xb0
	s_sub_i32 s0, s0, s1
	v_mul_f32_e32 v1, 0x4f7ffffe, v1
	v_cvt_u32_f32_e32 v1, v1
	s_abs_i32 s14, s0
	s_ashr_i32 s7, s6, 6
	s_xor_b32 s1, s0, s5
	v_readfirstlane_b32 s16, v1
	s_mul_i32 s15, s15, s16
	s_mul_hi_u32 s15, s16, s15
	s_add_i32 s16, s16, s15
	s_mul_hi_u32 s15, s14, s16
	s_mul_i32 s16, s15, s13
	s_sub_i32 s14, s14, s16
	s_ashr_i32 s12, s6, 8
	s_lshl_b32 s38, s7, 10
	s_ashr_i32 s1, s1, 31
	s_add_i32 s16, s15, 1
	s_sub_i32 s17, s14, s13
	s_cmp_ge_u32 s14, s13
	s_cselect_b32 s15, s16, s15
	s_cselect_b32 s14, s17, s14
	s_add_i32 s16, s15, 1
	s_cmp_ge_u32 s14, s13
	s_cselect_b32 s13, s16, s15
	s_xor_b32 s13, s13, s1
	s_sub_i32 s24, s13, s1
	s_mul_i32 s1, s24, s5
	s_sub_i32 s0, s0, s1
	s_add_i32 s22, s4, s0
	s_ashr_i32 s23, s22, 31
	s_lshl_b64 s[0:1], s[22:23], 19
	s_add_u32 s26, s34, s0
	s_addc_u32 s27, s35, s1
	s_ashr_i32 s25, s24, 31
	s_lshl_b64 s[0:1], s[24:25], 19
	s_add_u32 s28, s36, s0
	s_addc_u32 s29, s37, s1
	s_add_i32 s25, s38, 0
	v_lshl_add_u32 v152, v3, 11, v4
	s_add_i32 m0, s25, 0x10000
	v_mov_b32_e32 v153, v0
	global_load_lds_dwordx4 v152, s[28:29]
	s_add_i32 m0, s25, 0x12000
	s_add_u32 s0, s28, 0x40000
	global_load_lds_dwordx4 v148, s[28:29]
	s_addc_u32 s1, s29, 0
	s_add_i32 m0, s25, 0x14000
	s_add_i32 s40, s25, 0x2000
	global_load_lds_dwordx4 v152, s[0:1]
	s_add_i32 m0, s25, 0x16000
	v_mov_b32_e32 v149, v0
	global_load_lds_dwordx4 v148, s[0:1]
	s_mov_b32 m0, s25
	s_add_u32 s0, s26, 0x40000
	global_load_lds_dwordx4 v154, s[26:27]
	s_mov_b32 m0, s40
	s_addc_u32 s1, s27, 0
	s_add_i32 s41, s25, 0x4000
	global_load_lds_dwordx4 v150, s[26:27]
	s_mov_b32 m0, s41
	s_add_i32 s42, s25, 0x6000
	global_load_lds_dwordx4 v154, s[0:1]
	s_mov_b32 m0, s42
	v_mov_b32_e32 v155, v0
	global_load_lds_dwordx4 v150, s[0:1]
	v_mov_b32_e32 v151, v0
	s_cmp_eq_u32 s12, 1
	v_lshl_add_u64 v[8:9], s[28:29], 0, v[152:153]
	v_lshl_add_u64 v[6:7], s[28:29], 0, v[148:149]
	v_lshl_add_u64 v[2:3], s[26:27], 0, v[154:155]
	s_cselect_b64 s[0:1], -1, 0
	s_cmp_lg_u32 s12, 1
	v_lshl_add_u64 v[4:5], s[26:27], 0, v[150:151]
	s_cbranch_scc1 .LBB0_1479
	s_barrier

.LBB0_1492:
	s_cmp_lg_u32 s57, -1
	s_cselect_b32 s0, s57, 0
	s_cselect_b32 s1, s55, 0
	s_cmp_lg_u32 s58, -1
	v_mov_b32_e32 v2, s0
	v_mov_b32_e32 v3, s1
	s_cselect_b32 s0, s58, 0
	s_cselect_b32 s1, s55, 0
	ds_read_b32 v1, v2
	s_waitcnt vmcnt(0) lgkmcnt(0)
	v_mov_b32_e32 v2, s0
	v_mov_b32_e32 v3, s1
	ds_read_b32 v2, v2
	s_waitcnt vmcnt(0) lgkmcnt(0)
	s_getreg_b32 s6, hwreg(HW_REG_XCC_ID, 0, 4)
	s_waitcnt vmcnt(0)
	s_waitcnt lgkmcnt(0)
	s_barrier
	v_readfirstlane_b32 s4, v1
	v_readfirstlane_b32 s5, v2
	s_and_saveexec_b64 s[0:1], s[78:79]
	s_cbranch_execz .LBB0_1544
	v_readlane_b32 s7, v253, 59
	s_waitcnt vmcnt(0) expcnt(0) lgkmcnt(0)
	s_and_b32 s33, s6, 15
	v_mov_b32_e32 v1, s7
	ds_read_b32 v3, v1
	v_readlane_b32 s7, v253, 60
	s_waitcnt lgkmcnt(0)
	v_cmp_ne_u32_e32 vcc, 0, v3
	v_mov_b32_e32 v1, s7
	ds_read_b32 v2, v1
	s_cbranch_vccnz .LBB0_1508
	s_add_u32 s6, s4, 0x3c0200
	s_addc_u32 s7, s5, 0
	s_add_u32 s8, s4, 0x3c0400
	s_addc_u32 s9, s5, 0
	s_add_u32 s12, s4, 0x3c0500
	s_addc_u32 s13, s5, 0
	s_add_u32 s14, s4, 0x3c0600
	s_addc_u32 s15, s5, 0
	s_add_u32 s16, s4, 0x3c0700
	s_addc_u32 s17, s5, 0
	s_add_u32 s18, s4, 0x3c0800
	s_addc_u32 s19, s5, 0
	s_add_u32 s20, s4, 0x3c0900
	s_addc_u32 s21, s5, 0
	s_add_u32 s22, s4, 0x3c0a00
	s_addc_u32 s23, s5, 0
	s_add_u32 s24, s4, 0x3c0b00
	s_addc_u32 s25, s5, 0
	s_add_u32 s26, s4, 0x3c0c00
	s_addc_u32 s27, s5, 0
	s_add_u32 s28, s4, 0x3c0d00
	s_addc_u32 s29, s5, 0
	s_add_u32 s30, s4, 0x3c0e00
	s_addc_u32 s31, s5, 0
	s_add_u32 s34, s4, 0x3c0f00
	s_addc_u32 s35, s5, 0
	s_add_u32 s36, s4, 0x3c1000
	s_addc_u32 s37, s5, 0
	s_add_u32 s38, s4, 0x3c1100
	s_addc_u32 s39, s5, 0
	s_add_u32 s40, s4, 0x3c1200
	s_addc_u32 s41, s5, 0
	s_add_u32 s42, s4, 0x3c1300
	s_addc_u32 s43, s5, 0
	s_mov_b32 s50, 1
	s_branch .LBB0_1496

.LBB0_1544:
	s_or_b64 exec, exec, s[0:1]
	s_cmp_lg_u32 s57, -1
	s_cselect_b32 s0, s57, 0
	s_cselect_b32 s1, s55, 0
	s_cmp_lg_u32 s58, -1
	s_waitcnt lgkmcnt(0)
	v_mov_b32_e32 v2, s0
	v_mov_b32_e32 v3, s1
	s_cselect_b32 s0, s58, 0
	s_cselect_b32 s1, s55, 0
	s_barrier
	ds_read_b32 v1, v2
	s_waitcnt vmcnt(0) lgkmcnt(0)
	v_mov_b32_e32 v2, s0
	v_mov_b32_e32 v3, s1
	ds_read_b32 v2, v2
	s_waitcnt vmcnt(0) lgkmcnt(0)
	v_readlane_b32 s0, v254, 24
	s_cmp_lg_u32 s0, -1
	s_cselect_b32 s0, s0, 0
	s_cselect_b32 s1, s55, 0
	v_mov_b32_e32 v3, s1
	s_waitcnt lgkmcnt(0)
	v_readfirstlane_b32 s8, v1
	v_readfirstlane_b32 s9, v2
	v_mov_b32_e32 v2, s0
	v_readlane_b32 s0, v254, 25
	s_cmp_lg_u32 s0, -1
	s_cselect_b32 s0, s0, 0
	s_cselect_b32 s1, s55, 0
	ds_read_b32 v1, v2
	s_waitcnt vmcnt(0) lgkmcnt(0)
	v_mov_b32_e32 v2, s0
	v_mov_b32_e32 v3, s1
	ds_read_b32 v2, v2
	s_waitcnt vmcnt(0) lgkmcnt(0)
	v_readlane_b32 s0, v254, 30
	v_readlane_b32 s1, v254, 31
	s_and_b64 vcc, exec, s[0:1]
	s_waitcnt lgkmcnt(0)
	v_readfirstlane_b32 s33, v1
	v_readfirstlane_b32 s42, v2
	s_cbranch_vccnz .LBB0_1546
	v_readlane_b32 s0, v253, 4
	s_cmp_lg_u32 s0, -1
	s_cselect_b32 s0, s0, 0
	v_mov_b32_e32 v2, s0
	v_readlane_b32 s0, v253, 5
	s_cselect_b32 s1, s55, 0
	s_cmp_lg_u32 s0, -1
	v_mov_b32_e32 v3, s1
	s_cselect_b32 s0, s0, 0
	s_cselect_b32 s1, s55, 0
	ds_read_b32 v1, v2
	s_waitcnt vmcnt(0) lgkmcnt(0)
	v_mov_b32_e32 v2, s0
	v_mov_b32_e32 v3, s1
	ds_read_b32 v2, v2
	s_waitcnt vmcnt(0) lgkmcnt(0)
	v_readfirstlane_b32 s0, v1
	s_add_u32 s12, s0, 0x1000
	v_readfirstlane_b32 s1, v2
	s_addc_u32 s13, s1, 0
	s_mov_b64 s[0:1], 0x1b3000
	s_branch .LBB0_1547

.LBB0_1671:
	s_cmp_lg_u32 s57, -1
	s_cselect_b32 s0, s57, 0
	s_cselect_b32 s1, s55, 0
	s_cmp_lg_u32 s58, -1
	v_mov_b32_e32 v2, s0
	s_waitcnt lgkmcnt(0)
	v_mov_b32_e32 v3, s1
	s_cselect_b32 s0, s58, 0
	s_cselect_b32 s1, s55, 0
	ds_read_b32 v1, v2
	s_waitcnt vmcnt(0) lgkmcnt(0)
	v_mov_b32_e32 v2, s0
	v_mov_b32_e32 v3, s1
	ds_read_b32 v2, v2
	s_waitcnt vmcnt(0) lgkmcnt(0)
	s_getreg_b32 s6, hwreg(HW_REG_XCC_ID, 0, 4)
	s_waitcnt vmcnt(0)
	s_waitcnt lgkmcnt(0)
	s_barrier
	v_readfirstlane_b32 s4, v1
	v_readfirstlane_b32 s5, v2
	s_and_saveexec_b64 s[0:1], s[78:79]
	s_movk_i32 s53, 0xbc
	s_cbranch_execz .LBB0_1723
	v_readlane_b32 s7, v253, 59
	s_waitcnt vmcnt(0) expcnt(0) lgkmcnt(0)
	s_and_b32 s33, s6, 15
	v_mov_b32_e32 v1, s7
	ds_read_b32 v3, v1
	v_readlane_b32 s7, v253, 60
	s_waitcnt lgkmcnt(0)
	v_cmp_ne_u32_e32 vcc, 0, v3
	v_mov_b32_e32 v1, s7
	ds_read_b32 v2, v1
	s_cbranch_vccnz .LBB0_1687
	s_add_u32 s6, s4, 0x3c0200
	s_addc_u32 s7, s5, 0
	s_add_u32 s8, s4, 0x3c0400
	s_addc_u32 s9, s5, 0
	s_add_u32 s10, s4, 0x3c0500
	s_addc_u32 s11, s5, 0
	s_add_u32 s12, s4, 0x3c0600
	s_addc_u32 s13, s5, 0
	s_add_u32 s14, s4, 0x3c0700
	s_addc_u32 s15, s5, 0
	s_add_u32 s16, s4, 0x3c0800
	s_addc_u32 s17, s5, 0
	s_add_u32 s18, s4, 0x3c0900
	s_addc_u32 s19, s5, 0
	s_add_u32 s20, s4, 0x3c0a00
	s_addc_u32 s21, s5, 0
	s_add_u32 s22, s4, 0x3c0b00
	s_addc_u32 s23, s5, 0
	s_add_u32 s24, s4, 0x3c0c00
	s_addc_u32 s25, s5, 0
	s_add_u32 s26, s4, 0x3c0d00
	s_addc_u32 s27, s5, 0
	s_add_u32 s28, s4, 0x3c0e00
	s_addc_u32 s29, s5, 0
	s_add_u32 s30, s4, 0x3c0f00
	s_addc_u32 s31, s5, 0
	s_add_u32 s34, s4, 0x3c1000
	s_addc_u32 s35, s5, 0
	s_add_u32 s36, s4, 0x3c1100
	s_addc_u32 s37, s5, 0
	s_add_u32 s38, s4, 0x3c1200
	s_addc_u32 s39, s5, 0
	s_add_u32 s40, s4, 0x3c1300
	s_addc_u32 s41, s5, 0
	s_mov_b32 s49, 1
	s_branch .LBB0_1675

.LBB0_1724:
	s_cmp_lg_u32 s57, -1
	s_cselect_b32 s0, s57, 0
	s_cselect_b32 s1, s55, 0
	s_cmp_lg_u32 s58, -1
	v_mov_b64_e32 v[2:3], s[0:1]
	s_cselect_b32 s0, s58, 0
	s_cselect_b32 s1, s55, 0
	v_mov_b64_e32 v[4:5], s[0:1]
	ds_read_b32 v1, v2
	s_waitcnt vmcnt(0) lgkmcnt(0)
	ds_read_b32 v6, v4
	s_waitcnt vmcnt(0) lgkmcnt(0)
	v_readlane_b32 s0, v253, 4
	s_cmp_lg_u32 s0, -1
	s_cselect_b32 s0, s0, 0
	s_cselect_b32 s1, s55, 0
	v_mov_b32_e32 v7, s1
	v_readlane_b32 s4, v253, 6
	s_waitcnt lgkmcnt(0)
	v_readfirstlane_b32 s6, v1
	v_readfirstlane_b32 s7, v6
	v_mov_b32_e32 v6, s0
	ds_read_b32 v1, v6
	s_waitcnt vmcnt(0) lgkmcnt(0)
	v_readlane_b32 s0, v253, 5
	s_cmp_lg_u32 s0, -1
	s_cselect_b32 s0, s0, 0
	s_cselect_b32 s1, s55, 0
	v_mov_b32_e32 v6, s0
	v_mov_b32_e32 v7, s1
	ds_read_b32 v6, v6
	s_waitcnt vmcnt(0) lgkmcnt(0)
	v_readfirstlane_b32 s0, v1
	v_mov_b32_e32 v1, v224
	ds_read_b32 v2, v2
	s_waitcnt vmcnt(0) lgkmcnt(0)
	ds_read_b32 v3, v4
	s_waitcnt vmcnt(0) lgkmcnt(0)
	v_readfirstlane_b32 s1, v6
	v_ashrrev_i32_e32 v6, 6, v1
	v_mul_lo_u32 v6, v6, s76
	v_add_u32_e32 v6, s75, v6
	s_movk_i32 s4, 0x400
	v_cmp_gt_i32_e32 vcc, s4, v6
	s_waitcnt lgkmcnt(0)
	v_readfirstlane_b32 s8, v2
	v_readfirstlane_b32 s9, v3
	s_and_saveexec_b64 s[4:5], vcc
	s_cbranch_execz .LBB0_1729
	v_and_b32_e32 v4, 63, v1
	v_and_b32_e32 v1, 64, v230
	v_add_u32_e32 v2, 64, v1
	v_xor_b32_e32 v1, 1, v230
	v_cmp_lt_i32_e32 vcc, v1, v2
	v_xor_b32_e32 v3, 2, v230
	s_add_u32 s10, s0, 0x1000
	v_cndmask_b32_e32 v1, v230, v1, vcc
	v_cmp_lt_i32_e32 vcc, v3, v2
	s_addc_u32 s11, s1, 0
	s_add_u32 s12, s8, 0x52000
	v_cndmask_b32_e32 v3, v230, v3, vcc
	v_lshlrev_b32_e32 v74, 2, v3
	v_xor_b32_e32 v3, 4, v230
	v_cmp_lt_i32_e32 vcc, v3, v2
	s_addc_u32 s13, s9, 0
	s_add_u32 s0, s8, s48
	v_cndmask_b32_e32 v3, v230, v3, vcc
	v_lshlrev_b32_e32 v75, 2, v3
	v_xor_b32_e32 v3, 8, v230
	v_cmp_lt_i32_e32 vcc, v3, v2
	s_addc_u32 s1, s9, 0
	s_add_u32 s14, s0, 0x24000
	v_cndmask_b32_e32 v3, v230, v3, vcc
	v_lshlrev_b32_e32 v76, 2, v3
	v_xor_b32_e32 v3, 16, v230
	v_cmp_lt_i32_e32 vcc, v3, v2
	v_lshlrev_b32_e32 v8, 4, v4
	s_addc_u32 s15, s1, 0
	v_cndmask_b32_e32 v3, v230, v3, vcc
	v_lshlrev_b32_e32 v77, 2, v3
	v_xor_b32_e32 v3, 32, v230
	v_cmp_lt_i32_e32 vcc, v3, v2
	v_mov_b32_e32 v9, v0
	v_lshl_add_u64 v[12:13], s[10:11], 0, v[8:9]
	v_cndmask_b32_e32 v2, v230, v3, vcc
	v_lshlrev_b32_e32 v78, 2, v2
	v_or_b32_e32 v2, 0x400, v8
	v_mov_b32_e32 v3, v0
	v_lshl_add_u64 v[16:17], s[14:15], 0, v[2:3]
	v_lshl_add_u64 v[18:19], s[10:11], 0, v[2:3]
	v_lshl_add_u64 v[20:21], s[12:13], 0, v[2:3]
	v_or_b32_e32 v2, 0x800, v8
	v_lshl_add_u64 v[22:23], s[14:15], 0, v[2:3]
	v_lshl_add_u64 v[24:25], s[10:11], 0, v[2:3]
	v_lshl_add_u64 v[26:27], s[12:13], 0, v[2:3]
	v_or_b32_e32 v2, 0xc00, v8
	v_lshl_add_u64 v[28:29], s[14:15], 0, v[2:3]
	v_lshl_add_u64 v[30:31], s[10:11], 0, v[2:3]
	v_lshl_add_u64 v[32:33], s[12:13], 0, v[2:3]
	v_lshlrev_b32_e32 v2, 3, v4
	v_lshl_add_u64 v[2:3], s[8:9], 0, v[2:3]
	s_mov_b64 s[10:11], 0x5a00000
	v_ashrrev_i32_e32 v7, 31, v6
	v_lshl_add_u64 v[34:35], v[2:3], 0, s[10:11]
	v_lshl_add_u64 v[2:3], v[6:7], 2, s[8:9]
	s_mov_b64 s[10:11], 0x1c3000
	v_lshl_add_u64 v[36:37], v[2:3], 0, s[10:11]
	v_lshlrev_b64 v[2:3], 12, v[6:7]
	v_lshlrev_b32_e32 v1, 2, v1
	v_cmp_eq_u32_e64 s[0:1], 0, v4
	v_lshl_add_u64 v[10:11], s[14:15], 0, v[8:9]
	v_lshl_add_u64 v[14:15], s[12:13], 0, v[8:9]
	v_lshl_add_u64 v[38:39], s[8:9], 0, v[2:3]
	v_lshl_add_u64 v[40:41], s[6:7], 0, v[2:3]
	s_mov_b64 s[6:7], 0
	s_branch .LBB0_1727

.LBB0_1729:
	s_or_b64 exec, exec, s[4:5]
	s_cmp_lg_u32 s57, -1
	s_cselect_b32 s0, s57, 0
	s_cselect_b32 s1, s55, 0
	s_cmp_lg_u32 s58, -1
	v_mov_b32_e32 v2, s0
	s_waitcnt lgkmcnt(0)
	v_mov_b32_e32 v3, s1
	s_cselect_b32 s0, s58, 0
	s_cselect_b32 s1, s55, 0
	ds_read_b32 v1, v2
	s_waitcnt vmcnt(0) lgkmcnt(0)
	v_mov_b32_e32 v2, s0
	v_mov_b32_e32 v3, s1
	ds_read_b32 v2, v2
	s_waitcnt vmcnt(0) lgkmcnt(0)
	s_getreg_b32 s6, hwreg(HW_REG_XCC_ID, 0, 4)
	s_waitcnt vmcnt(0)
	s_waitcnt lgkmcnt(0)
	s_barrier
	v_readfirstlane_b32 s4, v1
	v_readfirstlane_b32 s5, v2
	s_and_saveexec_b64 s[0:1], s[78:79]
	s_cbranch_execnz .LBB0_1730
	s_getpc_b64 s[98:99]

.LBB0_1780:
	s_mov_b64 s[0:1], src_shared_base
	s_cmp_lg_u32 s57, -1
	s_cselect_b32 s0, s57, 0
	s_cselect_b32 s2, s1, 0
	s_cmp_lg_u32 s58, -1
	v_mov_b32_e32 v0, s0
	v_mov_b32_e32 v1, s2
	s_cselect_b32 s0, s58, 0
	ds_read_b32 v2, v0
	s_waitcnt vmcnt(0) lgkmcnt(0)
	v_mov_b32_e32 v0, s0
	v_readlane_b32 s0, v254, 24
	s_cselect_b32 s2, s1, 0
	s_cmp_lg_u32 s0, -1
	v_mov_b32_e32 v1, s2
	s_cselect_b32 s0, s0, 0
	ds_read_b32 v3, v0
	s_waitcnt vmcnt(0) lgkmcnt(0)
	v_mov_b32_e32 v0, s0
	v_readlane_b32 s0, v254, 25
	s_cselect_b32 s2, s1, 0
	s_cmp_lg_u32 s0, -1
	v_mov_b32_e32 v1, s2
	s_cselect_b32 s0, s0, 0
	ds_read_b32 v4, v0
	s_waitcnt vmcnt(0) lgkmcnt(0)
	s_cselect_b32 s2, s1, 0
	v_mov_b32_e32 v0, s0
	s_add_i32 s0, 0, 0x23fc0
	s_cmp_lg_u32 s0, -1
	v_mov_b32_e32 v1, s2
	s_cselect_b32 s0, s0, 0
	ds_read_b32 v5, v0
	s_waitcnt vmcnt(0) lgkmcnt(0)
	s_cselect_b32 s2, s1, 0
	v_mov_b32_e32 v0, s0
	s_add_i32 s0, 0, 0x23fc4
	s_cmp_lg_u32 s0, -1
	v_mov_b32_e32 v1, s2
	s_cselect_b32 s0, s0, 0
	s_cselect_b32 s1, s1, 0
	ds_read_b32 v6, v0
	s_waitcnt vmcnt(0) lgkmcnt(0)
	v_mov_b32_e32 v0, s0
	v_mov_b32_e32 v1, s1
	ds_read_b32 v1, v0
	s_waitcnt vmcnt(0) lgkmcnt(0)
	v_ashrrev_i32_e32 v0, 5, v224
	v_and_b32_e32 v0, -2, v0
	v_readlane_b32 s0, v253, 22
	s_movk_i32 s6, 0x4000
	s_waitcnt lgkmcnt(0)
	v_readfirstlane_b32 s4, v2
	v_add_u32_e32 v0, s0, v0
	v_cmp_gt_i32_e32 vcc, s6, v0
	v_readfirstlane_b32 s5, v3
	v_readfirstlane_b32 s0, v4
	v_readfirstlane_b32 s1, v5
	v_readfirstlane_b32 s2, v6
	v_readfirstlane_b32 s3, v1
	s_and_saveexec_b64 s[6:7], vcc
	v_readlane_b32 s8, v254, 8
	v_readlane_b32 s9, v254, 9
	s_cbranch_execz .LBB0_1783
	v_lshlrev_b32_e32 v1, 4, v224
	v_and_b32_e32 v2, 0x3f0, v1
	v_ashrrev_i32_e32 v1, 31, v0
	v_lshlrev_b64 v[4:5], 12, v[0:1]
	v_and_b32_e32 v8, 63, v224
	v_mov_b32_e32 v6, s4
	v_mov_b32_e32 v7, s5
	v_mov_b32_e32 v3, 0
	v_lshl_or_b32 v4, v8, 4, v4
	v_lshl_add_u64 v[2:3], s[2:3], 0, v[2:3]
	v_lshl_add_u64 v[4:5], s[0:1], 0, v[4:5]
	s_mov_b64 s[0:1], 0x1000
	v_lshl_add_u64 v[6:7], v[0:1], 2, v[6:7]
	s_mov_b64 s[2:3], 0x1e6004
	v_lshl_add_u64 v[4:5], v[4:5], 0, s[0:1]
	s_lshl_b64 s[0:1], s[8:9], 12
	v_lshl_add_u64 v[6:7], v[6:7], 0, s[2:3]
	s_lshl_b64 s[2:3], s[8:9], 2
	s_mov_b64 s[4:5], 0
	v_mov_b32_e32 v1, 0x358637bd
	s_movk_i32 s6, 0x3fff
